# gelu epilogues (EpiIn, EpiUp): compiler dst-sel pads (s_nop 0 after packed-f32 ops) removed
# speedup vs baseline: 1.0114x; 1.0029x over previous
; __device__ __forceinline__ f32x4 gelu4(f32x4 v) { f32x2 a = gelu_pk((f32x2){v[0], v[1]}), b = gelu_pk((f32x2){v[2], v[3]}); return (f32x4){a.x, a.y, b.x, b.y}; }
; __device__ __forceinline__ f32x2 gelu_pk(f32x2 v) {
;     const f32x2 av = __builtin_elementwise_abs(v), d = av * 0.2316418882f + 1.0f;
;     f32x2 t; t.x = __builtin_amdgcn_rcpf(d.x); t.y = __builtin_amdgcn_rcpf(d.y);
;     f32x2 q = t * 0.5307027145f + (-0.7265760135f); q = q * t + 0.7107068705f; q = q * t + (-0.142248368f); q = q * t + 0.127414796f; q = q * t;
;     const f32x2 s = (v * v) * (-0.72134752044f);
;     f32x2 e; e.x = __builtin_amdgcn_exp2f(s.x); e.y = __builtin_amdgcn_exp2f(s.y);
;     const f32x2 m = v * (q * e), r = v - m;
;     f32x2 o; o.x = v.x < 0.f ? m.x : r.x; o.y = v.y < 0.f ? m.y : r.y; return o;
;     __device__ __forceinline__ void operator()(f32x4 (&acc)[2][2][4][2], const Unit& u, int wr, int wc, int fr_, int fq_) const {
;     ...
;             for (int m = 0; m < 4; ++m) { const int row = row0 + ai * HALF + m * 16; const float rs = rstd[row]; bf16_t* rowp = base + (size_t)row * ld + col0;
;                 float s1 = 0.f, s2 = 0.f;
; #pragma unroll
;                 for (int bj = 0; bj < 2; ++bj) { f32x4 v0 = acc[ai][bj][m][0] * rs, v1 = acc[ai][bj][m][1] * rs;
;                     if (act) { v0 = gelu4(v0); v1 = gelu4(v1); }
.LBB0_354:
	s_lshl_b32 s6, s6, 8
	s_add_i32 s6, s6, s37
	v_add_u32_e32 v146, s6, v146
	v_readlane_b32 s6, v244, 38
	v_ashrrev_i32_e32 v147, 31, v146
	v_readlane_b32 s7, v244, 39
	v_cndmask_b32_e64 v150, 0, 1, s[14:15]
	s_andn2_b64 vcc, exec, s[14:15]
	v_lshl_add_u64 v[148:149], v[146:147], 2, s[6:7]
	global_load_dword v152, v[148:149], off
	global_load_dword v245, v[148:149], off offset:64
	global_load_dword v246, v[148:149], off offset:128
	global_load_dword v247, v[148:149], off offset:192
	global_load_dword v248, v[148:149], off offset:512
	global_load_dword v249, v[148:149], off offset:576
	global_load_dword v250, v[148:149], off offset:640
	global_load_dword v251, v[148:149], off offset:704
	v_cmp_ne_u32_e64 s[6:7], 1, v150
	s_waitcnt vmcnt(0)
	v_pk_mul_f32 v[126:127], v[126:127], v[152:153] op_sel_hi:[1,0]
	v_pk_mul_f32 v[150:151], v[124:125], v[152:153] op_sel_hi:[1,0]
	v_pk_mul_f32 v[122:123], v[122:123], v[152:153] op_sel_hi:[1,0]
	v_pk_mul_f32 v[124:125], v[120:121], v[152:153] op_sel_hi:[1,0]
	s_cbranch_vccnz .LBB0_356
	v_and_b32_e32 v121, 0x7fffffff, v151
	v_and_b32_e32 v120, 0x7fffffff, v150
	v_pk_fma_f32 v[120:121], v[120:121], s[90:91], 1.0 op_sel_hi:[1,0,0]
	v_mov_b64_e32 v[154:155], s[94:95]
	v_rcp_f32_e32 v120, v120
	v_rcp_f32_e32 v121, v121
	v_pk_mul_f32 v[166:167], v[150:151], v[150:151]
	v_cmp_gt_f32_e32 vcc, 0, v150
	v_pk_mul_f32 v[166:167], v[166:167], s[18:19] op_sel_hi:[1,0]
	v_pk_fma_f32 v[164:165], v[120:121], s[92:93], v[154:155] op_sel_hi:[1,0,0]
	v_exp_f32_e32 v166, v166
	v_pk_fma_f32 v[164:165], v[120:121], v[164:165], s[96:97] op_sel_hi:[1,1,0]
	v_exp_f32_e32 v167, v167
	v_pk_fma_f32 v[164:165], v[120:121], v[164:165], s[16:17] op_sel_hi:[1,1,0]
	v_pk_fma_f32 v[164:165], v[120:121], v[164:165], s[84:85] op_sel_hi:[1,1,0]
	v_pk_mul_f32 v[120:121], v[120:121], v[164:165]
	v_pk_mul_f32 v[164:165], v[126:127], v[126:127]
	v_pk_mul_f32 v[120:121], v[166:167], v[120:121]
	v_pk_mul_f32 v[164:165], v[164:165], s[18:19] op_sel_hi:[1,0]
	v_pk_mul_f32 v[166:167], v[150:151], v[120:121]
	v_pk_fma_f32 v[120:121], v[150:151], v[120:121], v[150:151] neg_lo:[1,0,0] neg_hi:[1,0,0]
	v_exp_f32_e32 v164, v164
	v_cndmask_b32_e32 v150, v120, v166, vcc
	v_cmp_gt_f32_e32 vcc, 0, v151
	v_and_b32_e32 v120, 0x7fffffff, v126
	v_exp_f32_e32 v165, v165
	v_cndmask_b32_e32 v151, v121, v167, vcc
	v_and_b32_e32 v121, 0x7fffffff, v127
	v_pk_fma_f32 v[120:121], v[120:121], s[90:91], 1.0 op_sel_hi:[1,0,0]
	v_cmp_gt_f32_e32 vcc, 0, v126
	v_rcp_f32_e32 v120, v120
	v_rcp_f32_e32 v121, v121
	s_nop 0
	v_pk_fma_f32 v[166:167], v[120:121], s[92:93], v[154:155] op_sel_hi:[1,0,0]
	v_pk_fma_f32 v[166:167], v[120:121], v[166:167], s[96:97] op_sel_hi:[1,1,0]
	v_pk_fma_f32 v[166:167], v[120:121], v[166:167], s[16:17] op_sel_hi:[1,1,0]
	v_pk_fma_f32 v[166:167], v[120:121], v[166:167], s[84:85] op_sel_hi:[1,1,0]
	v_pk_mul_f32 v[120:121], v[120:121], v[166:167]
	v_pk_mul_f32 v[166:167], v[124:125], v[124:125]
	v_pk_mul_f32 v[120:121], v[164:165], v[120:121]
	v_pk_mul_f32 v[166:167], v[166:167], s[18:19] op_sel_hi:[1,0]
	v_pk_mul_f32 v[164:165], v[126:127], v[120:121]
	v_pk_fma_f32 v[120:121], v[126:127], v[120:121], v[126:127] neg_lo:[1,0,0] neg_hi:[1,0,0]
	v_exp_f32_e32 v166, v166
	v_cndmask_b32_e32 v126, v120, v164, vcc
	v_cmp_gt_f32_e32 vcc, 0, v127
	v_and_b32_e32 v120, 0x7fffffff, v124
	v_exp_f32_e32 v167, v167
	v_cndmask_b32_e32 v127, v121, v165, vcc
	v_and_b32_e32 v121, 0x7fffffff, v125
	v_pk_fma_f32 v[120:121], v[120:121], s[90:91], 1.0 op_sel_hi:[1,0,0]
	v_cmp_gt_f32_e32 vcc, 0, v124
	v_rcp_f32_e32 v120, v120
	v_rcp_f32_e32 v121, v121
	s_nop 0
	v_pk_fma_f32 v[164:165], v[120:121], s[92:93], v[154:155] op_sel_hi:[1,0,0]
	v_pk_fma_f32 v[164:165], v[120:121], v[164:165], s[96:97] op_sel_hi:[1,1,0]
	v_pk_fma_f32 v[164:165], v[120:121], v[164:165], s[16:17] op_sel_hi:[1,1,0]
	v_pk_fma_f32 v[164:165], v[120:121], v[164:165], s[84:85] op_sel_hi:[1,1,0]
	v_pk_mul_f32 v[120:121], v[120:121], v[164:165]
	v_pk_mul_f32 v[164:165], v[122:123], v[122:123]
	v_pk_mul_f32 v[120:121], v[166:167], v[120:121]
	v_pk_mul_f32 v[166:167], v[124:125], v[120:121]
	v_pk_fma_f32 v[120:121], v[124:125], v[120:121], v[124:125] neg_lo:[1,0,0] neg_hi:[1,0,0]
	v_cndmask_b32_e32 v124, v120, v166, vcc
	v_cmp_gt_f32_e32 vcc, 0, v125
	v_and_b32_e32 v120, 0x7fffffff, v122
	s_nop 0
	v_cndmask_b32_e32 v125, v121, v167, vcc
	v_and_b32_e32 v121, 0x7fffffff, v123
	v_pk_fma_f32 v[120:121], v[120:121], s[90:91], 1.0 op_sel_hi:[1,0,0]
	v_cmp_gt_f32_e32 vcc, 0, v122
	v_rcp_f32_e32 v120, v120
	v_rcp_f32_e32 v121, v121
	s_nop 0
	v_pk_fma_f32 v[154:155], v[120:121], s[92:93], v[154:155] op_sel_hi:[1,0,0]
	v_pk_fma_f32 v[154:155], v[120:121], v[154:155], s[96:97] op_sel_hi:[1,1,0]
	v_pk_fma_f32 v[154:155], v[120:121], v[154:155], s[16:17] op_sel_hi:[1,1,0]
	v_pk_fma_f32 v[154:155], v[120:121], v[154:155], s[84:85] op_sel_hi:[1,1,0]
	v_pk_mul_f32 v[120:121], v[120:121], v[154:155]
	v_pk_mul_f32 v[154:155], v[164:165], s[18:19] op_sel_hi:[1,0]
	v_exp_f32_e32 v154, v154
	v_exp_f32_e32 v155, v155
	s_nop 0
	v_pk_mul_f32 v[120:121], v[154:155], v[120:121]
	v_pk_mul_f32 v[154:155], v[122:123], v[120:121]
	v_pk_fma_f32 v[120:121], v[122:123], v[120:121], v[122:123] neg_lo:[1,0,0] neg_hi:[1,0,0]
	v_cndmask_b32_e32 v122, v120, v154, vcc
	v_cmp_gt_f32_e32 vcc, 0, v123
	s_nop 1
	v_cndmask_b32_e32 v123, v121, v155, vcc
; __device__ __forceinline__ u32x4 pack8(f32x4 v0, f32x4 v1) { u32x4 w; w.x = cvt_pk_bf16(v0[0], v0[1]); w.y = cvt_pk_bf16(v0[2], v0[3]); w.z = cvt_pk_bf16(v1[0], v1[1]); w.w = cvt_pk_bf16(v1[2], v1[3]); return w; }
; __device__ __forceinline__ f32x4 gelu4(f32x4 v) { f32x2 a = gelu_pk((f32x2){v[0], v[1]}), b = gelu_pk((f32x2){v[2], v[3]}); return (f32x4){a.x, a.y, b.x, b.y}; }
; __device__ __forceinline__ f32x2 gelu_pk(f32x2 v) {
;     const f32x2 av = __builtin_elementwise_abs(v), d = av * 0.2316418882f + 1.0f;
;     f32x2 t; t.x = __builtin_amdgcn_rcpf(d.x); t.y = __builtin_amdgcn_rcpf(d.y);
;     f32x2 q = t * 0.5307027145f + (-0.7265760135f); q = q * t + 0.7107068705f; q = q * t + (-0.142248368f); q = q * t + 0.127414796f; q = q * t;
;     const f32x2 s = (v * v) * (-0.72134752044f);
;     f32x2 e; e.x = __builtin_amdgcn_exp2f(s.x); e.y = __builtin_amdgcn_exp2f(s.y);
;     const f32x2 m = v * (q * e), r = v - m;
;     f32x2 o; o.x = v.x < 0.f ? m.x : r.x; o.y = v.y < 0.f ? m.y : r.y; return o;
;     __device__ __forceinline__ void operator()(f32x4 (&acc)[2][2][4][2], const Unit& u, int wr, int wc, int fr_, int fq_) const {
;     ...
;                 for (int bj = 0; bj < 2; ++bj) { f32x4 v0 = acc[ai][bj][m][0] * rs, v1 = acc[ai][bj][m][1] * rs;
;                     if (act) { v0 = gelu4(v0); v1 = gelu4(v1); }
;                     s1 += ((v0[0] + v0[1]) + (v0[2] + v0[3])) + ((v1[0] + v1[1]) + (v1[2] + v1[3]));
;                     s2 += ((v0[0] * v0[0] + v0[1] * v0[1]) + (v0[2] * v0[2] + v0[3] * v0[3])) + ((v1[0] * v1[0] + v1[1] * v1[1]) + (v1[2] * v1[2] + v1[3] * v1[3]));
;                     *(u32x4*)(rowp + bj * HALF) = pack8(v0, v1); }
.LBB0_356:
	s_lshl_b32 s9, s9, 8
	s_or_b32 s9, s9, s38
	v_lshl_add_u32 v120, v163, 3, s9
	v_ashrrev_i32_e32 v121, 31, v120
	v_lshl_add_u64 v[120:121], v[120:121], 1, s[10:11]
	v_mul_lo_u32 v164, s87, v146
	v_mul_lo_u32 v165, s86, v147
	v_mad_u64_u32 v[154:155], s[10:11], s86, v146, 0
	v_add3_u32 v155, v155, v165, v164
	v_lshl_add_u64 v[154:155], v[154:155], 1, v[120:121]
	v_cvt_pk_bf16_f32 v164, v150, v151
	v_cvt_pk_bf16_f32 v165, v126, v127
	v_cvt_pk_bf16_f32 v166, v124, v125
	v_cvt_pk_bf16_f32 v167, v122, v123
	v_mov_b32_e32 v153, v152
	global_store_dwordx4 v[154:155], v[164:167], off
	v_pk_mul_f32 v[116:117], v[116:117], v[152:153]
	s_and_b64 vcc, exec, s[6:7]
	v_mov_b32_e32 v164, v152
	v_mov_b32_e32 v165, v152
	v_pk_mul_f32 v[118:119], v[118:119], v[164:165]
	v_pk_mul_f32 v[114:115], v[114:115], v[164:165]
	v_pk_mul_f32 v[112:113], v[112:113], v[152:153]
	s_cbranch_vccnz .LBB0_358
	v_and_b32_e32 v153, 0x7fffffff, v117
	v_and_b32_e32 v152, 0x7fffffff, v116
	v_pk_fma_f32 v[152:153], v[152:153], s[90:91], 1.0 op_sel_hi:[1,0,0]
	v_mov_b64_e32 v[164:165], s[94:95]
	v_rcp_f32_e32 v152, v152
	v_rcp_f32_e32 v153, v153
	v_pk_mul_f32 v[168:169], v[116:117], v[116:117]
	v_cmp_gt_f32_e32 vcc, 0, v116
	v_pk_mul_f32 v[168:169], v[168:169], s[18:19] op_sel_hi:[1,0]
	v_pk_fma_f32 v[166:167], v[152:153], s[92:93], v[164:165] op_sel_hi:[1,0,0]
	v_exp_f32_e32 v168, v168
	v_pk_fma_f32 v[166:167], v[152:153], v[166:167], s[96:97] op_sel_hi:[1,1,0]
	v_exp_f32_e32 v169, v169
	v_pk_fma_f32 v[166:167], v[152:153], v[166:167], s[16:17] op_sel_hi:[1,1,0]
	v_pk_fma_f32 v[166:167], v[152:153], v[166:167], s[84:85] op_sel_hi:[1,1,0]
	v_pk_mul_f32 v[152:153], v[152:153], v[166:167]
	v_pk_mul_f32 v[166:167], v[118:119], v[118:119]
	v_pk_mul_f32 v[152:153], v[168:169], v[152:153]
	v_pk_mul_f32 v[166:167], v[166:167], s[18:19] op_sel_hi:[1,0]
	v_pk_mul_f32 v[168:169], v[116:117], v[152:153]
	v_pk_fma_f32 v[152:153], v[116:117], v[152:153], v[116:117] neg_lo:[1,0,0] neg_hi:[1,0,0]
	v_exp_f32_e32 v166, v166
	v_cndmask_b32_e32 v116, v152, v168, vcc
	v_cmp_gt_f32_e32 vcc, 0, v117
	v_and_b32_e32 v152, 0x7fffffff, v118
	v_exp_f32_e32 v167, v167
	v_cndmask_b32_e32 v117, v153, v169, vcc
	v_and_b32_e32 v153, 0x7fffffff, v119
	v_pk_fma_f32 v[152:153], v[152:153], s[90:91], 1.0 op_sel_hi:[1,0,0]
	v_cmp_gt_f32_e32 vcc, 0, v118
	v_rcp_f32_e32 v152, v152
	v_rcp_f32_e32 v153, v153
	s_nop 0
	v_pk_fma_f32 v[168:169], v[152:153], s[92:93], v[164:165] op_sel_hi:[1,0,0]
	v_pk_fma_f32 v[168:169], v[152:153], v[168:169], s[96:97] op_sel_hi:[1,1,0]
	v_pk_fma_f32 v[168:169], v[152:153], v[168:169], s[16:17] op_sel_hi:[1,1,0]
	v_pk_fma_f32 v[168:169], v[152:153], v[168:169], s[84:85] op_sel_hi:[1,1,0]
	v_pk_mul_f32 v[152:153], v[152:153], v[168:169]
	v_pk_mul_f32 v[168:169], v[112:113], v[112:113]
	v_pk_mul_f32 v[152:153], v[166:167], v[152:153]
	v_pk_mul_f32 v[168:169], v[168:169], s[18:19] op_sel_hi:[1,0]
	v_pk_mul_f32 v[166:167], v[118:119], v[152:153]
	v_pk_fma_f32 v[152:153], v[118:119], v[152:153], v[118:119] neg_lo:[1,0,0] neg_hi:[1,0,0]
	v_exp_f32_e32 v168, v168
	v_cndmask_b32_e32 v118, v152, v166, vcc
	v_cmp_gt_f32_e32 vcc, 0, v119
	v_and_b32_e32 v152, 0x7fffffff, v112
	v_exp_f32_e32 v169, v169
	v_cndmask_b32_e32 v119, v153, v167, vcc
	v_and_b32_e32 v153, 0x7fffffff, v113
	v_pk_fma_f32 v[152:153], v[152:153], s[90:91], 1.0 op_sel_hi:[1,0,0]
	v_cmp_gt_f32_e32 vcc, 0, v112
	v_rcp_f32_e32 v152, v152
	v_rcp_f32_e32 v153, v153
	s_nop 0
	v_pk_fma_f32 v[166:167], v[152:153], s[92:93], v[164:165] op_sel_hi:[1,0,0]
	v_pk_fma_f32 v[166:167], v[152:153], v[166:167], s[96:97] op_sel_hi:[1,1,0]
	v_pk_fma_f32 v[166:167], v[152:153], v[166:167], s[16:17] op_sel_hi:[1,1,0]
	v_pk_fma_f32 v[166:167], v[152:153], v[166:167], s[84:85] op_sel_hi:[1,1,0]
	v_pk_mul_f32 v[152:153], v[152:153], v[166:167]
	v_pk_mul_f32 v[166:167], v[114:115], v[114:115]
	v_pk_mul_f32 v[152:153], v[168:169], v[152:153]
	v_pk_mul_f32 v[168:169], v[112:113], v[152:153]
	v_pk_fma_f32 v[152:153], v[112:113], v[152:153], v[112:113] neg_lo:[1,0,0] neg_hi:[1,0,0]
	v_cndmask_b32_e32 v112, v152, v168, vcc
	v_cmp_gt_f32_e32 vcc, 0, v113
	v_and_b32_e32 v152, 0x7fffffff, v114
	s_nop 0
	v_cndmask_b32_e32 v113, v153, v169, vcc
	v_and_b32_e32 v153, 0x7fffffff, v115
	v_pk_fma_f32 v[152:153], v[152:153], s[90:91], 1.0 op_sel_hi:[1,0,0]
	v_cmp_gt_f32_e32 vcc, 0, v114
	v_rcp_f32_e32 v152, v152
	v_rcp_f32_e32 v153, v153
	s_nop 0
	v_pk_fma_f32 v[164:165], v[152:153], s[92:93], v[164:165] op_sel_hi:[1,0,0]
	v_pk_fma_f32 v[164:165], v[152:153], v[164:165], s[96:97] op_sel_hi:[1,1,0]
	v_pk_fma_f32 v[164:165], v[152:153], v[164:165], s[16:17] op_sel_hi:[1,1,0]
	v_pk_fma_f32 v[164:165], v[152:153], v[164:165], s[84:85] op_sel_hi:[1,1,0]
	v_pk_mul_f32 v[152:153], v[152:153], v[164:165]
	v_pk_mul_f32 v[164:165], v[166:167], s[18:19] op_sel_hi:[1,0]
	v_exp_f32_e32 v164, v164
	v_exp_f32_e32 v165, v165
	s_nop 0
	v_pk_mul_f32 v[152:153], v[164:165], v[152:153]
	v_pk_mul_f32 v[164:165], v[114:115], v[152:153]
	v_pk_fma_f32 v[152:153], v[114:115], v[152:153], v[114:115] neg_lo:[1,0,0] neg_hi:[1,0,0]
	v_cndmask_b32_e32 v114, v152, v164, vcc
	v_cmp_gt_f32_e32 vcc, 0, v115
	s_nop 1
	v_cndmask_b32_e32 v115, v153, v165, vcc

; __device__ __forceinline__ f32x4 gelu4(f32x4 v) { f32x2 a = gelu_pk((f32x2){v[0], v[1]}), b = gelu_pk((f32x2){v[2], v[3]}); return (f32x4){a.x, a.y, b.x, b.y}; }
; __device__ __forceinline__ f32x2 gelu_pk(f32x2 v) {
;     const f32x2 av = __builtin_elementwise_abs(v), d = av * 0.2316418882f + 1.0f;
;     f32x2 t; t.x = __builtin_amdgcn_rcpf(d.x); t.y = __builtin_amdgcn_rcpf(d.y);
;     f32x2 q = t * 0.5307027145f + (-0.7265760135f); q = q * t + 0.7107068705f; q = q * t + (-0.142248368f); q = q * t + 0.127414796f; q = q * t;
;     const f32x2 s = (v * v) * (-0.72134752044f);
;     f32x2 e; e.x = __builtin_amdgcn_exp2f(s.x); e.y = __builtin_amdgcn_exp2f(s.y);
;     const f32x2 m = v * (q * e), r = v - m;
;     f32x2 o; o.x = v.x < 0.f ? m.x : r.x; o.y = v.y < 0.f ? m.y : r.y; return o;
;     __device__ __forceinline__ void operator()(f32x4 (&acc)[2][2][4][2], const Unit& u, int wr, int wc, int fr_, int fq_) const {
;     ...
;             for (int m = 0; m < 4; ++m) { const int row = row0 + ai * HALF + m * 16; const float rs = rstd[row]; bf16_t* rowp = base + (size_t)row * ld + col0;
;                 float s1 = 0.f, s2 = 0.f;
; #pragma unroll
;                 for (int bj = 0; bj < 2; ++bj) { f32x4 v0 = acc[ai][bj][m][0] * rs, v1 = acc[ai][bj][m][1] * rs;
;                     if (act) { v0 = gelu4(v0); v1 = gelu4(v1); }
.LBB0_362:
	v_mov_b32_e32 v114, v245
	s_and_b64 vcc, exec, s[6:7]
	s_waitcnt lgkmcnt(0)
	v_pk_mul_f32 v[110:111], v[110:111], v[114:115] op_sel_hi:[1,0]
	v_pk_mul_f32 v[108:109], v[108:109], v[114:115] op_sel_hi:[1,0]
	v_pk_mul_f32 v[106:107], v[106:107], v[114:115] op_sel_hi:[1,0]
	v_pk_mul_f32 v[104:105], v[104:105], v[114:115] op_sel_hi:[1,0]
	s_cbranch_vccnz .LBB0_364
	v_and_b32_e32 v113, 0x7fffffff, v109
	v_and_b32_e32 v112, 0x7fffffff, v108
	v_pk_fma_f32 v[112:113], v[112:113], s[90:91], 1.0 op_sel_hi:[1,0,0]
	v_mov_b64_e32 v[116:117], s[94:95]
	v_rcp_f32_e32 v112, v112
	v_rcp_f32_e32 v113, v113
	v_pk_mul_f32 v[122:123], v[108:109], v[108:109]
	v_cmp_gt_f32_e32 vcc, 0, v108
	v_pk_mul_f32 v[122:123], v[122:123], s[18:19] op_sel_hi:[1,0]
	v_pk_fma_f32 v[118:119], v[112:113], s[92:93], v[116:117] op_sel_hi:[1,0,0]
	v_exp_f32_e32 v122, v122
	v_pk_fma_f32 v[118:119], v[112:113], v[118:119], s[96:97] op_sel_hi:[1,1,0]
	v_exp_f32_e32 v123, v123
	v_pk_fma_f32 v[118:119], v[112:113], v[118:119], s[16:17] op_sel_hi:[1,1,0]
	v_pk_fma_f32 v[118:119], v[112:113], v[118:119], s[84:85] op_sel_hi:[1,1,0]
	v_pk_mul_f32 v[112:113], v[112:113], v[118:119]
	v_pk_mul_f32 v[118:119], v[110:111], v[110:111]
	v_pk_mul_f32 v[112:113], v[122:123], v[112:113]
	v_pk_mul_f32 v[118:119], v[118:119], s[18:19] op_sel_hi:[1,0]
	v_pk_mul_f32 v[122:123], v[108:109], v[112:113]
	v_pk_fma_f32 v[112:113], v[108:109], v[112:113], v[108:109] neg_lo:[1,0,0] neg_hi:[1,0,0]
	v_exp_f32_e32 v118, v118
	v_cndmask_b32_e32 v108, v112, v122, vcc
	v_cmp_gt_f32_e32 vcc, 0, v109
	v_and_b32_e32 v112, 0x7fffffff, v110
	v_exp_f32_e32 v119, v119
	v_cndmask_b32_e32 v109, v113, v123, vcc
	v_and_b32_e32 v113, 0x7fffffff, v111
	v_pk_fma_f32 v[112:113], v[112:113], s[90:91], 1.0 op_sel_hi:[1,0,0]
	v_cmp_gt_f32_e32 vcc, 0, v110
	v_rcp_f32_e32 v112, v112
	v_rcp_f32_e32 v113, v113
	s_nop 0
	v_pk_fma_f32 v[122:123], v[112:113], s[92:93], v[116:117] op_sel_hi:[1,0,0]
	v_pk_fma_f32 v[122:123], v[112:113], v[122:123], s[96:97] op_sel_hi:[1,1,0]
	v_pk_fma_f32 v[122:123], v[112:113], v[122:123], s[16:17] op_sel_hi:[1,1,0]
	v_pk_fma_f32 v[122:123], v[112:113], v[122:123], s[84:85] op_sel_hi:[1,1,0]
	v_pk_mul_f32 v[112:113], v[112:113], v[122:123]
	v_pk_mul_f32 v[122:123], v[104:105], v[104:105]
	v_pk_mul_f32 v[112:113], v[118:119], v[112:113]
	v_pk_mul_f32 v[122:123], v[122:123], s[18:19] op_sel_hi:[1,0]
	v_pk_mul_f32 v[118:119], v[110:111], v[112:113]
	v_pk_fma_f32 v[112:113], v[110:111], v[112:113], v[110:111] neg_lo:[1,0,0] neg_hi:[1,0,0]
	v_exp_f32_e32 v122, v122
	v_cndmask_b32_e32 v110, v112, v118, vcc
	v_cmp_gt_f32_e32 vcc, 0, v111
	v_and_b32_e32 v112, 0x7fffffff, v104
	v_exp_f32_e32 v123, v123
	v_cndmask_b32_e32 v111, v113, v119, vcc
	v_and_b32_e32 v113, 0x7fffffff, v105
	v_pk_fma_f32 v[112:113], v[112:113], s[90:91], 1.0 op_sel_hi:[1,0,0]
	v_cmp_gt_f32_e32 vcc, 0, v104
	v_rcp_f32_e32 v112, v112
	v_rcp_f32_e32 v113, v113
	s_nop 0
	v_pk_fma_f32 v[118:119], v[112:113], s[92:93], v[116:117] op_sel_hi:[1,0,0]
	v_pk_fma_f32 v[118:119], v[112:113], v[118:119], s[96:97] op_sel_hi:[1,1,0]
	v_pk_fma_f32 v[118:119], v[112:113], v[118:119], s[16:17] op_sel_hi:[1,1,0]
	v_pk_fma_f32 v[118:119], v[112:113], v[118:119], s[84:85] op_sel_hi:[1,1,0]
	v_pk_mul_f32 v[112:113], v[112:113], v[118:119]
	v_pk_mul_f32 v[118:119], v[106:107], v[106:107]
	v_pk_mul_f32 v[112:113], v[122:123], v[112:113]
	v_pk_mul_f32 v[122:123], v[104:105], v[112:113]
	v_pk_fma_f32 v[112:113], v[104:105], v[112:113], v[104:105] neg_lo:[1,0,0] neg_hi:[1,0,0]
	v_cndmask_b32_e32 v104, v112, v122, vcc
	v_cmp_gt_f32_e32 vcc, 0, v105
	v_and_b32_e32 v112, 0x7fffffff, v106
	s_nop 0
	v_cndmask_b32_e32 v105, v113, v123, vcc
	v_and_b32_e32 v113, 0x7fffffff, v107
	v_pk_fma_f32 v[112:113], v[112:113], s[90:91], 1.0 op_sel_hi:[1,0,0]
	v_cmp_gt_f32_e32 vcc, 0, v106
	v_rcp_f32_e32 v112, v112
	v_rcp_f32_e32 v113, v113
	s_nop 0
	v_pk_fma_f32 v[116:117], v[112:113], s[92:93], v[116:117] op_sel_hi:[1,0,0]
	v_pk_fma_f32 v[116:117], v[112:113], v[116:117], s[96:97] op_sel_hi:[1,1,0]
	v_pk_fma_f32 v[116:117], v[112:113], v[116:117], s[16:17] op_sel_hi:[1,1,0]
	v_pk_fma_f32 v[116:117], v[112:113], v[116:117], s[84:85] op_sel_hi:[1,1,0]
	v_pk_mul_f32 v[112:113], v[112:113], v[116:117]
	v_pk_mul_f32 v[116:117], v[118:119], s[18:19] op_sel_hi:[1,0]
	v_exp_f32_e32 v116, v116
	v_exp_f32_e32 v117, v117
	s_nop 0
	v_pk_mul_f32 v[112:113], v[116:117], v[112:113]
	v_pk_mul_f32 v[116:117], v[106:107], v[112:113]
	v_pk_fma_f32 v[112:113], v[106:107], v[112:113], v[106:107] neg_lo:[1,0,0] neg_hi:[1,0,0]
	v_cndmask_b32_e32 v106, v112, v116, vcc
	v_cmp_gt_f32_e32 vcc, 0, v107
	s_nop 1
	v_cndmask_b32_e32 v107, v113, v117, vcc
; __device__ __forceinline__ u32x4 pack8(f32x4 v0, f32x4 v1) { u32x4 w; w.x = cvt_pk_bf16(v0[0], v0[1]); w.y = cvt_pk_bf16(v0[2], v0[3]); w.z = cvt_pk_bf16(v1[0], v1[1]); w.w = cvt_pk_bf16(v1[2], v1[3]); return w; }
; __device__ __forceinline__ f32x4 gelu4(f32x4 v) { f32x2 a = gelu_pk((f32x2){v[0], v[1]}), b = gelu_pk((f32x2){v[2], v[3]}); return (f32x4){a.x, a.y, b.x, b.y}; }
; __device__ __forceinline__ f32x2 gelu_pk(f32x2 v) {
;     const f32x2 av = __builtin_elementwise_abs(v), d = av * 0.2316418882f + 1.0f;
;     f32x2 t; t.x = __builtin_amdgcn_rcpf(d.x); t.y = __builtin_amdgcn_rcpf(d.y);
;     f32x2 q = t * 0.5307027145f + (-0.7265760135f); q = q * t + 0.7107068705f; q = q * t + (-0.142248368f); q = q * t + 0.127414796f; q = q * t;
;     const f32x2 s = (v * v) * (-0.72134752044f);
;     f32x2 e; e.x = __builtin_amdgcn_exp2f(s.x); e.y = __builtin_amdgcn_exp2f(s.y);
;     const f32x2 m = v * (q * e), r = v - m;
;     f32x2 o; o.x = v.x < 0.f ? m.x : r.x; o.y = v.y < 0.f ? m.y : r.y; return o;
;     __device__ __forceinline__ void operator()(f32x4 (&acc)[2][2][4][2], const Unit& u, int wr, int wc, int fr_, int fq_) const {
;     ...
;                 for (int bj = 0; bj < 2; ++bj) { f32x4 v0 = acc[ai][bj][m][0] * rs, v1 = acc[ai][bj][m][1] * rs;
;                     if (act) { v0 = gelu4(v0); v1 = gelu4(v1); }
;                     s1 += ((v0[0] + v0[1]) + (v0[2] + v0[3])) + ((v1[0] + v1[1]) + (v1[2] + v1[3]));
;                     s2 += ((v0[0] * v0[0] + v0[1] * v0[1]) + (v0[2] * v0[2] + v0[3] * v0[3])) + ((v1[0] * v1[0] + v1[1] * v1[1]) + (v1[2] * v1[2] + v1[3] * v1[3]));
;                     *(u32x4*)(rowp + bj * HALF) = pack8(v0, v1); }
.LBB0_364:
	v_add_u32_e32 v112, 16, v146
	v_ashrrev_i32_e32 v113, 31, v112
	v_mul_lo_u32 v118, s86, v113
	v_mul_lo_u32 v119, s87, v112
	v_mad_u64_u32 v[116:117], s[10:11], s86, v112, 0
	v_mov_b32_e32 v115, v114
	v_add3_u32 v117, v117, v118, v119
	v_mov_b32_e32 v118, v114
	v_mov_b32_e32 v119, v114
	v_lshl_add_u64 v[116:117], v[116:117], 1, v[120:121]
	v_cvt_pk_bf16_f32 v122, v108, v109
	v_cvt_pk_bf16_f32 v123, v110, v111
	v_cvt_pk_bf16_f32 v124, v104, v105
	v_cvt_pk_bf16_f32 v125, v106, v107
	v_pk_mul_f32 v[102:103], v[102:103], v[118:119]
	v_pk_mul_f32 v[100:101], v[100:101], v[114:115]
	v_pk_mul_f32 v[98:99], v[98:99], v[118:119]
	s_and_b64 vcc, exec, s[6:7]
	v_pk_mul_f32 v[96:97], v[96:97], v[114:115]
	global_store_dwordx4 v[116:117], v[122:125], off
	s_cbranch_vccnz .LBB0_366
	v_and_b32_e32 v115, 0x7fffffff, v101
	v_and_b32_e32 v114, 0x7fffffff, v100
	v_pk_fma_f32 v[114:115], v[114:115], s[90:91], 1.0 op_sel_hi:[1,0,0]
	v_mov_b64_e32 v[118:119], s[94:95]
	v_rcp_f32_e32 v114, v114
	v_rcp_f32_e32 v115, v115
	v_pk_mul_f32 v[124:125], v[100:101], v[100:101]
	v_cmp_gt_f32_e32 vcc, 0, v100
	v_pk_mul_f32 v[124:125], v[124:125], s[18:19] op_sel_hi:[1,0]
	v_pk_fma_f32 v[122:123], v[114:115], s[92:93], v[118:119] op_sel_hi:[1,0,0]
	v_exp_f32_e32 v124, v124
	v_pk_fma_f32 v[122:123], v[114:115], v[122:123], s[96:97] op_sel_hi:[1,1,0]
	v_exp_f32_e32 v125, v125
	v_pk_fma_f32 v[122:123], v[114:115], v[122:123], s[16:17] op_sel_hi:[1,1,0]
	v_pk_fma_f32 v[122:123], v[114:115], v[122:123], s[84:85] op_sel_hi:[1,1,0]
	v_pk_mul_f32 v[114:115], v[114:115], v[122:123]
	v_pk_mul_f32 v[122:123], v[102:103], v[102:103]
	v_pk_mul_f32 v[114:115], v[124:125], v[114:115]
	v_pk_mul_f32 v[122:123], v[122:123], s[18:19] op_sel_hi:[1,0]
	v_pk_mul_f32 v[124:125], v[100:101], v[114:115]
	v_pk_fma_f32 v[114:115], v[100:101], v[114:115], v[100:101] neg_lo:[1,0,0] neg_hi:[1,0,0]
	v_exp_f32_e32 v122, v122
	v_cndmask_b32_e32 v100, v114, v124, vcc
	v_cmp_gt_f32_e32 vcc, 0, v101
	v_and_b32_e32 v114, 0x7fffffff, v102
	v_exp_f32_e32 v123, v123
	v_cndmask_b32_e32 v101, v115, v125, vcc
	v_and_b32_e32 v115, 0x7fffffff, v103
	v_pk_fma_f32 v[114:115], v[114:115], s[90:91], 1.0 op_sel_hi:[1,0,0]
	v_cmp_gt_f32_e32 vcc, 0, v102
	v_rcp_f32_e32 v114, v114
	v_rcp_f32_e32 v115, v115
	s_nop 0
	v_pk_fma_f32 v[124:125], v[114:115], s[92:93], v[118:119] op_sel_hi:[1,0,0]
	v_pk_fma_f32 v[124:125], v[114:115], v[124:125], s[96:97] op_sel_hi:[1,1,0]
	v_pk_fma_f32 v[124:125], v[114:115], v[124:125], s[16:17] op_sel_hi:[1,1,0]
	v_pk_fma_f32 v[124:125], v[114:115], v[124:125], s[84:85] op_sel_hi:[1,1,0]
	v_pk_mul_f32 v[114:115], v[114:115], v[124:125]
	v_pk_mul_f32 v[124:125], v[96:97], v[96:97]
	v_pk_mul_f32 v[114:115], v[122:123], v[114:115]
	v_pk_mul_f32 v[124:125], v[124:125], s[18:19] op_sel_hi:[1,0]
	v_pk_mul_f32 v[122:123], v[102:103], v[114:115]
	v_pk_fma_f32 v[114:115], v[102:103], v[114:115], v[102:103] neg_lo:[1,0,0] neg_hi:[1,0,0]
	v_exp_f32_e32 v124, v124
	v_cndmask_b32_e32 v102, v114, v122, vcc
	v_cmp_gt_f32_e32 vcc, 0, v103
	v_and_b32_e32 v114, 0x7fffffff, v96
	v_exp_f32_e32 v125, v125
	v_cndmask_b32_e32 v103, v115, v123, vcc
	v_and_b32_e32 v115, 0x7fffffff, v97
	v_pk_fma_f32 v[114:115], v[114:115], s[90:91], 1.0 op_sel_hi:[1,0,0]
	v_cmp_gt_f32_e32 vcc, 0, v96
	v_rcp_f32_e32 v114, v114
	v_rcp_f32_e32 v115, v115
	s_nop 0
	v_pk_fma_f32 v[122:123], v[114:115], s[92:93], v[118:119] op_sel_hi:[1,0,0]
	v_pk_fma_f32 v[122:123], v[114:115], v[122:123], s[96:97] op_sel_hi:[1,1,0]
	v_pk_fma_f32 v[122:123], v[114:115], v[122:123], s[16:17] op_sel_hi:[1,1,0]
	v_pk_fma_f32 v[122:123], v[114:115], v[122:123], s[84:85] op_sel_hi:[1,1,0]
	v_pk_mul_f32 v[114:115], v[114:115], v[122:123]
	v_pk_mul_f32 v[122:123], v[98:99], v[98:99]
	v_pk_mul_f32 v[114:115], v[124:125], v[114:115]
	v_pk_mul_f32 v[124:125], v[96:97], v[114:115]
	v_pk_fma_f32 v[114:115], v[96:97], v[114:115], v[96:97] neg_lo:[1,0,0] neg_hi:[1,0,0]
	v_cndmask_b32_e32 v96, v114, v124, vcc
	v_cmp_gt_f32_e32 vcc, 0, v97
	v_and_b32_e32 v114, 0x7fffffff, v98
	s_nop 0
	v_cndmask_b32_e32 v97, v115, v125, vcc
	v_and_b32_e32 v115, 0x7fffffff, v99
	v_pk_fma_f32 v[114:115], v[114:115], s[90:91], 1.0 op_sel_hi:[1,0,0]
	v_cmp_gt_f32_e32 vcc, 0, v98
	v_rcp_f32_e32 v114, v114
	v_rcp_f32_e32 v115, v115
	s_nop 0
	v_pk_fma_f32 v[118:119], v[114:115], s[92:93], v[118:119] op_sel_hi:[1,0,0]
	v_pk_fma_f32 v[118:119], v[114:115], v[118:119], s[96:97] op_sel_hi:[1,1,0]
	v_pk_fma_f32 v[118:119], v[114:115], v[118:119], s[16:17] op_sel_hi:[1,1,0]
	v_pk_fma_f32 v[118:119], v[114:115], v[118:119], s[84:85] op_sel_hi:[1,1,0]
	v_pk_mul_f32 v[114:115], v[114:115], v[118:119]
	v_pk_mul_f32 v[118:119], v[122:123], s[18:19] op_sel_hi:[1,0]
	v_exp_f32_e32 v118, v118
	v_exp_f32_e32 v119, v119
	s_nop 0
	v_pk_mul_f32 v[114:115], v[118:119], v[114:115]
	v_pk_mul_f32 v[118:119], v[98:99], v[114:115]
	v_pk_fma_f32 v[114:115], v[98:99], v[114:115], v[98:99] neg_lo:[1,0,0] neg_hi:[1,0,0]
	v_cndmask_b32_e32 v98, v114, v118, vcc
	v_cmp_gt_f32_e32 vcc, 0, v99
	s_nop 1
	v_cndmask_b32_e32 v99, v115, v119, vcc

; __device__ __forceinline__ f32x4 gelu4(f32x4 v) { f32x2 a = gelu_pk((f32x2){v[0], v[1]}), b = gelu_pk((f32x2){v[2], v[3]}); return (f32x4){a.x, a.y, b.x, b.y}; }
; __device__ __forceinline__ f32x2 gelu_pk(f32x2 v) {
;     const f32x2 av = __builtin_elementwise_abs(v), d = av * 0.2316418882f + 1.0f;
;     f32x2 t; t.x = __builtin_amdgcn_rcpf(d.x); t.y = __builtin_amdgcn_rcpf(d.y);
;     f32x2 q = t * 0.5307027145f + (-0.7265760135f); q = q * t + 0.7107068705f; q = q * t + (-0.142248368f); q = q * t + 0.127414796f; q = q * t;
;     const f32x2 s = (v * v) * (-0.72134752044f);
;     f32x2 e; e.x = __builtin_amdgcn_exp2f(s.x); e.y = __builtin_amdgcn_exp2f(s.y);
;     const f32x2 m = v * (q * e), r = v - m;
;     f32x2 o; o.x = v.x < 0.f ? m.x : r.x; o.y = v.y < 0.f ? m.y : r.y; return o;
;     __device__ __forceinline__ void operator()(f32x4 (&acc)[2][2][4][2], const Unit& u, int wr, int wc, int fr_, int fq_) const {
;     ...
;             for (int m = 0; m < 4; ++m) { const int row = row0 + ai * HALF + m * 16; const float rs = rstd[row]; bf16_t* rowp = base + (size_t)row * ld + col0;
;                 float s1 = 0.f, s2 = 0.f;
; #pragma unroll
;                 for (int bj = 0; bj < 2; ++bj) { f32x4 v0 = acc[ai][bj][m][0] * rs, v1 = acc[ai][bj][m][1] * rs;
;                     if (act) { v0 = gelu4(v0); v1 = gelu4(v1); }
.LBB0_370:
	v_mov_b32_e32 v98, v246
	s_and_b64 vcc, exec, s[6:7]
	s_waitcnt lgkmcnt(0)
	v_pk_mul_f32 v[94:95], v[94:95], v[98:99] op_sel_hi:[1,0]
	v_pk_mul_f32 v[92:93], v[92:93], v[98:99] op_sel_hi:[1,0]
	v_pk_mul_f32 v[90:91], v[90:91], v[98:99] op_sel_hi:[1,0]
	v_pk_mul_f32 v[88:89], v[88:89], v[98:99] op_sel_hi:[1,0]
	s_cbranch_vccnz .LBB0_372
	v_and_b32_e32 v97, 0x7fffffff, v93
	v_and_b32_e32 v96, 0x7fffffff, v92
	v_pk_fma_f32 v[96:97], v[96:97], s[90:91], 1.0 op_sel_hi:[1,0,0]
	v_mov_b64_e32 v[100:101], s[94:95]
	v_rcp_f32_e32 v96, v96
	v_rcp_f32_e32 v97, v97
	v_pk_mul_f32 v[104:105], v[92:93], v[92:93]
	v_cmp_gt_f32_e32 vcc, 0, v92
	v_pk_mul_f32 v[104:105], v[104:105], s[18:19] op_sel_hi:[1,0]
	v_pk_fma_f32 v[102:103], v[96:97], s[92:93], v[100:101] op_sel_hi:[1,0,0]
	v_exp_f32_e32 v104, v104
	v_pk_fma_f32 v[102:103], v[96:97], v[102:103], s[96:97] op_sel_hi:[1,1,0]
	v_exp_f32_e32 v105, v105
	v_pk_fma_f32 v[102:103], v[96:97], v[102:103], s[16:17] op_sel_hi:[1,1,0]
	v_pk_fma_f32 v[102:103], v[96:97], v[102:103], s[84:85] op_sel_hi:[1,1,0]
	v_pk_mul_f32 v[96:97], v[96:97], v[102:103]
	v_pk_mul_f32 v[102:103], v[94:95], v[94:95]
	v_pk_mul_f32 v[96:97], v[104:105], v[96:97]
	v_pk_mul_f32 v[102:103], v[102:103], s[18:19] op_sel_hi:[1,0]
	v_pk_mul_f32 v[104:105], v[92:93], v[96:97]
	v_pk_fma_f32 v[96:97], v[92:93], v[96:97], v[92:93] neg_lo:[1,0,0] neg_hi:[1,0,0]
	v_exp_f32_e32 v102, v102
	v_cndmask_b32_e32 v92, v96, v104, vcc
	v_cmp_gt_f32_e32 vcc, 0, v93
	v_and_b32_e32 v96, 0x7fffffff, v94
	v_exp_f32_e32 v103, v103
	v_cndmask_b32_e32 v93, v97, v105, vcc
	v_and_b32_e32 v97, 0x7fffffff, v95
	v_pk_fma_f32 v[96:97], v[96:97], s[90:91], 1.0 op_sel_hi:[1,0,0]
	v_cmp_gt_f32_e32 vcc, 0, v94
	v_rcp_f32_e32 v96, v96
	v_rcp_f32_e32 v97, v97
	s_nop 0
	v_pk_fma_f32 v[104:105], v[96:97], s[92:93], v[100:101] op_sel_hi:[1,0,0]
	v_pk_fma_f32 v[104:105], v[96:97], v[104:105], s[96:97] op_sel_hi:[1,1,0]
	v_pk_fma_f32 v[104:105], v[96:97], v[104:105], s[16:17] op_sel_hi:[1,1,0]
	v_pk_fma_f32 v[104:105], v[96:97], v[104:105], s[84:85] op_sel_hi:[1,1,0]
	v_pk_mul_f32 v[96:97], v[96:97], v[104:105]
	v_pk_mul_f32 v[104:105], v[88:89], v[88:89]
	v_pk_mul_f32 v[96:97], v[102:103], v[96:97]
	v_pk_mul_f32 v[104:105], v[104:105], s[18:19] op_sel_hi:[1,0]
	v_pk_mul_f32 v[102:103], v[94:95], v[96:97]
	v_pk_fma_f32 v[96:97], v[94:95], v[96:97], v[94:95] neg_lo:[1,0,0] neg_hi:[1,0,0]
	v_exp_f32_e32 v104, v104
	v_cndmask_b32_e32 v94, v96, v102, vcc
	v_cmp_gt_f32_e32 vcc, 0, v95
	v_and_b32_e32 v96, 0x7fffffff, v88
	v_exp_f32_e32 v105, v105
	v_cndmask_b32_e32 v95, v97, v103, vcc
	v_and_b32_e32 v97, 0x7fffffff, v89
	v_pk_fma_f32 v[96:97], v[96:97], s[90:91], 1.0 op_sel_hi:[1,0,0]
	v_cmp_gt_f32_e32 vcc, 0, v88
	v_rcp_f32_e32 v96, v96
	v_rcp_f32_e32 v97, v97
	s_nop 0
	v_pk_fma_f32 v[102:103], v[96:97], s[92:93], v[100:101] op_sel_hi:[1,0,0]
	v_pk_fma_f32 v[102:103], v[96:97], v[102:103], s[96:97] op_sel_hi:[1,1,0]
	v_pk_fma_f32 v[102:103], v[96:97], v[102:103], s[16:17] op_sel_hi:[1,1,0]
	v_pk_fma_f32 v[102:103], v[96:97], v[102:103], s[84:85] op_sel_hi:[1,1,0]
	v_pk_mul_f32 v[96:97], v[96:97], v[102:103]
	v_pk_mul_f32 v[102:103], v[90:91], v[90:91]
	v_pk_mul_f32 v[96:97], v[104:105], v[96:97]
	v_pk_mul_f32 v[104:105], v[88:89], v[96:97]
	v_pk_fma_f32 v[96:97], v[88:89], v[96:97], v[88:89] neg_lo:[1,0,0] neg_hi:[1,0,0]
	v_cndmask_b32_e32 v88, v96, v104, vcc
	v_cmp_gt_f32_e32 vcc, 0, v89
	v_and_b32_e32 v96, 0x7fffffff, v90
	s_nop 0
	v_cndmask_b32_e32 v89, v97, v105, vcc
	v_and_b32_e32 v97, 0x7fffffff, v91
	v_pk_fma_f32 v[96:97], v[96:97], s[90:91], 1.0 op_sel_hi:[1,0,0]
	v_cmp_gt_f32_e32 vcc, 0, v90
	v_rcp_f32_e32 v96, v96
	v_rcp_f32_e32 v97, v97
	s_nop 0
	v_pk_fma_f32 v[100:101], v[96:97], s[92:93], v[100:101] op_sel_hi:[1,0,0]
	v_pk_fma_f32 v[100:101], v[96:97], v[100:101], s[96:97] op_sel_hi:[1,1,0]
	v_pk_fma_f32 v[100:101], v[96:97], v[100:101], s[16:17] op_sel_hi:[1,1,0]
	v_pk_fma_f32 v[100:101], v[96:97], v[100:101], s[84:85] op_sel_hi:[1,1,0]
	v_pk_mul_f32 v[96:97], v[96:97], v[100:101]
	v_pk_mul_f32 v[100:101], v[102:103], s[18:19] op_sel_hi:[1,0]
	v_exp_f32_e32 v100, v100
	v_exp_f32_e32 v101, v101
	s_nop 0
	v_pk_mul_f32 v[96:97], v[100:101], v[96:97]
	v_pk_mul_f32 v[100:101], v[90:91], v[96:97]
	v_pk_fma_f32 v[96:97], v[90:91], v[96:97], v[90:91] neg_lo:[1,0,0] neg_hi:[1,0,0]
	v_cndmask_b32_e32 v90, v96, v100, vcc
	v_cmp_gt_f32_e32 vcc, 0, v91
	s_nop 1
	v_cndmask_b32_e32 v91, v97, v101, vcc
; __device__ __forceinline__ u32x4 pack8(f32x4 v0, f32x4 v1) { u32x4 w; w.x = cvt_pk_bf16(v0[0], v0[1]); w.y = cvt_pk_bf16(v0[2], v0[3]); w.z = cvt_pk_bf16(v1[0], v1[1]); w.w = cvt_pk_bf16(v1[2], v1[3]); return w; }
; __device__ __forceinline__ f32x4 gelu4(f32x4 v) { f32x2 a = gelu_pk((f32x2){v[0], v[1]}), b = gelu_pk((f32x2){v[2], v[3]}); return (f32x4){a.x, a.y, b.x, b.y}; }
; __device__ __forceinline__ f32x2 gelu_pk(f32x2 v) {
;     const f32x2 av = __builtin_elementwise_abs(v), d = av * 0.2316418882f + 1.0f;
;     f32x2 t; t.x = __builtin_amdgcn_rcpf(d.x); t.y = __builtin_amdgcn_rcpf(d.y);
;     f32x2 q = t * 0.5307027145f + (-0.7265760135f); q = q * t + 0.7107068705f; q = q * t + (-0.142248368f); q = q * t + 0.127414796f; q = q * t;
;     const f32x2 s = (v * v) * (-0.72134752044f);
;     f32x2 e; e.x = __builtin_amdgcn_exp2f(s.x); e.y = __builtin_amdgcn_exp2f(s.y);
;     const f32x2 m = v * (q * e), r = v - m;
;     f32x2 o; o.x = v.x < 0.f ? m.x : r.x; o.y = v.y < 0.f ? m.y : r.y; return o;
;     __device__ __forceinline__ void operator()(f32x4 (&acc)[2][2][4][2], const Unit& u, int wr, int wc, int fr_, int fq_) const {
;     ...
;                 for (int bj = 0; bj < 2; ++bj) { f32x4 v0 = acc[ai][bj][m][0] * rs, v1 = acc[ai][bj][m][1] * rs;
;                     if (act) { v0 = gelu4(v0); v1 = gelu4(v1); }
;                     s1 += ((v0[0] + v0[1]) + (v0[2] + v0[3])) + ((v1[0] + v1[1]) + (v1[2] + v1[3]));
;                     s2 += ((v0[0] * v0[0] + v0[1] * v0[1]) + (v0[2] * v0[2] + v0[3] * v0[3])) + ((v1[0] * v1[0] + v1[1] * v1[1]) + (v1[2] * v1[2] + v1[3] * v1[3]));
;                     *(u32x4*)(rowp + bj * HALF) = pack8(v0, v1); }
.LBB0_372:
	v_add_u32_e32 v96, 32, v146
	v_ashrrev_i32_e32 v97, 31, v96
	v_mul_lo_u32 v102, s86, v97
	v_mul_lo_u32 v103, s87, v96
	v_mad_u64_u32 v[100:101], s[14:15], s86, v96, 0
	v_add3_u32 v101, v101, v102, v103
	v_lshl_add_u64 v[100:101], v[100:101], 1, v[120:121]
	v_cvt_pk_bf16_f32 v102, v92, v93
	v_cvt_pk_bf16_f32 v103, v94, v95
	v_cvt_pk_bf16_f32 v104, v88, v89
	v_cvt_pk_bf16_f32 v105, v90, v91
	v_mov_b32_e32 v99, v98
	global_store_dwordx4 v[100:101], v[102:105], off
	v_pk_mul_f32 v[84:85], v[84:85], v[98:99]
	s_and_b64 vcc, exec, s[6:7]
	v_mov_b32_e32 v102, v98
	v_mov_b32_e32 v103, v98
	v_pk_mul_f32 v[86:87], v[86:87], v[102:103]
	v_pk_mul_f32 v[82:83], v[82:83], v[102:103]
	v_pk_mul_f32 v[80:81], v[80:81], v[98:99]
	s_cbranch_vccnz .LBB0_374
	v_and_b32_e32 v99, 0x7fffffff, v85
	v_and_b32_e32 v98, 0x7fffffff, v84
	v_pk_fma_f32 v[98:99], v[98:99], s[90:91], 1.0 op_sel_hi:[1,0,0]
	v_mov_b64_e32 v[102:103], s[94:95]
	v_rcp_f32_e32 v98, v98
	v_rcp_f32_e32 v99, v99
	v_pk_mul_f32 v[106:107], v[84:85], v[84:85]
	v_cmp_gt_f32_e32 vcc, 0, v84
	v_pk_mul_f32 v[106:107], v[106:107], s[18:19] op_sel_hi:[1,0]
	v_pk_fma_f32 v[104:105], v[98:99], s[92:93], v[102:103] op_sel_hi:[1,0,0]
	v_exp_f32_e32 v106, v106
	v_pk_fma_f32 v[104:105], v[98:99], v[104:105], s[96:97] op_sel_hi:[1,1,0]
	v_exp_f32_e32 v107, v107
	v_pk_fma_f32 v[104:105], v[98:99], v[104:105], s[16:17] op_sel_hi:[1,1,0]
	v_pk_fma_f32 v[104:105], v[98:99], v[104:105], s[84:85] op_sel_hi:[1,1,0]
	v_pk_mul_f32 v[98:99], v[98:99], v[104:105]
	v_pk_mul_f32 v[104:105], v[86:87], v[86:87]
	v_pk_mul_f32 v[98:99], v[106:107], v[98:99]
	v_pk_mul_f32 v[104:105], v[104:105], s[18:19] op_sel_hi:[1,0]
	v_pk_mul_f32 v[106:107], v[84:85], v[98:99]
	v_pk_fma_f32 v[98:99], v[84:85], v[98:99], v[84:85] neg_lo:[1,0,0] neg_hi:[1,0,0]
	v_exp_f32_e32 v104, v104
	v_cndmask_b32_e32 v84, v98, v106, vcc
	v_cmp_gt_f32_e32 vcc, 0, v85
	v_and_b32_e32 v98, 0x7fffffff, v86
	v_exp_f32_e32 v105, v105
	v_cndmask_b32_e32 v85, v99, v107, vcc
	v_and_b32_e32 v99, 0x7fffffff, v87
	v_pk_fma_f32 v[98:99], v[98:99], s[90:91], 1.0 op_sel_hi:[1,0,0]
	v_cmp_gt_f32_e32 vcc, 0, v86
	v_rcp_f32_e32 v98, v98
	v_rcp_f32_e32 v99, v99
	s_nop 0
	v_pk_fma_f32 v[106:107], v[98:99], s[92:93], v[102:103] op_sel_hi:[1,0,0]
	v_pk_fma_f32 v[106:107], v[98:99], v[106:107], s[96:97] op_sel_hi:[1,1,0]
	v_pk_fma_f32 v[106:107], v[98:99], v[106:107], s[16:17] op_sel_hi:[1,1,0]
	v_pk_fma_f32 v[106:107], v[98:99], v[106:107], s[84:85] op_sel_hi:[1,1,0]
	v_pk_mul_f32 v[98:99], v[98:99], v[106:107]
	v_pk_mul_f32 v[106:107], v[80:81], v[80:81]
	v_pk_mul_f32 v[98:99], v[104:105], v[98:99]
	v_pk_mul_f32 v[106:107], v[106:107], s[18:19] op_sel_hi:[1,0]
	v_pk_mul_f32 v[104:105], v[86:87], v[98:99]
	v_pk_fma_f32 v[98:99], v[86:87], v[98:99], v[86:87] neg_lo:[1,0,0] neg_hi:[1,0,0]
	v_exp_f32_e32 v106, v106
	v_cndmask_b32_e32 v86, v98, v104, vcc
	v_cmp_gt_f32_e32 vcc, 0, v87
	v_and_b32_e32 v98, 0x7fffffff, v80
	v_exp_f32_e32 v107, v107
	v_cndmask_b32_e32 v87, v99, v105, vcc
	v_and_b32_e32 v99, 0x7fffffff, v81
	v_pk_fma_f32 v[98:99], v[98:99], s[90:91], 1.0 op_sel_hi:[1,0,0]
	v_cmp_gt_f32_e32 vcc, 0, v80
	v_rcp_f32_e32 v98, v98
	v_rcp_f32_e32 v99, v99
	s_nop 0
	v_pk_fma_f32 v[104:105], v[98:99], s[92:93], v[102:103] op_sel_hi:[1,0,0]
	v_pk_fma_f32 v[104:105], v[98:99], v[104:105], s[96:97] op_sel_hi:[1,1,0]
	v_pk_fma_f32 v[104:105], v[98:99], v[104:105], s[16:17] op_sel_hi:[1,1,0]
	v_pk_fma_f32 v[104:105], v[98:99], v[104:105], s[84:85] op_sel_hi:[1,1,0]
	v_pk_mul_f32 v[98:99], v[98:99], v[104:105]
	v_pk_mul_f32 v[104:105], v[82:83], v[82:83]
	v_pk_mul_f32 v[98:99], v[106:107], v[98:99]
	v_pk_mul_f32 v[106:107], v[80:81], v[98:99]
	v_pk_fma_f32 v[98:99], v[80:81], v[98:99], v[80:81] neg_lo:[1,0,0] neg_hi:[1,0,0]
	v_cndmask_b32_e32 v80, v98, v106, vcc
	v_cmp_gt_f32_e32 vcc, 0, v81
	v_and_b32_e32 v98, 0x7fffffff, v82
	s_nop 0
	v_cndmask_b32_e32 v81, v99, v107, vcc
	v_and_b32_e32 v99, 0x7fffffff, v83
	v_pk_fma_f32 v[98:99], v[98:99], s[90:91], 1.0 op_sel_hi:[1,0,0]
	v_cmp_gt_f32_e32 vcc, 0, v82
	v_rcp_f32_e32 v98, v98
	v_rcp_f32_e32 v99, v99
	s_nop 0
	v_pk_fma_f32 v[102:103], v[98:99], s[92:93], v[102:103] op_sel_hi:[1,0,0]
	v_pk_fma_f32 v[102:103], v[98:99], v[102:103], s[96:97] op_sel_hi:[1,1,0]
	v_pk_fma_f32 v[102:103], v[98:99], v[102:103], s[16:17] op_sel_hi:[1,1,0]
	v_pk_fma_f32 v[102:103], v[98:99], v[102:103], s[84:85] op_sel_hi:[1,1,0]
	v_pk_mul_f32 v[98:99], v[98:99], v[102:103]
	v_pk_mul_f32 v[102:103], v[104:105], s[18:19] op_sel_hi:[1,0]
	v_exp_f32_e32 v102, v102
	v_exp_f32_e32 v103, v103
	s_nop 0
	v_pk_mul_f32 v[98:99], v[102:103], v[98:99]
	v_pk_mul_f32 v[102:103], v[82:83], v[98:99]
	v_pk_fma_f32 v[98:99], v[82:83], v[98:99], v[82:83] neg_lo:[1,0,0] neg_hi:[1,0,0]
	v_cndmask_b32_e32 v82, v98, v102, vcc
	v_cmp_gt_f32_e32 vcc, 0, v83
	s_nop 1
	v_cndmask_b32_e32 v83, v99, v103, vcc

; __device__ __forceinline__ f32x4 gelu4(f32x4 v) { f32x2 a = gelu_pk((f32x2){v[0], v[1]}), b = gelu_pk((f32x2){v[2], v[3]}); return (f32x4){a.x, a.y, b.x, b.y}; }
; __device__ __forceinline__ f32x2 gelu_pk(f32x2 v) {
;     const f32x2 av = __builtin_elementwise_abs(v), d = av * 0.2316418882f + 1.0f;
;     f32x2 t; t.x = __builtin_amdgcn_rcpf(d.x); t.y = __builtin_amdgcn_rcpf(d.y);
;     f32x2 q = t * 0.5307027145f + (-0.7265760135f); q = q * t + 0.7107068705f; q = q * t + (-0.142248368f); q = q * t + 0.127414796f; q = q * t;
;     const f32x2 s = (v * v) * (-0.72134752044f);
;     f32x2 e; e.x = __builtin_amdgcn_exp2f(s.x); e.y = __builtin_amdgcn_exp2f(s.y);
;     const f32x2 m = v * (q * e), r = v - m;
;     f32x2 o; o.x = v.x < 0.f ? m.x : r.x; o.y = v.y < 0.f ? m.y : r.y; return o;
;     __device__ __forceinline__ void operator()(f32x4 (&acc)[2][2][4][2], const Unit& u, int wr, int wc, int fr_, int fq_) const {
;     ...
;             for (int m = 0; m < 4; ++m) { const int row = row0 + ai * HALF + m * 16; const float rs = rstd[row]; bf16_t* rowp = base + (size_t)row * ld + col0;
;                 float s1 = 0.f, s2 = 0.f;
; #pragma unroll
;                 for (int bj = 0; bj < 2; ++bj) { f32x4 v0 = acc[ai][bj][m][0] * rs, v1 = acc[ai][bj][m][1] * rs;
;                     if (act) { v0 = gelu4(v0); v1 = gelu4(v1); }
.LBB0_378:
	v_mov_b32_e32 v82, v247
	s_and_b64 vcc, exec, s[6:7]
	s_waitcnt lgkmcnt(0)
	v_pk_mul_f32 v[78:79], v[78:79], v[82:83] op_sel_hi:[1,0]
	v_pk_mul_f32 v[76:77], v[76:77], v[82:83] op_sel_hi:[1,0]
	v_pk_mul_f32 v[74:75], v[74:75], v[82:83] op_sel_hi:[1,0]
	v_pk_mul_f32 v[72:73], v[72:73], v[82:83] op_sel_hi:[1,0]
	s_cbranch_vccnz .LBB0_380
	v_and_b32_e32 v81, 0x7fffffff, v77
	v_and_b32_e32 v80, 0x7fffffff, v76
	v_pk_fma_f32 v[80:81], v[80:81], s[90:91], 1.0 op_sel_hi:[1,0,0]
	v_mov_b64_e32 v[84:85], s[94:95]
	v_rcp_f32_e32 v80, v80
	v_rcp_f32_e32 v81, v81
	v_pk_mul_f32 v[88:89], v[76:77], v[76:77]
	v_cmp_gt_f32_e32 vcc, 0, v76
	v_pk_mul_f32 v[88:89], v[88:89], s[18:19] op_sel_hi:[1,0]
	v_pk_fma_f32 v[86:87], v[80:81], s[92:93], v[84:85] op_sel_hi:[1,0,0]
	v_exp_f32_e32 v88, v88
	v_pk_fma_f32 v[86:87], v[80:81], v[86:87], s[96:97] op_sel_hi:[1,1,0]
	v_exp_f32_e32 v89, v89
	v_pk_fma_f32 v[86:87], v[80:81], v[86:87], s[16:17] op_sel_hi:[1,1,0]
	v_pk_fma_f32 v[86:87], v[80:81], v[86:87], s[84:85] op_sel_hi:[1,1,0]
	v_pk_mul_f32 v[80:81], v[80:81], v[86:87]
	v_pk_mul_f32 v[86:87], v[78:79], v[78:79]
	v_pk_mul_f32 v[80:81], v[88:89], v[80:81]
	v_pk_mul_f32 v[86:87], v[86:87], s[18:19] op_sel_hi:[1,0]
	v_pk_mul_f32 v[88:89], v[76:77], v[80:81]
	v_pk_fma_f32 v[80:81], v[76:77], v[80:81], v[76:77] neg_lo:[1,0,0] neg_hi:[1,0,0]
	v_exp_f32_e32 v86, v86
	v_cndmask_b32_e32 v76, v80, v88, vcc
	v_cmp_gt_f32_e32 vcc, 0, v77
	v_and_b32_e32 v80, 0x7fffffff, v78
	v_exp_f32_e32 v87, v87
	v_cndmask_b32_e32 v77, v81, v89, vcc
	v_and_b32_e32 v81, 0x7fffffff, v79
	v_pk_fma_f32 v[80:81], v[80:81], s[90:91], 1.0 op_sel_hi:[1,0,0]
	v_cmp_gt_f32_e32 vcc, 0, v78
	v_rcp_f32_e32 v80, v80
	v_rcp_f32_e32 v81, v81
	s_nop 0
	v_pk_fma_f32 v[88:89], v[80:81], s[92:93], v[84:85] op_sel_hi:[1,0,0]
	v_pk_fma_f32 v[88:89], v[80:81], v[88:89], s[96:97] op_sel_hi:[1,1,0]
	v_pk_fma_f32 v[88:89], v[80:81], v[88:89], s[16:17] op_sel_hi:[1,1,0]
	v_pk_fma_f32 v[88:89], v[80:81], v[88:89], s[84:85] op_sel_hi:[1,1,0]
	v_pk_mul_f32 v[80:81], v[80:81], v[88:89]
	v_pk_mul_f32 v[88:89], v[72:73], v[72:73]
	v_pk_mul_f32 v[80:81], v[86:87], v[80:81]
	v_pk_mul_f32 v[88:89], v[88:89], s[18:19] op_sel_hi:[1,0]
	v_pk_mul_f32 v[86:87], v[78:79], v[80:81]
	v_pk_fma_f32 v[80:81], v[78:79], v[80:81], v[78:79] neg_lo:[1,0,0] neg_hi:[1,0,0]
	v_exp_f32_e32 v88, v88
	v_cndmask_b32_e32 v78, v80, v86, vcc
	v_cmp_gt_f32_e32 vcc, 0, v79
	v_and_b32_e32 v80, 0x7fffffff, v72
	v_exp_f32_e32 v89, v89
	v_cndmask_b32_e32 v79, v81, v87, vcc
	v_and_b32_e32 v81, 0x7fffffff, v73
	v_pk_fma_f32 v[80:81], v[80:81], s[90:91], 1.0 op_sel_hi:[1,0,0]
	v_cmp_gt_f32_e32 vcc, 0, v72
	v_rcp_f32_e32 v80, v80
	v_rcp_f32_e32 v81, v81
	s_nop 0
	v_pk_fma_f32 v[86:87], v[80:81], s[92:93], v[84:85] op_sel_hi:[1,0,0]
	v_pk_fma_f32 v[86:87], v[80:81], v[86:87], s[96:97] op_sel_hi:[1,1,0]
	v_pk_fma_f32 v[86:87], v[80:81], v[86:87], s[16:17] op_sel_hi:[1,1,0]
	v_pk_fma_f32 v[86:87], v[80:81], v[86:87], s[84:85] op_sel_hi:[1,1,0]
	v_pk_mul_f32 v[80:81], v[80:81], v[86:87]
	v_pk_mul_f32 v[86:87], v[74:75], v[74:75]
	v_pk_mul_f32 v[80:81], v[88:89], v[80:81]
	v_pk_mul_f32 v[88:89], v[72:73], v[80:81]
	v_pk_fma_f32 v[80:81], v[72:73], v[80:81], v[72:73] neg_lo:[1,0,0] neg_hi:[1,0,0]
	v_cndmask_b32_e32 v72, v80, v88, vcc
	v_cmp_gt_f32_e32 vcc, 0, v73
	v_and_b32_e32 v80, 0x7fffffff, v74
	s_nop 0
	v_cndmask_b32_e32 v73, v81, v89, vcc
	v_and_b32_e32 v81, 0x7fffffff, v75
	v_pk_fma_f32 v[80:81], v[80:81], s[90:91], 1.0 op_sel_hi:[1,0,0]
	v_cmp_gt_f32_e32 vcc, 0, v74
	v_rcp_f32_e32 v80, v80
	v_rcp_f32_e32 v81, v81
	s_nop 0
	v_pk_fma_f32 v[84:85], v[80:81], s[92:93], v[84:85] op_sel_hi:[1,0,0]
	v_pk_fma_f32 v[84:85], v[80:81], v[84:85], s[96:97] op_sel_hi:[1,1,0]
	v_pk_fma_f32 v[84:85], v[80:81], v[84:85], s[16:17] op_sel_hi:[1,1,0]
	v_pk_fma_f32 v[84:85], v[80:81], v[84:85], s[84:85] op_sel_hi:[1,1,0]
	v_pk_mul_f32 v[80:81], v[80:81], v[84:85]
	v_pk_mul_f32 v[84:85], v[86:87], s[18:19] op_sel_hi:[1,0]
	v_exp_f32_e32 v84, v84
	v_exp_f32_e32 v85, v85
	s_nop 0
	v_pk_mul_f32 v[80:81], v[84:85], v[80:81]
	v_pk_mul_f32 v[84:85], v[74:75], v[80:81]
	v_pk_fma_f32 v[80:81], v[74:75], v[80:81], v[74:75] neg_lo:[1,0,0] neg_hi:[1,0,0]
	v_cndmask_b32_e32 v74, v80, v84, vcc
	v_cmp_gt_f32_e32 vcc, 0, v75
	s_nop 1
	v_cndmask_b32_e32 v75, v81, v85, vcc
; __device__ __forceinline__ u32x4 pack8(f32x4 v0, f32x4 v1) { u32x4 w; w.x = cvt_pk_bf16(v0[0], v0[1]); w.y = cvt_pk_bf16(v0[2], v0[3]); w.z = cvt_pk_bf16(v1[0], v1[1]); w.w = cvt_pk_bf16(v1[2], v1[3]); return w; }
; __device__ __forceinline__ f32x4 gelu4(f32x4 v) { f32x2 a = gelu_pk((f32x2){v[0], v[1]}), b = gelu_pk((f32x2){v[2], v[3]}); return (f32x4){a.x, a.y, b.x, b.y}; }
; __device__ __forceinline__ f32x2 gelu_pk(f32x2 v) {
;     const f32x2 av = __builtin_elementwise_abs(v), d = av * 0.2316418882f + 1.0f;
;     f32x2 t; t.x = __builtin_amdgcn_rcpf(d.x); t.y = __builtin_amdgcn_rcpf(d.y);
;     f32x2 q = t * 0.5307027145f + (-0.7265760135f); q = q * t + 0.7107068705f; q = q * t + (-0.142248368f); q = q * t + 0.127414796f; q = q * t;
;     const f32x2 s = (v * v) * (-0.72134752044f);
;     f32x2 e; e.x = __builtin_amdgcn_exp2f(s.x); e.y = __builtin_amdgcn_exp2f(s.y);
;     const f32x2 m = v * (q * e), r = v - m;
;     f32x2 o; o.x = v.x < 0.f ? m.x : r.x; o.y = v.y < 0.f ? m.y : r.y; return o;
;     __device__ __forceinline__ void operator()(f32x4 (&acc)[2][2][4][2], const Unit& u, int wr, int wc, int fr_, int fq_) const {
;     ...
;                 for (int bj = 0; bj < 2; ++bj) { f32x4 v0 = acc[ai][bj][m][0] * rs, v1 = acc[ai][bj][m][1] * rs;
;                     if (act) { v0 = gelu4(v0); v1 = gelu4(v1); }
;                     s1 += ((v0[0] + v0[1]) + (v0[2] + v0[3])) + ((v1[0] + v1[1]) + (v1[2] + v1[3]));
;                     s2 += ((v0[0] * v0[0] + v0[1] * v0[1]) + (v0[2] * v0[2] + v0[3] * v0[3])) + ((v1[0] * v1[0] + v1[1] * v1[1]) + (v1[2] * v1[2] + v1[3] * v1[3]));
;                     *(u32x4*)(rowp + bj * HALF) = pack8(v0, v1); }
.LBB0_380:
	v_add_u32_e32 v80, 48, v146
	v_ashrrev_i32_e32 v81, 31, v80
	v_mul_lo_u32 v86, s86, v81
	v_mul_lo_u32 v87, s87, v80
	v_mad_u64_u32 v[84:85], s[14:15], s86, v80, 0
	v_add3_u32 v85, v85, v86, v87
	v_lshl_add_u64 v[84:85], v[84:85], 1, v[120:121]
	v_cvt_pk_bf16_f32 v86, v76, v77
	v_cvt_pk_bf16_f32 v87, v78, v79
	v_cvt_pk_bf16_f32 v88, v72, v73
	v_cvt_pk_bf16_f32 v89, v74, v75
	v_mov_b32_e32 v83, v82
	global_store_dwordx4 v[84:85], v[86:89], off
	v_pk_mul_f32 v[68:69], v[68:69], v[82:83]
	s_and_b64 vcc, exec, s[6:7]
	v_mov_b32_e32 v86, v82
	v_mov_b32_e32 v87, v82
	v_pk_mul_f32 v[70:71], v[70:71], v[86:87]
	v_pk_mul_f32 v[66:67], v[66:67], v[86:87]
	v_pk_mul_f32 v[64:65], v[64:65], v[82:83]
	s_cbranch_vccnz .LBB0_382
	v_and_b32_e32 v83, 0x7fffffff, v69
	v_and_b32_e32 v82, 0x7fffffff, v68
	v_pk_fma_f32 v[82:83], v[82:83], s[90:91], 1.0 op_sel_hi:[1,0,0]
	v_mov_b64_e32 v[86:87], s[94:95]
	v_rcp_f32_e32 v82, v82
	v_rcp_f32_e32 v83, v83
	v_pk_mul_f32 v[90:91], v[68:69], v[68:69]
	v_cmp_gt_f32_e32 vcc, 0, v68
	v_pk_mul_f32 v[90:91], v[90:91], s[18:19] op_sel_hi:[1,0]
	v_pk_fma_f32 v[88:89], v[82:83], s[92:93], v[86:87] op_sel_hi:[1,0,0]
	v_exp_f32_e32 v90, v90
	v_pk_fma_f32 v[88:89], v[82:83], v[88:89], s[96:97] op_sel_hi:[1,1,0]
	v_exp_f32_e32 v91, v91
	v_pk_fma_f32 v[88:89], v[82:83], v[88:89], s[16:17] op_sel_hi:[1,1,0]
	v_pk_fma_f32 v[88:89], v[82:83], v[88:89], s[84:85] op_sel_hi:[1,1,0]
	v_pk_mul_f32 v[82:83], v[82:83], v[88:89]
	v_pk_mul_f32 v[88:89], v[70:71], v[70:71]
	v_pk_mul_f32 v[82:83], v[90:91], v[82:83]
	v_pk_mul_f32 v[88:89], v[88:89], s[18:19] op_sel_hi:[1,0]
	v_pk_mul_f32 v[90:91], v[68:69], v[82:83]
	v_pk_fma_f32 v[82:83], v[68:69], v[82:83], v[68:69] neg_lo:[1,0,0] neg_hi:[1,0,0]
	v_exp_f32_e32 v88, v88
	v_cndmask_b32_e32 v68, v82, v90, vcc
	v_cmp_gt_f32_e32 vcc, 0, v69
	v_and_b32_e32 v82, 0x7fffffff, v70
	v_exp_f32_e32 v89, v89
	v_cndmask_b32_e32 v69, v83, v91, vcc
	v_and_b32_e32 v83, 0x7fffffff, v71
	v_pk_fma_f32 v[82:83], v[82:83], s[90:91], 1.0 op_sel_hi:[1,0,0]
	v_cmp_gt_f32_e32 vcc, 0, v70
	v_rcp_f32_e32 v82, v82
	v_rcp_f32_e32 v83, v83
	s_nop 0
	v_pk_fma_f32 v[90:91], v[82:83], s[92:93], v[86:87] op_sel_hi:[1,0,0]
	v_pk_fma_f32 v[90:91], v[82:83], v[90:91], s[96:97] op_sel_hi:[1,1,0]
	v_pk_fma_f32 v[90:91], v[82:83], v[90:91], s[16:17] op_sel_hi:[1,1,0]
	v_pk_fma_f32 v[90:91], v[82:83], v[90:91], s[84:85] op_sel_hi:[1,1,0]
	v_pk_mul_f32 v[82:83], v[82:83], v[90:91]
	v_pk_mul_f32 v[90:91], v[64:65], v[64:65]
	v_pk_mul_f32 v[82:83], v[88:89], v[82:83]
	v_pk_mul_f32 v[90:91], v[90:91], s[18:19] op_sel_hi:[1,0]
	v_pk_mul_f32 v[88:89], v[70:71], v[82:83]
	v_pk_fma_f32 v[82:83], v[70:71], v[82:83], v[70:71] neg_lo:[1,0,0] neg_hi:[1,0,0]
	v_exp_f32_e32 v90, v90
	v_cndmask_b32_e32 v70, v82, v88, vcc
	v_cmp_gt_f32_e32 vcc, 0, v71
	v_and_b32_e32 v82, 0x7fffffff, v64
	v_exp_f32_e32 v91, v91
	v_cndmask_b32_e32 v71, v83, v89, vcc
	v_and_b32_e32 v83, 0x7fffffff, v65
	v_pk_fma_f32 v[82:83], v[82:83], s[90:91], 1.0 op_sel_hi:[1,0,0]
	v_cmp_gt_f32_e32 vcc, 0, v64
	v_rcp_f32_e32 v82, v82
	v_rcp_f32_e32 v83, v83
	s_nop 0
	v_pk_fma_f32 v[88:89], v[82:83], s[92:93], v[86:87] op_sel_hi:[1,0,0]
	v_pk_fma_f32 v[88:89], v[82:83], v[88:89], s[96:97] op_sel_hi:[1,1,0]
	v_pk_fma_f32 v[88:89], v[82:83], v[88:89], s[16:17] op_sel_hi:[1,1,0]
	v_pk_fma_f32 v[88:89], v[82:83], v[88:89], s[84:85] op_sel_hi:[1,1,0]
	v_pk_mul_f32 v[82:83], v[82:83], v[88:89]
	v_pk_mul_f32 v[88:89], v[66:67], v[66:67]
	v_pk_mul_f32 v[82:83], v[90:91], v[82:83]
	v_pk_mul_f32 v[90:91], v[64:65], v[82:83]
	v_pk_fma_f32 v[82:83], v[64:65], v[82:83], v[64:65] neg_lo:[1,0,0] neg_hi:[1,0,0]
	v_cndmask_b32_e32 v64, v82, v90, vcc
	v_cmp_gt_f32_e32 vcc, 0, v65
	v_and_b32_e32 v82, 0x7fffffff, v66
	s_nop 0
	v_cndmask_b32_e32 v65, v83, v91, vcc
	v_and_b32_e32 v83, 0x7fffffff, v67
	v_pk_fma_f32 v[82:83], v[82:83], s[90:91], 1.0 op_sel_hi:[1,0,0]
	v_cmp_gt_f32_e32 vcc, 0, v66
	v_rcp_f32_e32 v82, v82
	v_rcp_f32_e32 v83, v83
	s_nop 0
	v_pk_fma_f32 v[86:87], v[82:83], s[92:93], v[86:87] op_sel_hi:[1,0,0]
	v_pk_fma_f32 v[86:87], v[82:83], v[86:87], s[96:97] op_sel_hi:[1,1,0]
	v_pk_fma_f32 v[86:87], v[82:83], v[86:87], s[16:17] op_sel_hi:[1,1,0]
	v_pk_fma_f32 v[86:87], v[82:83], v[86:87], s[84:85] op_sel_hi:[1,1,0]
	v_pk_mul_f32 v[82:83], v[82:83], v[86:87]
	v_pk_mul_f32 v[86:87], v[88:89], s[18:19] op_sel_hi:[1,0]
	v_exp_f32_e32 v86, v86
	v_exp_f32_e32 v87, v87
	s_nop 0
	v_pk_mul_f32 v[82:83], v[86:87], v[82:83]
	v_pk_mul_f32 v[86:87], v[66:67], v[82:83]
	v_pk_fma_f32 v[82:83], v[66:67], v[82:83], v[66:67] neg_lo:[1,0,0] neg_hi:[1,0,0]
	v_cndmask_b32_e32 v66, v82, v86, vcc
	v_cmp_gt_f32_e32 vcc, 0, v67
	s_nop 1
	v_cndmask_b32_e32 v67, v83, v87, vcc

; __device__ __forceinline__ f32x4 gelu4(f32x4 v) { f32x2 a = gelu_pk((f32x2){v[0], v[1]}), b = gelu_pk((f32x2){v[2], v[3]}); return (f32x4){a.x, a.y, b.x, b.y}; }
; __device__ __forceinline__ f32x2 gelu_pk(f32x2 v) {
;     const f32x2 av = __builtin_elementwise_abs(v), d = av * 0.2316418882f + 1.0f;
;     f32x2 t; t.x = __builtin_amdgcn_rcpf(d.x); t.y = __builtin_amdgcn_rcpf(d.y);
;     f32x2 q = t * 0.5307027145f + (-0.7265760135f); q = q * t + 0.7107068705f; q = q * t + (-0.142248368f); q = q * t + 0.127414796f; q = q * t;
;     const f32x2 s = (v * v) * (-0.72134752044f);
;     f32x2 e; e.x = __builtin_amdgcn_exp2f(s.x); e.y = __builtin_amdgcn_exp2f(s.y);
;     const f32x2 m = v * (q * e), r = v - m;
;     f32x2 o; o.x = v.x < 0.f ? m.x : r.x; o.y = v.y < 0.f ? m.y : r.y; return o;
;     __device__ __forceinline__ void operator()(f32x4 (&acc)[2][2][4][2], const Unit& u, int wr, int wc, int fr_, int fq_) const {
;     ...
;             for (int m = 0; m < 4; ++m) { const int row = row0 + ai * HALF + m * 16; const float rs = rstd[row]; bf16_t* rowp = base + (size_t)row * ld + col0;
;                 float s1 = 0.f, s2 = 0.f;
; #pragma unroll
;                 for (int bj = 0; bj < 2; ++bj) { f32x4 v0 = acc[ai][bj][m][0] * rs, v1 = acc[ai][bj][m][1] * rs;
;                     if (act) { v0 = gelu4(v0); v1 = gelu4(v1); }
.LBB0_386:
	v_mov_b32_e32 v66, v248
	s_and_b64 vcc, exec, s[6:7]
	s_waitcnt lgkmcnt(0)
	v_pk_mul_f32 v[62:63], v[62:63], v[66:67] op_sel_hi:[1,0]
	v_pk_mul_f32 v[60:61], v[60:61], v[66:67] op_sel_hi:[1,0]
	v_pk_mul_f32 v[58:59], v[58:59], v[66:67] op_sel_hi:[1,0]
	v_pk_mul_f32 v[56:57], v[56:57], v[66:67] op_sel_hi:[1,0]
	s_cbranch_vccnz .LBB0_388
	v_and_b32_e32 v65, 0x7fffffff, v61
	v_and_b32_e32 v64, 0x7fffffff, v60
	v_pk_fma_f32 v[64:65], v[64:65], s[90:91], 1.0 op_sel_hi:[1,0,0]
	v_mov_b64_e32 v[68:69], s[94:95]
	v_rcp_f32_e32 v64, v64
	v_rcp_f32_e32 v65, v65
	v_pk_mul_f32 v[72:73], v[60:61], v[60:61]
	v_cmp_gt_f32_e32 vcc, 0, v60
	v_pk_mul_f32 v[72:73], v[72:73], s[18:19] op_sel_hi:[1,0]
	v_pk_fma_f32 v[70:71], v[64:65], s[92:93], v[68:69] op_sel_hi:[1,0,0]
	v_exp_f32_e32 v72, v72
	v_pk_fma_f32 v[70:71], v[64:65], v[70:71], s[96:97] op_sel_hi:[1,1,0]
	v_exp_f32_e32 v73, v73
	v_pk_fma_f32 v[70:71], v[64:65], v[70:71], s[16:17] op_sel_hi:[1,1,0]
	v_pk_fma_f32 v[70:71], v[64:65], v[70:71], s[84:85] op_sel_hi:[1,1,0]
	v_pk_mul_f32 v[64:65], v[64:65], v[70:71]
	v_pk_mul_f32 v[70:71], v[62:63], v[62:63]
	v_pk_mul_f32 v[64:65], v[72:73], v[64:65]
	v_pk_mul_f32 v[70:71], v[70:71], s[18:19] op_sel_hi:[1,0]
	v_pk_mul_f32 v[72:73], v[60:61], v[64:65]
	v_pk_fma_f32 v[64:65], v[60:61], v[64:65], v[60:61] neg_lo:[1,0,0] neg_hi:[1,0,0]
	v_exp_f32_e32 v70, v70
	v_cndmask_b32_e32 v60, v64, v72, vcc
	v_cmp_gt_f32_e32 vcc, 0, v61
	v_and_b32_e32 v64, 0x7fffffff, v62
	v_exp_f32_e32 v71, v71
	v_cndmask_b32_e32 v61, v65, v73, vcc
	v_and_b32_e32 v65, 0x7fffffff, v63
	v_pk_fma_f32 v[64:65], v[64:65], s[90:91], 1.0 op_sel_hi:[1,0,0]
	v_cmp_gt_f32_e32 vcc, 0, v62
	v_rcp_f32_e32 v64, v64
	v_rcp_f32_e32 v65, v65
	s_nop 0
	v_pk_fma_f32 v[72:73], v[64:65], s[92:93], v[68:69] op_sel_hi:[1,0,0]
	v_pk_fma_f32 v[72:73], v[64:65], v[72:73], s[96:97] op_sel_hi:[1,1,0]
	v_pk_fma_f32 v[72:73], v[64:65], v[72:73], s[16:17] op_sel_hi:[1,1,0]
	v_pk_fma_f32 v[72:73], v[64:65], v[72:73], s[84:85] op_sel_hi:[1,1,0]
	v_pk_mul_f32 v[64:65], v[64:65], v[72:73]
	v_pk_mul_f32 v[72:73], v[56:57], v[56:57]
	v_pk_mul_f32 v[64:65], v[70:71], v[64:65]
	v_pk_mul_f32 v[72:73], v[72:73], s[18:19] op_sel_hi:[1,0]
	v_pk_mul_f32 v[70:71], v[62:63], v[64:65]
	v_pk_fma_f32 v[64:65], v[62:63], v[64:65], v[62:63] neg_lo:[1,0,0] neg_hi:[1,0,0]
	v_exp_f32_e32 v72, v72
	v_cndmask_b32_e32 v62, v64, v70, vcc
	v_cmp_gt_f32_e32 vcc, 0, v63
	v_and_b32_e32 v64, 0x7fffffff, v56
	v_exp_f32_e32 v73, v73
	v_cndmask_b32_e32 v63, v65, v71, vcc
	v_and_b32_e32 v65, 0x7fffffff, v57
	v_pk_fma_f32 v[64:65], v[64:65], s[90:91], 1.0 op_sel_hi:[1,0,0]
	v_cmp_gt_f32_e32 vcc, 0, v56
	v_rcp_f32_e32 v64, v64
	v_rcp_f32_e32 v65, v65
	s_nop 0
	v_pk_fma_f32 v[70:71], v[64:65], s[92:93], v[68:69] op_sel_hi:[1,0,0]
	v_pk_fma_f32 v[70:71], v[64:65], v[70:71], s[96:97] op_sel_hi:[1,1,0]
	v_pk_fma_f32 v[70:71], v[64:65], v[70:71], s[16:17] op_sel_hi:[1,1,0]
	v_pk_fma_f32 v[70:71], v[64:65], v[70:71], s[84:85] op_sel_hi:[1,1,0]
	v_pk_mul_f32 v[64:65], v[64:65], v[70:71]
	v_pk_mul_f32 v[70:71], v[58:59], v[58:59]
	v_pk_mul_f32 v[64:65], v[72:73], v[64:65]
	v_pk_mul_f32 v[72:73], v[56:57], v[64:65]
	v_pk_fma_f32 v[64:65], v[56:57], v[64:65], v[56:57] neg_lo:[1,0,0] neg_hi:[1,0,0]
	v_cndmask_b32_e32 v56, v64, v72, vcc
	v_cmp_gt_f32_e32 vcc, 0, v57
	v_and_b32_e32 v64, 0x7fffffff, v58
	s_nop 0
	v_cndmask_b32_e32 v57, v65, v73, vcc
	v_and_b32_e32 v65, 0x7fffffff, v59
	v_pk_fma_f32 v[64:65], v[64:65], s[90:91], 1.0 op_sel_hi:[1,0,0]
	v_cmp_gt_f32_e32 vcc, 0, v58
	v_rcp_f32_e32 v64, v64
	v_rcp_f32_e32 v65, v65
	s_nop 0
	v_pk_fma_f32 v[68:69], v[64:65], s[92:93], v[68:69] op_sel_hi:[1,0,0]
	v_pk_fma_f32 v[68:69], v[64:65], v[68:69], s[96:97] op_sel_hi:[1,1,0]
	v_pk_fma_f32 v[68:69], v[64:65], v[68:69], s[16:17] op_sel_hi:[1,1,0]
	v_pk_fma_f32 v[68:69], v[64:65], v[68:69], s[84:85] op_sel_hi:[1,1,0]
	v_pk_mul_f32 v[64:65], v[64:65], v[68:69]
	v_pk_mul_f32 v[68:69], v[70:71], s[18:19] op_sel_hi:[1,0]
	v_exp_f32_e32 v68, v68
	v_exp_f32_e32 v69, v69
	s_nop 0
	v_pk_mul_f32 v[64:65], v[68:69], v[64:65]
	v_pk_mul_f32 v[68:69], v[58:59], v[64:65]
	v_pk_fma_f32 v[64:65], v[58:59], v[64:65], v[58:59] neg_lo:[1,0,0] neg_hi:[1,0,0]
	v_cndmask_b32_e32 v58, v64, v68, vcc
	v_cmp_gt_f32_e32 vcc, 0, v59
	s_nop 1
	v_cndmask_b32_e32 v59, v65, v69, vcc
; __device__ __forceinline__ u32x4 pack8(f32x4 v0, f32x4 v1) { u32x4 w; w.x = cvt_pk_bf16(v0[0], v0[1]); w.y = cvt_pk_bf16(v0[2], v0[3]); w.z = cvt_pk_bf16(v1[0], v1[1]); w.w = cvt_pk_bf16(v1[2], v1[3]); return w; }
; __device__ __forceinline__ f32x4 gelu4(f32x4 v) { f32x2 a = gelu_pk((f32x2){v[0], v[1]}), b = gelu_pk((f32x2){v[2], v[3]}); return (f32x4){a.x, a.y, b.x, b.y}; }
; __device__ __forceinline__ f32x2 gelu_pk(f32x2 v) {
;     const f32x2 av = __builtin_elementwise_abs(v), d = av * 0.2316418882f + 1.0f;
;     f32x2 t; t.x = __builtin_amdgcn_rcpf(d.x); t.y = __builtin_amdgcn_rcpf(d.y);
;     f32x2 q = t * 0.5307027145f + (-0.7265760135f); q = q * t + 0.7107068705f; q = q * t + (-0.142248368f); q = q * t + 0.127414796f; q = q * t;
;     const f32x2 s = (v * v) * (-0.72134752044f);
;     f32x2 e; e.x = __builtin_amdgcn_exp2f(s.x); e.y = __builtin_amdgcn_exp2f(s.y);
;     const f32x2 m = v * (q * e), r = v - m;
;     f32x2 o; o.x = v.x < 0.f ? m.x : r.x; o.y = v.y < 0.f ? m.y : r.y; return o;
;     __device__ __forceinline__ void operator()(f32x4 (&acc)[2][2][4][2], const Unit& u, int wr, int wc, int fr_, int fq_) const {
;     ...
;                 for (int bj = 0; bj < 2; ++bj) { f32x4 v0 = acc[ai][bj][m][0] * rs, v1 = acc[ai][bj][m][1] * rs;
;                     if (act) { v0 = gelu4(v0); v1 = gelu4(v1); }
;                     s1 += ((v0[0] + v0[1]) + (v0[2] + v0[3])) + ((v1[0] + v1[1]) + (v1[2] + v1[3]));
;                     s2 += ((v0[0] * v0[0] + v0[1] * v0[1]) + (v0[2] * v0[2] + v0[3] * v0[3])) + ((v1[0] * v1[0] + v1[1] * v1[1]) + (v1[2] * v1[2] + v1[3] * v1[3]));
;                     *(u32x4*)(rowp + bj * HALF) = pack8(v0, v1); }
.LBB0_388:
	v_add_u32_e32 v64, 0x80, v146
	v_ashrrev_i32_e32 v65, 31, v64
	v_mul_lo_u32 v70, s86, v65
	v_mul_lo_u32 v71, s87, v64
	v_mad_u64_u32 v[68:69], s[14:15], s86, v64, 0
	v_add3_u32 v69, v69, v70, v71
	v_lshl_add_u64 v[68:69], v[68:69], 1, v[120:121]
	v_cvt_pk_bf16_f32 v70, v60, v61
	v_cvt_pk_bf16_f32 v71, v62, v63
	v_cvt_pk_bf16_f32 v72, v56, v57
	v_cvt_pk_bf16_f32 v73, v58, v59
	v_mov_b32_e32 v67, v66
	global_store_dwordx4 v[68:69], v[70:73], off
	v_pk_mul_f32 v[52:53], v[52:53], v[66:67]
	s_and_b64 vcc, exec, s[6:7]
	v_mov_b32_e32 v70, v66
	v_mov_b32_e32 v71, v66
	v_pk_mul_f32 v[54:55], v[54:55], v[70:71]
	v_pk_mul_f32 v[50:51], v[50:51], v[70:71]
	v_pk_mul_f32 v[48:49], v[48:49], v[66:67]
	s_cbranch_vccnz .LBB0_390
	v_and_b32_e32 v67, 0x7fffffff, v53
	v_and_b32_e32 v66, 0x7fffffff, v52
	v_pk_fma_f32 v[66:67], v[66:67], s[90:91], 1.0 op_sel_hi:[1,0,0]
	v_mov_b64_e32 v[70:71], s[94:95]
	v_rcp_f32_e32 v66, v66
	v_rcp_f32_e32 v67, v67
	v_pk_mul_f32 v[74:75], v[52:53], v[52:53]
	v_cmp_gt_f32_e32 vcc, 0, v52
	v_pk_mul_f32 v[74:75], v[74:75], s[18:19] op_sel_hi:[1,0]
	v_pk_fma_f32 v[72:73], v[66:67], s[92:93], v[70:71] op_sel_hi:[1,0,0]
	v_exp_f32_e32 v74, v74
	v_pk_fma_f32 v[72:73], v[66:67], v[72:73], s[96:97] op_sel_hi:[1,1,0]
	v_exp_f32_e32 v75, v75
	v_pk_fma_f32 v[72:73], v[66:67], v[72:73], s[16:17] op_sel_hi:[1,1,0]
	v_pk_fma_f32 v[72:73], v[66:67], v[72:73], s[84:85] op_sel_hi:[1,1,0]
	v_pk_mul_f32 v[66:67], v[66:67], v[72:73]
	v_pk_mul_f32 v[72:73], v[54:55], v[54:55]
	v_pk_mul_f32 v[66:67], v[74:75], v[66:67]
	v_pk_mul_f32 v[72:73], v[72:73], s[18:19] op_sel_hi:[1,0]
	v_pk_mul_f32 v[74:75], v[52:53], v[66:67]
	v_pk_fma_f32 v[66:67], v[52:53], v[66:67], v[52:53] neg_lo:[1,0,0] neg_hi:[1,0,0]
	v_exp_f32_e32 v72, v72
	v_cndmask_b32_e32 v52, v66, v74, vcc
	v_cmp_gt_f32_e32 vcc, 0, v53
	v_and_b32_e32 v66, 0x7fffffff, v54
	v_exp_f32_e32 v73, v73
	v_cndmask_b32_e32 v53, v67, v75, vcc
	v_and_b32_e32 v67, 0x7fffffff, v55
	v_pk_fma_f32 v[66:67], v[66:67], s[90:91], 1.0 op_sel_hi:[1,0,0]
	v_cmp_gt_f32_e32 vcc, 0, v54
	v_rcp_f32_e32 v66, v66
	v_rcp_f32_e32 v67, v67
	s_nop 0
	v_pk_fma_f32 v[74:75], v[66:67], s[92:93], v[70:71] op_sel_hi:[1,0,0]
	v_pk_fma_f32 v[74:75], v[66:67], v[74:75], s[96:97] op_sel_hi:[1,1,0]
	v_pk_fma_f32 v[74:75], v[66:67], v[74:75], s[16:17] op_sel_hi:[1,1,0]
	v_pk_fma_f32 v[74:75], v[66:67], v[74:75], s[84:85] op_sel_hi:[1,1,0]
	v_pk_mul_f32 v[66:67], v[66:67], v[74:75]
	v_pk_mul_f32 v[74:75], v[48:49], v[48:49]
	v_pk_mul_f32 v[66:67], v[72:73], v[66:67]
	v_pk_mul_f32 v[74:75], v[74:75], s[18:19] op_sel_hi:[1,0]
	v_pk_mul_f32 v[72:73], v[54:55], v[66:67]
	v_pk_fma_f32 v[66:67], v[54:55], v[66:67], v[54:55] neg_lo:[1,0,0] neg_hi:[1,0,0]
	v_exp_f32_e32 v74, v74
	v_cndmask_b32_e32 v54, v66, v72, vcc
	v_cmp_gt_f32_e32 vcc, 0, v55
	v_and_b32_e32 v66, 0x7fffffff, v48
	v_exp_f32_e32 v75, v75
	v_cndmask_b32_e32 v55, v67, v73, vcc
	v_and_b32_e32 v67, 0x7fffffff, v49
	v_pk_fma_f32 v[66:67], v[66:67], s[90:91], 1.0 op_sel_hi:[1,0,0]
	v_cmp_gt_f32_e32 vcc, 0, v48
	v_rcp_f32_e32 v66, v66
	v_rcp_f32_e32 v67, v67
	s_nop 0
	v_pk_fma_f32 v[72:73], v[66:67], s[92:93], v[70:71] op_sel_hi:[1,0,0]
	v_pk_fma_f32 v[72:73], v[66:67], v[72:73], s[96:97] op_sel_hi:[1,1,0]
	v_pk_fma_f32 v[72:73], v[66:67], v[72:73], s[16:17] op_sel_hi:[1,1,0]
	v_pk_fma_f32 v[72:73], v[66:67], v[72:73], s[84:85] op_sel_hi:[1,1,0]
	v_pk_mul_f32 v[66:67], v[66:67], v[72:73]
	v_pk_mul_f32 v[72:73], v[50:51], v[50:51]
	v_pk_mul_f32 v[66:67], v[74:75], v[66:67]
	v_pk_mul_f32 v[74:75], v[48:49], v[66:67]
	v_pk_fma_f32 v[66:67], v[48:49], v[66:67], v[48:49] neg_lo:[1,0,0] neg_hi:[1,0,0]
	v_cndmask_b32_e32 v48, v66, v74, vcc
	v_cmp_gt_f32_e32 vcc, 0, v49
	v_and_b32_e32 v66, 0x7fffffff, v50
	s_nop 0
	v_cndmask_b32_e32 v49, v67, v75, vcc
	v_and_b32_e32 v67, 0x7fffffff, v51
	v_pk_fma_f32 v[66:67], v[66:67], s[90:91], 1.0 op_sel_hi:[1,0,0]
	v_cmp_gt_f32_e32 vcc, 0, v50
	v_rcp_f32_e32 v66, v66
	v_rcp_f32_e32 v67, v67
	s_nop 0
	v_pk_fma_f32 v[70:71], v[66:67], s[92:93], v[70:71] op_sel_hi:[1,0,0]
	v_pk_fma_f32 v[70:71], v[66:67], v[70:71], s[96:97] op_sel_hi:[1,1,0]
	v_pk_fma_f32 v[70:71], v[66:67], v[70:71], s[16:17] op_sel_hi:[1,1,0]
	v_pk_fma_f32 v[70:71], v[66:67], v[70:71], s[84:85] op_sel_hi:[1,1,0]
	v_pk_mul_f32 v[66:67], v[66:67], v[70:71]
	v_pk_mul_f32 v[70:71], v[72:73], s[18:19] op_sel_hi:[1,0]
	v_exp_f32_e32 v70, v70
	v_exp_f32_e32 v71, v71
	s_nop 0
	v_pk_mul_f32 v[66:67], v[70:71], v[66:67]
	v_pk_mul_f32 v[70:71], v[50:51], v[66:67]
	v_pk_fma_f32 v[66:67], v[50:51], v[66:67], v[50:51] neg_lo:[1,0,0] neg_hi:[1,0,0]
	v_cndmask_b32_e32 v50, v66, v70, vcc
	v_cmp_gt_f32_e32 vcc, 0, v51
	s_nop 1
	v_cndmask_b32_e32 v51, v67, v71, vcc

; __device__ __forceinline__ f32x4 gelu4(f32x4 v) { f32x2 a = gelu_pk((f32x2){v[0], v[1]}), b = gelu_pk((f32x2){v[2], v[3]}); return (f32x4){a.x, a.y, b.x, b.y}; }
; __device__ __forceinline__ f32x2 gelu_pk(f32x2 v) {
;     const f32x2 av = __builtin_elementwise_abs(v), d = av * 0.2316418882f + 1.0f;
;     f32x2 t; t.x = __builtin_amdgcn_rcpf(d.x); t.y = __builtin_amdgcn_rcpf(d.y);
;     f32x2 q = t * 0.5307027145f + (-0.7265760135f); q = q * t + 0.7107068705f; q = q * t + (-0.142248368f); q = q * t + 0.127414796f; q = q * t;
;     const f32x2 s = (v * v) * (-0.72134752044f);
;     f32x2 e; e.x = __builtin_amdgcn_exp2f(s.x); e.y = __builtin_amdgcn_exp2f(s.y);
;     const f32x2 m = v * (q * e), r = v - m;
;     f32x2 o; o.x = v.x < 0.f ? m.x : r.x; o.y = v.y < 0.f ? m.y : r.y; return o;
;     __device__ __forceinline__ void operator()(f32x4 (&acc)[2][2][4][2], const Unit& u, int wr, int wc, int fr_, int fq_) const {
;     ...
;             for (int m = 0; m < 4; ++m) { const int row = row0 + ai * HALF + m * 16; const float rs = rstd[row]; bf16_t* rowp = base + (size_t)row * ld + col0;
;                 float s1 = 0.f, s2 = 0.f;
; #pragma unroll
;                 for (int bj = 0; bj < 2; ++bj) { f32x4 v0 = acc[ai][bj][m][0] * rs, v1 = acc[ai][bj][m][1] * rs;
;                     if (act) { v0 = gelu4(v0); v1 = gelu4(v1); }
.LBB0_394:
	v_mov_b32_e32 v50, v249
	s_and_b64 vcc, exec, s[6:7]
	s_waitcnt lgkmcnt(0)
	v_pk_mul_f32 v[46:47], v[46:47], v[50:51] op_sel_hi:[1,0]
	v_pk_mul_f32 v[44:45], v[44:45], v[50:51] op_sel_hi:[1,0]
	v_pk_mul_f32 v[42:43], v[42:43], v[50:51] op_sel_hi:[1,0]
	v_pk_mul_f32 v[40:41], v[40:41], v[50:51] op_sel_hi:[1,0]
	s_cbranch_vccnz .LBB0_396
	v_and_b32_e32 v49, 0x7fffffff, v45
	v_and_b32_e32 v48, 0x7fffffff, v44
	v_pk_fma_f32 v[48:49], v[48:49], s[90:91], 1.0 op_sel_hi:[1,0,0]
	v_mov_b64_e32 v[52:53], s[94:95]
	v_rcp_f32_e32 v48, v48
	v_rcp_f32_e32 v49, v49
	v_pk_mul_f32 v[56:57], v[44:45], v[44:45]
	v_cmp_gt_f32_e32 vcc, 0, v44
	v_pk_mul_f32 v[56:57], v[56:57], s[18:19] op_sel_hi:[1,0]
	v_pk_fma_f32 v[54:55], v[48:49], s[92:93], v[52:53] op_sel_hi:[1,0,0]
	v_exp_f32_e32 v56, v56
	v_pk_fma_f32 v[54:55], v[48:49], v[54:55], s[96:97] op_sel_hi:[1,1,0]
	v_exp_f32_e32 v57, v57
	v_pk_fma_f32 v[54:55], v[48:49], v[54:55], s[16:17] op_sel_hi:[1,1,0]
	v_pk_fma_f32 v[54:55], v[48:49], v[54:55], s[84:85] op_sel_hi:[1,1,0]
	v_pk_mul_f32 v[48:49], v[48:49], v[54:55]
	v_pk_mul_f32 v[54:55], v[46:47], v[46:47]
	v_pk_mul_f32 v[48:49], v[56:57], v[48:49]
	v_pk_mul_f32 v[54:55], v[54:55], s[18:19] op_sel_hi:[1,0]
	v_pk_mul_f32 v[56:57], v[44:45], v[48:49]
	v_pk_fma_f32 v[48:49], v[44:45], v[48:49], v[44:45] neg_lo:[1,0,0] neg_hi:[1,0,0]
	v_exp_f32_e32 v54, v54
	v_cndmask_b32_e32 v44, v48, v56, vcc
	v_cmp_gt_f32_e32 vcc, 0, v45
	v_and_b32_e32 v48, 0x7fffffff, v46
	v_exp_f32_e32 v55, v55
	v_cndmask_b32_e32 v45, v49, v57, vcc
	v_and_b32_e32 v49, 0x7fffffff, v47
	v_pk_fma_f32 v[48:49], v[48:49], s[90:91], 1.0 op_sel_hi:[1,0,0]
	v_cmp_gt_f32_e32 vcc, 0, v46
	v_rcp_f32_e32 v48, v48
	v_rcp_f32_e32 v49, v49
	s_nop 0
	v_pk_fma_f32 v[56:57], v[48:49], s[92:93], v[52:53] op_sel_hi:[1,0,0]
	v_pk_fma_f32 v[56:57], v[48:49], v[56:57], s[96:97] op_sel_hi:[1,1,0]
	v_pk_fma_f32 v[56:57], v[48:49], v[56:57], s[16:17] op_sel_hi:[1,1,0]
	v_pk_fma_f32 v[56:57], v[48:49], v[56:57], s[84:85] op_sel_hi:[1,1,0]
	v_pk_mul_f32 v[48:49], v[48:49], v[56:57]
	v_pk_mul_f32 v[56:57], v[40:41], v[40:41]
	v_pk_mul_f32 v[48:49], v[54:55], v[48:49]
	v_pk_mul_f32 v[56:57], v[56:57], s[18:19] op_sel_hi:[1,0]
	v_pk_mul_f32 v[54:55], v[46:47], v[48:49]
	v_pk_fma_f32 v[48:49], v[46:47], v[48:49], v[46:47] neg_lo:[1,0,0] neg_hi:[1,0,0]
	v_exp_f32_e32 v56, v56
	v_cndmask_b32_e32 v46, v48, v54, vcc
	v_cmp_gt_f32_e32 vcc, 0, v47
	v_and_b32_e32 v48, 0x7fffffff, v40
	v_exp_f32_e32 v57, v57
	v_cndmask_b32_e32 v47, v49, v55, vcc
	v_and_b32_e32 v49, 0x7fffffff, v41
	v_pk_fma_f32 v[48:49], v[48:49], s[90:91], 1.0 op_sel_hi:[1,0,0]
	v_cmp_gt_f32_e32 vcc, 0, v40
	v_rcp_f32_e32 v48, v48
	v_rcp_f32_e32 v49, v49
	s_nop 0
	v_pk_fma_f32 v[54:55], v[48:49], s[92:93], v[52:53] op_sel_hi:[1,0,0]
	v_pk_fma_f32 v[54:55], v[48:49], v[54:55], s[96:97] op_sel_hi:[1,1,0]
	v_pk_fma_f32 v[54:55], v[48:49], v[54:55], s[16:17] op_sel_hi:[1,1,0]
	v_pk_fma_f32 v[54:55], v[48:49], v[54:55], s[84:85] op_sel_hi:[1,1,0]
	v_pk_mul_f32 v[48:49], v[48:49], v[54:55]
	v_pk_mul_f32 v[54:55], v[42:43], v[42:43]
	v_pk_mul_f32 v[48:49], v[56:57], v[48:49]
	v_pk_mul_f32 v[56:57], v[40:41], v[48:49]
	v_pk_fma_f32 v[48:49], v[40:41], v[48:49], v[40:41] neg_lo:[1,0,0] neg_hi:[1,0,0]
	v_cndmask_b32_e32 v40, v48, v56, vcc
	v_cmp_gt_f32_e32 vcc, 0, v41
	v_and_b32_e32 v48, 0x7fffffff, v42
	s_nop 0
	v_cndmask_b32_e32 v41, v49, v57, vcc
	v_and_b32_e32 v49, 0x7fffffff, v43
	v_pk_fma_f32 v[48:49], v[48:49], s[90:91], 1.0 op_sel_hi:[1,0,0]
	v_cmp_gt_f32_e32 vcc, 0, v42
	v_rcp_f32_e32 v48, v48
	v_rcp_f32_e32 v49, v49
	s_nop 0
	v_pk_fma_f32 v[52:53], v[48:49], s[92:93], v[52:53] op_sel_hi:[1,0,0]
	v_pk_fma_f32 v[52:53], v[48:49], v[52:53], s[96:97] op_sel_hi:[1,1,0]
	v_pk_fma_f32 v[52:53], v[48:49], v[52:53], s[16:17] op_sel_hi:[1,1,0]
	v_pk_fma_f32 v[52:53], v[48:49], v[52:53], s[84:85] op_sel_hi:[1,1,0]
	v_pk_mul_f32 v[48:49], v[48:49], v[52:53]
	v_pk_mul_f32 v[52:53], v[54:55], s[18:19] op_sel_hi:[1,0]
	v_exp_f32_e32 v52, v52
	v_exp_f32_e32 v53, v53
	s_nop 0
	v_pk_mul_f32 v[48:49], v[52:53], v[48:49]
	v_pk_mul_f32 v[52:53], v[42:43], v[48:49]
	v_pk_fma_f32 v[48:49], v[42:43], v[48:49], v[42:43] neg_lo:[1,0,0] neg_hi:[1,0,0]
	v_cndmask_b32_e32 v42, v48, v52, vcc
	v_cmp_gt_f32_e32 vcc, 0, v43
	s_nop 1
	v_cndmask_b32_e32 v43, v49, v53, vcc
; __device__ __forceinline__ u32x4 pack8(f32x4 v0, f32x4 v1) { u32x4 w; w.x = cvt_pk_bf16(v0[0], v0[1]); w.y = cvt_pk_bf16(v0[2], v0[3]); w.z = cvt_pk_bf16(v1[0], v1[1]); w.w = cvt_pk_bf16(v1[2], v1[3]); return w; }
; __device__ __forceinline__ f32x4 gelu4(f32x4 v) { f32x2 a = gelu_pk((f32x2){v[0], v[1]}), b = gelu_pk((f32x2){v[2], v[3]}); return (f32x4){a.x, a.y, b.x, b.y}; }
; __device__ __forceinline__ f32x2 gelu_pk(f32x2 v) {
;     const f32x2 av = __builtin_elementwise_abs(v), d = av * 0.2316418882f + 1.0f;
;     f32x2 t; t.x = __builtin_amdgcn_rcpf(d.x); t.y = __builtin_amdgcn_rcpf(d.y);
;     f32x2 q = t * 0.5307027145f + (-0.7265760135f); q = q * t + 0.7107068705f; q = q * t + (-0.142248368f); q = q * t + 0.127414796f; q = q * t;
;     const f32x2 s = (v * v) * (-0.72134752044f);
;     f32x2 e; e.x = __builtin_amdgcn_exp2f(s.x); e.y = __builtin_amdgcn_exp2f(s.y);
;     const f32x2 m = v * (q * e), r = v - m;
;     f32x2 o; o.x = v.x < 0.f ? m.x : r.x; o.y = v.y < 0.f ? m.y : r.y; return o;
;     __device__ __forceinline__ void operator()(f32x4 (&acc)[2][2][4][2], const Unit& u, int wr, int wc, int fr_, int fq_) const {
;     ...
;                 for (int bj = 0; bj < 2; ++bj) { f32x4 v0 = acc[ai][bj][m][0] * rs, v1 = acc[ai][bj][m][1] * rs;
;                     if (act) { v0 = gelu4(v0); v1 = gelu4(v1); }
;                     s1 += ((v0[0] + v0[1]) + (v0[2] + v0[3])) + ((v1[0] + v1[1]) + (v1[2] + v1[3]));
;                     s2 += ((v0[0] * v0[0] + v0[1] * v0[1]) + (v0[2] * v0[2] + v0[3] * v0[3])) + ((v1[0] * v1[0] + v1[1] * v1[1]) + (v1[2] * v1[2] + v1[3] * v1[3]));
;                     *(u32x4*)(rowp + bj * HALF) = pack8(v0, v1); }
.LBB0_396:
	v_add_u32_e32 v48, 0x90, v146
	v_ashrrev_i32_e32 v49, 31, v48
	v_mul_lo_u32 v54, s86, v49
	v_mul_lo_u32 v55, s87, v48
	v_mad_u64_u32 v[52:53], s[14:15], s86, v48, 0
	v_add3_u32 v53, v53, v54, v55
	v_lshl_add_u64 v[52:53], v[52:53], 1, v[120:121]
	v_cvt_pk_bf16_f32 v54, v44, v45
	v_cvt_pk_bf16_f32 v55, v46, v47
	v_cvt_pk_bf16_f32 v56, v40, v41
	v_cvt_pk_bf16_f32 v57, v42, v43
	v_mov_b32_e32 v51, v50
	global_store_dwordx4 v[52:53], v[54:57], off
	v_pk_mul_f32 v[36:37], v[36:37], v[50:51]
	s_and_b64 vcc, exec, s[6:7]
	v_mov_b32_e32 v54, v50
	v_mov_b32_e32 v55, v50
	v_pk_mul_f32 v[38:39], v[38:39], v[54:55]
	v_pk_mul_f32 v[34:35], v[34:35], v[54:55]
	v_pk_mul_f32 v[32:33], v[32:33], v[50:51]
	s_cbranch_vccnz .LBB0_398
	v_and_b32_e32 v51, 0x7fffffff, v37
	v_and_b32_e32 v50, 0x7fffffff, v36
	v_pk_fma_f32 v[50:51], v[50:51], s[90:91], 1.0 op_sel_hi:[1,0,0]
	v_mov_b64_e32 v[54:55], s[94:95]
	v_rcp_f32_e32 v50, v50
	v_rcp_f32_e32 v51, v51
	v_pk_mul_f32 v[58:59], v[36:37], v[36:37]
	v_cmp_gt_f32_e32 vcc, 0, v36
	v_pk_mul_f32 v[58:59], v[58:59], s[18:19] op_sel_hi:[1,0]
	v_pk_fma_f32 v[56:57], v[50:51], s[92:93], v[54:55] op_sel_hi:[1,0,0]
	v_exp_f32_e32 v58, v58
	v_pk_fma_f32 v[56:57], v[50:51], v[56:57], s[96:97] op_sel_hi:[1,1,0]
	v_exp_f32_e32 v59, v59
	v_pk_fma_f32 v[56:57], v[50:51], v[56:57], s[16:17] op_sel_hi:[1,1,0]
	v_pk_fma_f32 v[56:57], v[50:51], v[56:57], s[84:85] op_sel_hi:[1,1,0]
	v_pk_mul_f32 v[50:51], v[50:51], v[56:57]
	v_pk_mul_f32 v[56:57], v[38:39], v[38:39]
	v_pk_mul_f32 v[50:51], v[58:59], v[50:51]
	v_pk_mul_f32 v[56:57], v[56:57], s[18:19] op_sel_hi:[1,0]
	v_pk_mul_f32 v[58:59], v[36:37], v[50:51]
	v_pk_fma_f32 v[50:51], v[36:37], v[50:51], v[36:37] neg_lo:[1,0,0] neg_hi:[1,0,0]
	v_exp_f32_e32 v56, v56
	v_cndmask_b32_e32 v36, v50, v58, vcc
	v_cmp_gt_f32_e32 vcc, 0, v37
	v_and_b32_e32 v50, 0x7fffffff, v38
	v_exp_f32_e32 v57, v57
	v_cndmask_b32_e32 v37, v51, v59, vcc
	v_and_b32_e32 v51, 0x7fffffff, v39
	v_pk_fma_f32 v[50:51], v[50:51], s[90:91], 1.0 op_sel_hi:[1,0,0]
	v_cmp_gt_f32_e32 vcc, 0, v38
	v_rcp_f32_e32 v50, v50
	v_rcp_f32_e32 v51, v51
	s_nop 0
	v_pk_fma_f32 v[58:59], v[50:51], s[92:93], v[54:55] op_sel_hi:[1,0,0]
	v_pk_fma_f32 v[58:59], v[50:51], v[58:59], s[96:97] op_sel_hi:[1,1,0]
	v_pk_fma_f32 v[58:59], v[50:51], v[58:59], s[16:17] op_sel_hi:[1,1,0]
	v_pk_fma_f32 v[58:59], v[50:51], v[58:59], s[84:85] op_sel_hi:[1,1,0]
	v_pk_mul_f32 v[50:51], v[50:51], v[58:59]
	v_pk_mul_f32 v[58:59], v[32:33], v[32:33]
	v_pk_mul_f32 v[50:51], v[56:57], v[50:51]
	v_pk_mul_f32 v[58:59], v[58:59], s[18:19] op_sel_hi:[1,0]
	v_pk_mul_f32 v[56:57], v[38:39], v[50:51]
	v_pk_fma_f32 v[50:51], v[38:39], v[50:51], v[38:39] neg_lo:[1,0,0] neg_hi:[1,0,0]
	v_exp_f32_e32 v58, v58
	v_cndmask_b32_e32 v38, v50, v56, vcc
	v_cmp_gt_f32_e32 vcc, 0, v39
	v_and_b32_e32 v50, 0x7fffffff, v32
	v_exp_f32_e32 v59, v59
	v_cndmask_b32_e32 v39, v51, v57, vcc
	v_and_b32_e32 v51, 0x7fffffff, v33
	v_pk_fma_f32 v[50:51], v[50:51], s[90:91], 1.0 op_sel_hi:[1,0,0]
	v_cmp_gt_f32_e32 vcc, 0, v32
	v_rcp_f32_e32 v50, v50
	v_rcp_f32_e32 v51, v51
	s_nop 0
	v_pk_fma_f32 v[56:57], v[50:51], s[92:93], v[54:55] op_sel_hi:[1,0,0]
	v_pk_fma_f32 v[56:57], v[50:51], v[56:57], s[96:97] op_sel_hi:[1,1,0]
	v_pk_fma_f32 v[56:57], v[50:51], v[56:57], s[16:17] op_sel_hi:[1,1,0]
	v_pk_fma_f32 v[56:57], v[50:51], v[56:57], s[84:85] op_sel_hi:[1,1,0]
	v_pk_mul_f32 v[50:51], v[50:51], v[56:57]
	v_pk_mul_f32 v[56:57], v[34:35], v[34:35]
	v_pk_mul_f32 v[50:51], v[58:59], v[50:51]
	v_pk_mul_f32 v[58:59], v[32:33], v[50:51]
	v_pk_fma_f32 v[50:51], v[32:33], v[50:51], v[32:33] neg_lo:[1,0,0] neg_hi:[1,0,0]
	v_cndmask_b32_e32 v32, v50, v58, vcc
	v_cmp_gt_f32_e32 vcc, 0, v33
	v_and_b32_e32 v50, 0x7fffffff, v34
	s_nop 0
	v_cndmask_b32_e32 v33, v51, v59, vcc
	v_and_b32_e32 v51, 0x7fffffff, v35
	v_pk_fma_f32 v[50:51], v[50:51], s[90:91], 1.0 op_sel_hi:[1,0,0]
	v_cmp_gt_f32_e32 vcc, 0, v34
	v_rcp_f32_e32 v50, v50
	v_rcp_f32_e32 v51, v51
	s_nop 0
	v_pk_fma_f32 v[54:55], v[50:51], s[92:93], v[54:55] op_sel_hi:[1,0,0]
	v_pk_fma_f32 v[54:55], v[50:51], v[54:55], s[96:97] op_sel_hi:[1,1,0]
	v_pk_fma_f32 v[54:55], v[50:51], v[54:55], s[16:17] op_sel_hi:[1,1,0]
	v_pk_fma_f32 v[54:55], v[50:51], v[54:55], s[84:85] op_sel_hi:[1,1,0]
	v_pk_mul_f32 v[50:51], v[50:51], v[54:55]
	v_pk_mul_f32 v[54:55], v[56:57], s[18:19] op_sel_hi:[1,0]
	v_exp_f32_e32 v54, v54
	v_exp_f32_e32 v55, v55
	s_nop 0
	v_pk_mul_f32 v[50:51], v[54:55], v[50:51]
	v_pk_mul_f32 v[54:55], v[34:35], v[50:51]
	v_pk_fma_f32 v[50:51], v[34:35], v[50:51], v[34:35] neg_lo:[1,0,0] neg_hi:[1,0,0]
	v_cndmask_b32_e32 v34, v50, v54, vcc
	v_cmp_gt_f32_e32 vcc, 0, v35
	s_nop 1
	v_cndmask_b32_e32 v35, v51, v55, vcc

; __device__ __forceinline__ f32x4 gelu4(f32x4 v) { f32x2 a = gelu_pk((f32x2){v[0], v[1]}), b = gelu_pk((f32x2){v[2], v[3]}); return (f32x4){a.x, a.y, b.x, b.y}; }
; __device__ __forceinline__ f32x2 gelu_pk(f32x2 v) {
;     const f32x2 av = __builtin_elementwise_abs(v), d = av * 0.2316418882f + 1.0f;
;     f32x2 t; t.x = __builtin_amdgcn_rcpf(d.x); t.y = __builtin_amdgcn_rcpf(d.y);
;     f32x2 q = t * 0.5307027145f + (-0.7265760135f); q = q * t + 0.7107068705f; q = q * t + (-0.142248368f); q = q * t + 0.127414796f; q = q * t;
;     const f32x2 s = (v * v) * (-0.72134752044f);
;     f32x2 e; e.x = __builtin_amdgcn_exp2f(s.x); e.y = __builtin_amdgcn_exp2f(s.y);
;     const f32x2 m = v * (q * e), r = v - m;
;     f32x2 o; o.x = v.x < 0.f ? m.x : r.x; o.y = v.y < 0.f ? m.y : r.y; return o;
;     __device__ __forceinline__ void operator()(f32x4 (&acc)[2][2][4][2], const Unit& u, int wr, int wc, int fr_, int fq_) const {
;     ...
;             for (int m = 0; m < 4; ++m) { const int row = row0 + ai * HALF + m * 16; const float rs = rstd[row]; bf16_t* rowp = base + (size_t)row * ld + col0;
;                 float s1 = 0.f, s2 = 0.f;
; #pragma unroll
;                 for (int bj = 0; bj < 2; ++bj) { f32x4 v0 = acc[ai][bj][m][0] * rs, v1 = acc[ai][bj][m][1] * rs;
;                     if (act) { v0 = gelu4(v0); v1 = gelu4(v1); }
.LBB0_402:
	v_mov_b32_e32 v34, v250
	s_and_b64 vcc, exec, s[6:7]
	s_waitcnt lgkmcnt(0)
	v_pk_mul_f32 v[30:31], v[30:31], v[34:35] op_sel_hi:[1,0]
	v_pk_mul_f32 v[28:29], v[28:29], v[34:35] op_sel_hi:[1,0]
	v_pk_mul_f32 v[26:27], v[26:27], v[34:35] op_sel_hi:[1,0]
	v_pk_mul_f32 v[24:25], v[24:25], v[34:35] op_sel_hi:[1,0]
	s_cbranch_vccnz .LBB0_404
	v_and_b32_e32 v33, 0x7fffffff, v29
	v_and_b32_e32 v32, 0x7fffffff, v28
	v_pk_fma_f32 v[32:33], v[32:33], s[90:91], 1.0 op_sel_hi:[1,0,0]
	v_mov_b64_e32 v[36:37], s[94:95]
	v_rcp_f32_e32 v32, v32
	v_rcp_f32_e32 v33, v33
	v_pk_mul_f32 v[40:41], v[28:29], v[28:29]
	v_cmp_gt_f32_e32 vcc, 0, v28
	v_pk_mul_f32 v[40:41], v[40:41], s[18:19] op_sel_hi:[1,0]
	v_pk_fma_f32 v[38:39], v[32:33], s[92:93], v[36:37] op_sel_hi:[1,0,0]
	v_exp_f32_e32 v40, v40
	v_pk_fma_f32 v[38:39], v[32:33], v[38:39], s[96:97] op_sel_hi:[1,1,0]
	v_exp_f32_e32 v41, v41
	v_pk_fma_f32 v[38:39], v[32:33], v[38:39], s[16:17] op_sel_hi:[1,1,0]
	v_pk_fma_f32 v[38:39], v[32:33], v[38:39], s[84:85] op_sel_hi:[1,1,0]
	v_pk_mul_f32 v[32:33], v[32:33], v[38:39]
	v_pk_mul_f32 v[38:39], v[30:31], v[30:31]
	v_pk_mul_f32 v[32:33], v[40:41], v[32:33]
	v_pk_mul_f32 v[38:39], v[38:39], s[18:19] op_sel_hi:[1,0]
	v_pk_mul_f32 v[40:41], v[28:29], v[32:33]
	v_pk_fma_f32 v[32:33], v[28:29], v[32:33], v[28:29] neg_lo:[1,0,0] neg_hi:[1,0,0]
	v_exp_f32_e32 v38, v38
	v_cndmask_b32_e32 v28, v32, v40, vcc
	v_cmp_gt_f32_e32 vcc, 0, v29
	v_and_b32_e32 v32, 0x7fffffff, v30
	v_exp_f32_e32 v39, v39
	v_cndmask_b32_e32 v29, v33, v41, vcc
	v_and_b32_e32 v33, 0x7fffffff, v31
	v_pk_fma_f32 v[32:33], v[32:33], s[90:91], 1.0 op_sel_hi:[1,0,0]
	v_cmp_gt_f32_e32 vcc, 0, v30
	v_rcp_f32_e32 v32, v32
	v_rcp_f32_e32 v33, v33
	s_nop 0
	v_pk_fma_f32 v[40:41], v[32:33], s[92:93], v[36:37] op_sel_hi:[1,0,0]
	v_pk_fma_f32 v[40:41], v[32:33], v[40:41], s[96:97] op_sel_hi:[1,1,0]
	v_pk_fma_f32 v[40:41], v[32:33], v[40:41], s[16:17] op_sel_hi:[1,1,0]
	v_pk_fma_f32 v[40:41], v[32:33], v[40:41], s[84:85] op_sel_hi:[1,1,0]
	v_pk_mul_f32 v[32:33], v[32:33], v[40:41]
	v_pk_mul_f32 v[40:41], v[24:25], v[24:25]
	v_pk_mul_f32 v[32:33], v[38:39], v[32:33]
	v_pk_mul_f32 v[40:41], v[40:41], s[18:19] op_sel_hi:[1,0]
	v_pk_mul_f32 v[38:39], v[30:31], v[32:33]
	v_pk_fma_f32 v[32:33], v[30:31], v[32:33], v[30:31] neg_lo:[1,0,0] neg_hi:[1,0,0]
	v_exp_f32_e32 v40, v40
	v_cndmask_b32_e32 v30, v32, v38, vcc
	v_cmp_gt_f32_e32 vcc, 0, v31
	v_and_b32_e32 v32, 0x7fffffff, v24
	v_exp_f32_e32 v41, v41
	v_cndmask_b32_e32 v31, v33, v39, vcc
	v_and_b32_e32 v33, 0x7fffffff, v25
	v_pk_fma_f32 v[32:33], v[32:33], s[90:91], 1.0 op_sel_hi:[1,0,0]
	v_cmp_gt_f32_e32 vcc, 0, v24
	v_rcp_f32_e32 v32, v32
	v_rcp_f32_e32 v33, v33
	s_nop 0
	v_pk_fma_f32 v[38:39], v[32:33], s[92:93], v[36:37] op_sel_hi:[1,0,0]
	v_pk_fma_f32 v[38:39], v[32:33], v[38:39], s[96:97] op_sel_hi:[1,1,0]
	v_pk_fma_f32 v[38:39], v[32:33], v[38:39], s[16:17] op_sel_hi:[1,1,0]
	v_pk_fma_f32 v[38:39], v[32:33], v[38:39], s[84:85] op_sel_hi:[1,1,0]
	v_pk_mul_f32 v[32:33], v[32:33], v[38:39]
	v_pk_mul_f32 v[38:39], v[26:27], v[26:27]
	v_pk_mul_f32 v[32:33], v[40:41], v[32:33]
	v_pk_mul_f32 v[40:41], v[24:25], v[32:33]
	v_pk_fma_f32 v[32:33], v[24:25], v[32:33], v[24:25] neg_lo:[1,0,0] neg_hi:[1,0,0]
	v_cndmask_b32_e32 v24, v32, v40, vcc
	v_cmp_gt_f32_e32 vcc, 0, v25
	v_and_b32_e32 v32, 0x7fffffff, v26
	s_nop 0
	v_cndmask_b32_e32 v25, v33, v41, vcc
	v_and_b32_e32 v33, 0x7fffffff, v27
	v_pk_fma_f32 v[32:33], v[32:33], s[90:91], 1.0 op_sel_hi:[1,0,0]
	v_cmp_gt_f32_e32 vcc, 0, v26
	v_rcp_f32_e32 v32, v32
	v_rcp_f32_e32 v33, v33
	s_nop 0
	v_pk_fma_f32 v[36:37], v[32:33], s[92:93], v[36:37] op_sel_hi:[1,0,0]
	v_pk_fma_f32 v[36:37], v[32:33], v[36:37], s[96:97] op_sel_hi:[1,1,0]
	v_pk_fma_f32 v[36:37], v[32:33], v[36:37], s[16:17] op_sel_hi:[1,1,0]
	v_pk_fma_f32 v[36:37], v[32:33], v[36:37], s[84:85] op_sel_hi:[1,1,0]
	v_pk_mul_f32 v[32:33], v[32:33], v[36:37]
	v_pk_mul_f32 v[36:37], v[38:39], s[18:19] op_sel_hi:[1,0]
	v_exp_f32_e32 v36, v36
	v_exp_f32_e32 v37, v37
	s_nop 0
	v_pk_mul_f32 v[32:33], v[36:37], v[32:33]
	v_pk_mul_f32 v[36:37], v[26:27], v[32:33]
	v_pk_fma_f32 v[32:33], v[26:27], v[32:33], v[26:27] neg_lo:[1,0,0] neg_hi:[1,0,0]
	v_cndmask_b32_e32 v26, v32, v36, vcc
	v_cmp_gt_f32_e32 vcc, 0, v27
	s_nop 1
	v_cndmask_b32_e32 v27, v33, v37, vcc
; __device__ __forceinline__ u32x4 pack8(f32x4 v0, f32x4 v1) { u32x4 w; w.x = cvt_pk_bf16(v0[0], v0[1]); w.y = cvt_pk_bf16(v0[2], v0[3]); w.z = cvt_pk_bf16(v1[0], v1[1]); w.w = cvt_pk_bf16(v1[2], v1[3]); return w; }
; __device__ __forceinline__ f32x4 gelu4(f32x4 v) { f32x2 a = gelu_pk((f32x2){v[0], v[1]}), b = gelu_pk((f32x2){v[2], v[3]}); return (f32x4){a.x, a.y, b.x, b.y}; }
; __device__ __forceinline__ f32x2 gelu_pk(f32x2 v) {
;     const f32x2 av = __builtin_elementwise_abs(v), d = av * 0.2316418882f + 1.0f;
;     f32x2 t; t.x = __builtin_amdgcn_rcpf(d.x); t.y = __builtin_amdgcn_rcpf(d.y);
;     f32x2 q = t * 0.5307027145f + (-0.7265760135f); q = q * t + 0.7107068705f; q = q * t + (-0.142248368f); q = q * t + 0.127414796f; q = q * t;
;     const f32x2 s = (v * v) * (-0.72134752044f);
;     f32x2 e; e.x = __builtin_amdgcn_exp2f(s.x); e.y = __builtin_amdgcn_exp2f(s.y);
;     const f32x2 m = v * (q * e), r = v - m;
;     f32x2 o; o.x = v.x < 0.f ? m.x : r.x; o.y = v.y < 0.f ? m.y : r.y; return o;
;     __device__ __forceinline__ void operator()(f32x4 (&acc)[2][2][4][2], const Unit& u, int wr, int wc, int fr_, int fq_) const {
;     ...
;                 for (int bj = 0; bj < 2; ++bj) { f32x4 v0 = acc[ai][bj][m][0] * rs, v1 = acc[ai][bj][m][1] * rs;
;                     if (act) { v0 = gelu4(v0); v1 = gelu4(v1); }
;                     s1 += ((v0[0] + v0[1]) + (v0[2] + v0[3])) + ((v1[0] + v1[1]) + (v1[2] + v1[3]));
;                     s2 += ((v0[0] * v0[0] + v0[1] * v0[1]) + (v0[2] * v0[2] + v0[3] * v0[3])) + ((v1[0] * v1[0] + v1[1] * v1[1]) + (v1[2] * v1[2] + v1[3] * v1[3]));
;                     *(u32x4*)(rowp + bj * HALF) = pack8(v0, v1); }
.LBB0_404:
	v_add_u32_e32 v32, 0xa0, v146
	v_ashrrev_i32_e32 v33, 31, v32
	v_mul_lo_u32 v38, s86, v33
	v_mul_lo_u32 v39, s87, v32
	v_mad_u64_u32 v[36:37], s[14:15], s86, v32, 0
	v_add3_u32 v37, v37, v38, v39
	v_lshl_add_u64 v[36:37], v[36:37], 1, v[120:121]
	v_cvt_pk_bf16_f32 v38, v28, v29
	v_cvt_pk_bf16_f32 v39, v30, v31
	v_cvt_pk_bf16_f32 v40, v24, v25
	v_cvt_pk_bf16_f32 v41, v26, v27
	v_mov_b32_e32 v35, v34
	global_store_dwordx4 v[36:37], v[38:41], off
	v_pk_mul_f32 v[20:21], v[20:21], v[34:35]
	s_and_b64 vcc, exec, s[6:7]
	v_mov_b32_e32 v38, v34
	v_mov_b32_e32 v39, v34
	v_pk_mul_f32 v[22:23], v[22:23], v[38:39]
	v_pk_mul_f32 v[18:19], v[18:19], v[38:39]
	v_pk_mul_f32 v[16:17], v[16:17], v[34:35]
	s_cbranch_vccnz .LBB0_406
	v_and_b32_e32 v35, 0x7fffffff, v21
	v_and_b32_e32 v34, 0x7fffffff, v20
	v_pk_fma_f32 v[34:35], v[34:35], s[90:91], 1.0 op_sel_hi:[1,0,0]
	v_mov_b64_e32 v[38:39], s[94:95]
	v_rcp_f32_e32 v34, v34
	v_rcp_f32_e32 v35, v35
	v_pk_mul_f32 v[42:43], v[20:21], v[20:21]
	v_cmp_gt_f32_e32 vcc, 0, v20
	v_pk_mul_f32 v[42:43], v[42:43], s[18:19] op_sel_hi:[1,0]
	v_pk_fma_f32 v[40:41], v[34:35], s[92:93], v[38:39] op_sel_hi:[1,0,0]
	v_exp_f32_e32 v42, v42
	v_pk_fma_f32 v[40:41], v[34:35], v[40:41], s[96:97] op_sel_hi:[1,1,0]
	v_exp_f32_e32 v43, v43
	v_pk_fma_f32 v[40:41], v[34:35], v[40:41], s[16:17] op_sel_hi:[1,1,0]
	v_pk_fma_f32 v[40:41], v[34:35], v[40:41], s[84:85] op_sel_hi:[1,1,0]
	v_pk_mul_f32 v[34:35], v[34:35], v[40:41]
	v_pk_mul_f32 v[40:41], v[22:23], v[22:23]
	v_pk_mul_f32 v[34:35], v[42:43], v[34:35]
	v_pk_mul_f32 v[40:41], v[40:41], s[18:19] op_sel_hi:[1,0]
	v_pk_mul_f32 v[42:43], v[20:21], v[34:35]
	v_pk_fma_f32 v[34:35], v[20:21], v[34:35], v[20:21] neg_lo:[1,0,0] neg_hi:[1,0,0]
	v_exp_f32_e32 v40, v40
	v_cndmask_b32_e32 v20, v34, v42, vcc
	v_cmp_gt_f32_e32 vcc, 0, v21
	v_and_b32_e32 v34, 0x7fffffff, v22
	v_exp_f32_e32 v41, v41
	v_cndmask_b32_e32 v21, v35, v43, vcc
	v_and_b32_e32 v35, 0x7fffffff, v23
	v_pk_fma_f32 v[34:35], v[34:35], s[90:91], 1.0 op_sel_hi:[1,0,0]
	v_cmp_gt_f32_e32 vcc, 0, v22
	v_rcp_f32_e32 v34, v34
	v_rcp_f32_e32 v35, v35
	s_nop 0
	v_pk_fma_f32 v[42:43], v[34:35], s[92:93], v[38:39] op_sel_hi:[1,0,0]
	v_pk_fma_f32 v[42:43], v[34:35], v[42:43], s[96:97] op_sel_hi:[1,1,0]
	v_pk_fma_f32 v[42:43], v[34:35], v[42:43], s[16:17] op_sel_hi:[1,1,0]
	v_pk_fma_f32 v[42:43], v[34:35], v[42:43], s[84:85] op_sel_hi:[1,1,0]
	v_pk_mul_f32 v[34:35], v[34:35], v[42:43]
	v_pk_mul_f32 v[42:43], v[16:17], v[16:17]
	v_pk_mul_f32 v[34:35], v[40:41], v[34:35]
	v_pk_mul_f32 v[42:43], v[42:43], s[18:19] op_sel_hi:[1,0]
	v_pk_mul_f32 v[40:41], v[22:23], v[34:35]
	v_pk_fma_f32 v[34:35], v[22:23], v[34:35], v[22:23] neg_lo:[1,0,0] neg_hi:[1,0,0]
	v_exp_f32_e32 v42, v42
	v_cndmask_b32_e32 v22, v34, v40, vcc
	v_cmp_gt_f32_e32 vcc, 0, v23
	v_and_b32_e32 v34, 0x7fffffff, v16
	v_exp_f32_e32 v43, v43
	v_cndmask_b32_e32 v23, v35, v41, vcc
	v_and_b32_e32 v35, 0x7fffffff, v17
	v_pk_fma_f32 v[34:35], v[34:35], s[90:91], 1.0 op_sel_hi:[1,0,0]
	v_cmp_gt_f32_e32 vcc, 0, v16
	v_rcp_f32_e32 v34, v34
	v_rcp_f32_e32 v35, v35
	s_nop 0
	v_pk_fma_f32 v[40:41], v[34:35], s[92:93], v[38:39] op_sel_hi:[1,0,0]
	v_pk_fma_f32 v[40:41], v[34:35], v[40:41], s[96:97] op_sel_hi:[1,1,0]
	v_pk_fma_f32 v[40:41], v[34:35], v[40:41], s[16:17] op_sel_hi:[1,1,0]
	v_pk_fma_f32 v[40:41], v[34:35], v[40:41], s[84:85] op_sel_hi:[1,1,0]
	v_pk_mul_f32 v[34:35], v[34:35], v[40:41]
	v_pk_mul_f32 v[40:41], v[18:19], v[18:19]
	v_pk_mul_f32 v[34:35], v[42:43], v[34:35]
	v_pk_mul_f32 v[42:43], v[16:17], v[34:35]
	v_pk_fma_f32 v[34:35], v[16:17], v[34:35], v[16:17] neg_lo:[1,0,0] neg_hi:[1,0,0]
	v_cndmask_b32_e32 v16, v34, v42, vcc
	v_cmp_gt_f32_e32 vcc, 0, v17
	v_and_b32_e32 v34, 0x7fffffff, v18
	s_nop 0
	v_cndmask_b32_e32 v17, v35, v43, vcc
	v_and_b32_e32 v35, 0x7fffffff, v19
	v_pk_fma_f32 v[34:35], v[34:35], s[90:91], 1.0 op_sel_hi:[1,0,0]
	v_cmp_gt_f32_e32 vcc, 0, v18
	v_rcp_f32_e32 v34, v34
	v_rcp_f32_e32 v35, v35
	s_nop 0
	v_pk_fma_f32 v[38:39], v[34:35], s[92:93], v[38:39] op_sel_hi:[1,0,0]
	v_pk_fma_f32 v[38:39], v[34:35], v[38:39], s[96:97] op_sel_hi:[1,1,0]
	v_pk_fma_f32 v[38:39], v[34:35], v[38:39], s[16:17] op_sel_hi:[1,1,0]
	v_pk_fma_f32 v[38:39], v[34:35], v[38:39], s[84:85] op_sel_hi:[1,1,0]
	v_pk_mul_f32 v[34:35], v[34:35], v[38:39]
	v_pk_mul_f32 v[38:39], v[40:41], s[18:19] op_sel_hi:[1,0]
	v_exp_f32_e32 v38, v38
	v_exp_f32_e32 v39, v39
	s_nop 0
	v_pk_mul_f32 v[34:35], v[38:39], v[34:35]
	v_pk_mul_f32 v[38:39], v[18:19], v[34:35]
	v_pk_fma_f32 v[34:35], v[18:19], v[34:35], v[18:19] neg_lo:[1,0,0] neg_hi:[1,0,0]
	v_cndmask_b32_e32 v18, v34, v38, vcc
	v_cmp_gt_f32_e32 vcc, 0, v19
	s_nop 1
	v_cndmask_b32_e32 v19, v35, v39, vcc

; __device__ __forceinline__ f32x4 gelu4(f32x4 v) { f32x2 a = gelu_pk((f32x2){v[0], v[1]}), b = gelu_pk((f32x2){v[2], v[3]}); return (f32x4){a.x, a.y, b.x, b.y}; }
; __device__ __forceinline__ f32x2 gelu_pk(f32x2 v) {
;     const f32x2 av = __builtin_elementwise_abs(v), d = av * 0.2316418882f + 1.0f;
;     f32x2 t; t.x = __builtin_amdgcn_rcpf(d.x); t.y = __builtin_amdgcn_rcpf(d.y);
;     f32x2 q = t * 0.5307027145f + (-0.7265760135f); q = q * t + 0.7107068705f; q = q * t + (-0.142248368f); q = q * t + 0.127414796f; q = q * t;
;     const f32x2 s = (v * v) * (-0.72134752044f);
;     f32x2 e; e.x = __builtin_amdgcn_exp2f(s.x); e.y = __builtin_amdgcn_exp2f(s.y);
;     const f32x2 m = v * (q * e), r = v - m;
;     f32x2 o; o.x = v.x < 0.f ? m.x : r.x; o.y = v.y < 0.f ? m.y : r.y; return o;
;     __device__ __forceinline__ void operator()(f32x4 (&acc)[2][2][4][2], const Unit& u, int wr, int wc, int fr_, int fq_) const {
;     ...
;             for (int m = 0; m < 4; ++m) { const int row = row0 + ai * HALF + m * 16; const float rs = rstd[row]; bf16_t* rowp = base + (size_t)row * ld + col0;
;                 float s1 = 0.f, s2 = 0.f;
; #pragma unroll
;                 for (int bj = 0; bj < 2; ++bj) { f32x4 v0 = acc[ai][bj][m][0] * rs, v1 = acc[ai][bj][m][1] * rs;
;                     if (act) { v0 = gelu4(v0); v1 = gelu4(v1); }
.LBB0_410:
	v_mov_b32_e32 v18, v251
	s_and_b64 vcc, exec, s[6:7]
	s_waitcnt lgkmcnt(0)
	v_pk_mul_f32 v[14:15], v[14:15], v[18:19] op_sel_hi:[1,0]
	v_pk_mul_f32 v[12:13], v[12:13], v[18:19] op_sel_hi:[1,0]
	v_pk_mul_f32 v[10:11], v[10:11], v[18:19] op_sel_hi:[1,0]
	v_pk_mul_f32 v[8:9], v[8:9], v[18:19] op_sel_hi:[1,0]
	s_cbranch_vccnz .LBB0_412
	v_and_b32_e32 v17, 0x7fffffff, v13
	v_and_b32_e32 v16, 0x7fffffff, v12
	v_pk_fma_f32 v[16:17], v[16:17], s[90:91], 1.0 op_sel_hi:[1,0,0]
	v_mov_b64_e32 v[20:21], s[94:95]
	v_rcp_f32_e32 v16, v16
	v_rcp_f32_e32 v17, v17
	v_pk_mul_f32 v[24:25], v[12:13], v[12:13]
	v_cmp_gt_f32_e32 vcc, 0, v12
	v_pk_mul_f32 v[24:25], v[24:25], s[18:19] op_sel_hi:[1,0]
	v_pk_fma_f32 v[22:23], v[16:17], s[92:93], v[20:21] op_sel_hi:[1,0,0]
	v_exp_f32_e32 v24, v24
	v_pk_fma_f32 v[22:23], v[16:17], v[22:23], s[96:97] op_sel_hi:[1,1,0]
	v_exp_f32_e32 v25, v25
	v_pk_fma_f32 v[22:23], v[16:17], v[22:23], s[16:17] op_sel_hi:[1,1,0]
	v_pk_fma_f32 v[22:23], v[16:17], v[22:23], s[84:85] op_sel_hi:[1,1,0]
	v_pk_mul_f32 v[16:17], v[16:17], v[22:23]
	v_pk_mul_f32 v[22:23], v[14:15], v[14:15]
	v_pk_mul_f32 v[16:17], v[24:25], v[16:17]
	v_pk_mul_f32 v[22:23], v[22:23], s[18:19] op_sel_hi:[1,0]
	v_pk_mul_f32 v[24:25], v[12:13], v[16:17]
	v_pk_fma_f32 v[16:17], v[12:13], v[16:17], v[12:13] neg_lo:[1,0,0] neg_hi:[1,0,0]
	v_exp_f32_e32 v22, v22
	v_cndmask_b32_e32 v12, v16, v24, vcc
	v_cmp_gt_f32_e32 vcc, 0, v13
	v_and_b32_e32 v16, 0x7fffffff, v14
	v_exp_f32_e32 v23, v23
	v_cndmask_b32_e32 v13, v17, v25, vcc
	v_and_b32_e32 v17, 0x7fffffff, v15
	v_pk_fma_f32 v[16:17], v[16:17], s[90:91], 1.0 op_sel_hi:[1,0,0]
	v_cmp_gt_f32_e32 vcc, 0, v14
	v_rcp_f32_e32 v16, v16
	v_rcp_f32_e32 v17, v17
	s_nop 0
	v_pk_fma_f32 v[24:25], v[16:17], s[92:93], v[20:21] op_sel_hi:[1,0,0]
	v_pk_fma_f32 v[24:25], v[16:17], v[24:25], s[96:97] op_sel_hi:[1,1,0]
	v_pk_fma_f32 v[24:25], v[16:17], v[24:25], s[16:17] op_sel_hi:[1,1,0]
	v_pk_fma_f32 v[24:25], v[16:17], v[24:25], s[84:85] op_sel_hi:[1,1,0]
	v_pk_mul_f32 v[16:17], v[16:17], v[24:25]
	v_pk_mul_f32 v[24:25], v[8:9], v[8:9]
	v_pk_mul_f32 v[16:17], v[22:23], v[16:17]
	v_pk_mul_f32 v[24:25], v[24:25], s[18:19] op_sel_hi:[1,0]
	v_pk_mul_f32 v[22:23], v[14:15], v[16:17]
	v_pk_fma_f32 v[16:17], v[14:15], v[16:17], v[14:15] neg_lo:[1,0,0] neg_hi:[1,0,0]
	v_exp_f32_e32 v24, v24
	v_cndmask_b32_e32 v14, v16, v22, vcc
	v_cmp_gt_f32_e32 vcc, 0, v15
	v_and_b32_e32 v16, 0x7fffffff, v8
	v_exp_f32_e32 v25, v25
	v_cndmask_b32_e32 v15, v17, v23, vcc
	v_and_b32_e32 v17, 0x7fffffff, v9
	v_pk_fma_f32 v[16:17], v[16:17], s[90:91], 1.0 op_sel_hi:[1,0,0]
	v_cmp_gt_f32_e32 vcc, 0, v8
	v_rcp_f32_e32 v16, v16
	v_rcp_f32_e32 v17, v17
	s_nop 0
	v_pk_fma_f32 v[22:23], v[16:17], s[92:93], v[20:21] op_sel_hi:[1,0,0]
	v_pk_fma_f32 v[22:23], v[16:17], v[22:23], s[96:97] op_sel_hi:[1,1,0]
	v_pk_fma_f32 v[22:23], v[16:17], v[22:23], s[16:17] op_sel_hi:[1,1,0]
	v_pk_fma_f32 v[22:23], v[16:17], v[22:23], s[84:85] op_sel_hi:[1,1,0]
	v_pk_mul_f32 v[16:17], v[16:17], v[22:23]
	v_pk_mul_f32 v[22:23], v[10:11], v[10:11]
	v_pk_mul_f32 v[16:17], v[24:25], v[16:17]
	v_pk_mul_f32 v[24:25], v[8:9], v[16:17]
	v_pk_fma_f32 v[16:17], v[8:9], v[16:17], v[8:9] neg_lo:[1,0,0] neg_hi:[1,0,0]
	v_cndmask_b32_e32 v8, v16, v24, vcc
	v_cmp_gt_f32_e32 vcc, 0, v9
	v_and_b32_e32 v16, 0x7fffffff, v10
	s_nop 0
	v_cndmask_b32_e32 v9, v17, v25, vcc
	v_and_b32_e32 v17, 0x7fffffff, v11
	v_pk_fma_f32 v[16:17], v[16:17], s[90:91], 1.0 op_sel_hi:[1,0,0]
	v_cmp_gt_f32_e32 vcc, 0, v10
	v_rcp_f32_e32 v16, v16
	v_rcp_f32_e32 v17, v17
	s_nop 0
	v_pk_fma_f32 v[20:21], v[16:17], s[92:93], v[20:21] op_sel_hi:[1,0,0]
	v_pk_fma_f32 v[20:21], v[16:17], v[20:21], s[96:97] op_sel_hi:[1,1,0]
	v_pk_fma_f32 v[20:21], v[16:17], v[20:21], s[16:17] op_sel_hi:[1,1,0]
	v_pk_fma_f32 v[20:21], v[16:17], v[20:21], s[84:85] op_sel_hi:[1,1,0]
	v_pk_mul_f32 v[16:17], v[16:17], v[20:21]
	v_pk_mul_f32 v[20:21], v[22:23], s[18:19] op_sel_hi:[1,0]
	v_exp_f32_e32 v20, v20
	v_exp_f32_e32 v21, v21
	s_nop 0
	v_pk_mul_f32 v[16:17], v[20:21], v[16:17]
	v_pk_mul_f32 v[20:21], v[10:11], v[16:17]
	v_pk_fma_f32 v[16:17], v[10:11], v[16:17], v[10:11] neg_lo:[1,0,0] neg_hi:[1,0,0]
	v_cndmask_b32_e32 v10, v16, v20, vcc
	v_cmp_gt_f32_e32 vcc, 0, v11
	s_nop 1
	v_cndmask_b32_e32 v11, v17, v21, vcc
; __device__ __forceinline__ u32x4 pack8(f32x4 v0, f32x4 v1) { u32x4 w; w.x = cvt_pk_bf16(v0[0], v0[1]); w.y = cvt_pk_bf16(v0[2], v0[3]); w.z = cvt_pk_bf16(v1[0], v1[1]); w.w = cvt_pk_bf16(v1[2], v1[3]); return w; }
; __device__ __forceinline__ f32x4 gelu4(f32x4 v) { f32x2 a = gelu_pk((f32x2){v[0], v[1]}), b = gelu_pk((f32x2){v[2], v[3]}); return (f32x4){a.x, a.y, b.x, b.y}; }
; __device__ __forceinline__ f32x2 gelu_pk(f32x2 v) {
;     const f32x2 av = __builtin_elementwise_abs(v), d = av * 0.2316418882f + 1.0f;
;     f32x2 t; t.x = __builtin_amdgcn_rcpf(d.x); t.y = __builtin_amdgcn_rcpf(d.y);
;     f32x2 q = t * 0.5307027145f + (-0.7265760135f); q = q * t + 0.7107068705f; q = q * t + (-0.142248368f); q = q * t + 0.127414796f; q = q * t;
;     const f32x2 s = (v * v) * (-0.72134752044f);
;     f32x2 e; e.x = __builtin_amdgcn_exp2f(s.x); e.y = __builtin_amdgcn_exp2f(s.y);
;     const f32x2 m = v * (q * e), r = v - m;
;     f32x2 o; o.x = v.x < 0.f ? m.x : r.x; o.y = v.y < 0.f ? m.y : r.y; return o;
;     __device__ __forceinline__ void operator()(f32x4 (&acc)[2][2][4][2], const Unit& u, int wr, int wc, int fr_, int fq_) const {
;     ...
;                 for (int bj = 0; bj < 2; ++bj) { f32x4 v0 = acc[ai][bj][m][0] * rs, v1 = acc[ai][bj][m][1] * rs;
;                     if (act) { v0 = gelu4(v0); v1 = gelu4(v1); }
;                     s1 += ((v0[0] + v0[1]) + (v0[2] + v0[3])) + ((v1[0] + v1[1]) + (v1[2] + v1[3]));
;                     s2 += ((v0[0] * v0[0] + v0[1] * v0[1]) + (v0[2] * v0[2] + v0[3] * v0[3])) + ((v1[0] * v1[0] + v1[1] * v1[1]) + (v1[2] * v1[2] + v1[3] * v1[3]));
;                     *(u32x4*)(rowp + bj * HALF) = pack8(v0, v1); }
.LBB0_412:
	v_add_u32_e32 v16, 0xb0, v146
	v_ashrrev_i32_e32 v17, 31, v16
	v_mul_lo_u32 v22, s86, v17
	v_mul_lo_u32 v23, s87, v16
	v_mad_u64_u32 v[20:21], s[14:15], s86, v16, 0
	v_add3_u32 v21, v21, v22, v23
	v_lshl_add_u64 v[20:21], v[20:21], 1, v[120:121]
	v_cvt_pk_bf16_f32 v22, v12, v13
	v_cvt_pk_bf16_f32 v23, v14, v15
	v_cvt_pk_bf16_f32 v24, v8, v9
	v_cvt_pk_bf16_f32 v25, v10, v11
	v_mov_b32_e32 v19, v18
	global_store_dwordx4 v[20:21], v[22:25], off
	v_pk_mul_f32 v[4:5], v[4:5], v[18:19]
	s_and_b64 vcc, exec, s[6:7]
	v_mov_b32_e32 v22, v18
	v_mov_b32_e32 v23, v18
	v_pk_mul_f32 v[6:7], v[6:7], v[22:23]
	v_pk_mul_f32 v[2:3], v[2:3], v[22:23]
	v_pk_mul_f32 v[0:1], v[0:1], v[18:19]
	s_cbranch_vccnz .LBB0_414
	v_and_b32_e32 v19, 0x7fffffff, v5
	v_and_b32_e32 v18, 0x7fffffff, v4
	v_pk_fma_f32 v[18:19], v[18:19], s[90:91], 1.0 op_sel_hi:[1,0,0]
	v_mov_b64_e32 v[22:23], s[94:95]
	v_rcp_f32_e32 v18, v18
	v_rcp_f32_e32 v19, v19
	v_pk_mul_f32 v[26:27], v[4:5], v[4:5]
	v_cmp_gt_f32_e32 vcc, 0, v4
	v_pk_mul_f32 v[26:27], v[26:27], s[18:19] op_sel_hi:[1,0]
	v_pk_fma_f32 v[24:25], v[18:19], s[92:93], v[22:23] op_sel_hi:[1,0,0]
	v_exp_f32_e32 v26, v26
	v_pk_fma_f32 v[24:25], v[18:19], v[24:25], s[96:97] op_sel_hi:[1,1,0]
	v_exp_f32_e32 v27, v27
	v_pk_fma_f32 v[24:25], v[18:19], v[24:25], s[16:17] op_sel_hi:[1,1,0]
	v_pk_fma_f32 v[24:25], v[18:19], v[24:25], s[84:85] op_sel_hi:[1,1,0]
	v_pk_mul_f32 v[18:19], v[18:19], v[24:25]
	v_pk_mul_f32 v[24:25], v[6:7], v[6:7]
	v_pk_mul_f32 v[18:19], v[26:27], v[18:19]
	v_pk_mul_f32 v[24:25], v[24:25], s[18:19] op_sel_hi:[1,0]
	v_pk_mul_f32 v[26:27], v[4:5], v[18:19]
	v_pk_fma_f32 v[18:19], v[4:5], v[18:19], v[4:5] neg_lo:[1,0,0] neg_hi:[1,0,0]
	v_exp_f32_e32 v24, v24
	v_cndmask_b32_e32 v4, v18, v26, vcc
	v_cmp_gt_f32_e32 vcc, 0, v5
	v_and_b32_e32 v18, 0x7fffffff, v6
	v_exp_f32_e32 v25, v25
	v_cndmask_b32_e32 v5, v19, v27, vcc
	v_and_b32_e32 v19, 0x7fffffff, v7
	v_pk_fma_f32 v[18:19], v[18:19], s[90:91], 1.0 op_sel_hi:[1,0,0]
	v_cmp_gt_f32_e32 vcc, 0, v6
	v_rcp_f32_e32 v18, v18
	v_rcp_f32_e32 v19, v19
	s_nop 0
	v_pk_fma_f32 v[26:27], v[18:19], s[92:93], v[22:23] op_sel_hi:[1,0,0]
	v_pk_fma_f32 v[26:27], v[18:19], v[26:27], s[96:97] op_sel_hi:[1,1,0]
	v_pk_fma_f32 v[26:27], v[18:19], v[26:27], s[16:17] op_sel_hi:[1,1,0]
	v_pk_fma_f32 v[26:27], v[18:19], v[26:27], s[84:85] op_sel_hi:[1,1,0]
	v_pk_mul_f32 v[18:19], v[18:19], v[26:27]
	v_pk_mul_f32 v[26:27], v[0:1], v[0:1]
	v_pk_mul_f32 v[18:19], v[24:25], v[18:19]
	v_pk_mul_f32 v[26:27], v[26:27], s[18:19] op_sel_hi:[1,0]
	v_pk_mul_f32 v[24:25], v[6:7], v[18:19]
	v_pk_fma_f32 v[18:19], v[6:7], v[18:19], v[6:7] neg_lo:[1,0,0] neg_hi:[1,0,0]
	v_exp_f32_e32 v26, v26
	v_cndmask_b32_e32 v6, v18, v24, vcc
	v_cmp_gt_f32_e32 vcc, 0, v7
	v_and_b32_e32 v18, 0x7fffffff, v0
	v_exp_f32_e32 v27, v27
	v_cndmask_b32_e32 v7, v19, v25, vcc
	v_and_b32_e32 v19, 0x7fffffff, v1
	v_pk_fma_f32 v[18:19], v[18:19], s[90:91], 1.0 op_sel_hi:[1,0,0]
	v_cmp_gt_f32_e32 vcc, 0, v0
	v_rcp_f32_e32 v18, v18
	v_rcp_f32_e32 v19, v19
	s_nop 0
	v_pk_fma_f32 v[24:25], v[18:19], s[92:93], v[22:23] op_sel_hi:[1,0,0]
	v_pk_fma_f32 v[24:25], v[18:19], v[24:25], s[96:97] op_sel_hi:[1,1,0]
	v_pk_fma_f32 v[24:25], v[18:19], v[24:25], s[16:17] op_sel_hi:[1,1,0]
	v_pk_fma_f32 v[24:25], v[18:19], v[24:25], s[84:85] op_sel_hi:[1,1,0]
	v_pk_mul_f32 v[18:19], v[18:19], v[24:25]
	v_pk_mul_f32 v[24:25], v[2:3], v[2:3]
	v_pk_mul_f32 v[18:19], v[26:27], v[18:19]
	v_pk_mul_f32 v[26:27], v[0:1], v[18:19]
	v_pk_fma_f32 v[18:19], v[0:1], v[18:19], v[0:1] neg_lo:[1,0,0] neg_hi:[1,0,0]
	v_cndmask_b32_e32 v0, v18, v26, vcc
	v_cmp_gt_f32_e32 vcc, 0, v1
	v_and_b32_e32 v18, 0x7fffffff, v2
	s_nop 0
	v_cndmask_b32_e32 v1, v19, v27, vcc
	v_and_b32_e32 v19, 0x7fffffff, v3
	v_pk_fma_f32 v[18:19], v[18:19], s[90:91], 1.0 op_sel_hi:[1,0,0]
	v_cmp_gt_f32_e32 vcc, 0, v2
	v_rcp_f32_e32 v18, v18
	v_rcp_f32_e32 v19, v19
	s_nop 0
	v_pk_fma_f32 v[22:23], v[18:19], s[92:93], v[22:23] op_sel_hi:[1,0,0]
	v_pk_fma_f32 v[22:23], v[18:19], v[22:23], s[96:97] op_sel_hi:[1,1,0]
	v_pk_fma_f32 v[22:23], v[18:19], v[22:23], s[16:17] op_sel_hi:[1,1,0]
	v_pk_fma_f32 v[22:23], v[18:19], v[22:23], s[84:85] op_sel_hi:[1,1,0]
	v_pk_mul_f32 v[18:19], v[18:19], v[22:23]
	v_pk_mul_f32 v[22:23], v[24:25], s[18:19] op_sel_hi:[1,0]
	v_exp_f32_e32 v22, v22
	v_exp_f32_e32 v23, v23
	s_nop 0
	v_pk_mul_f32 v[18:19], v[22:23], v[18:19]
	v_pk_mul_f32 v[22:23], v[2:3], v[18:19]
	v_pk_fma_f32 v[18:19], v[2:3], v[18:19], v[2:3] neg_lo:[1,0,0] neg_hi:[1,0,0]
	v_cndmask_b32_e32 v2, v18, v22, vcc
	v_cmp_gt_f32_e32 vcc, 0, v3
	s_nop 1
	v_cndmask_b32_e32 v3, v19, v23, vcc

.LBB0_1368:
	s_waitcnt vmcnt(18)
	v_mfma_f32_16x16x32_bf16 v[166:169], v[0:3], v[92:95], 0
	s_add_i32 s57, s57, 2
	v_add_u32_e32 v126, 0x200, v126
	v_add_u32_e32 v128, 32, v128
	s_waitcnt vmcnt(17)
	v_mfma_f32_16x16x32_bf16 v[166:169], v[4:7], v[88:91], v[166:169]
	v_mfma_f32_16x16x32_bf16 v[172:175], v[8:11], v[92:95], 0
	s_waitcnt vmcnt(15)
	s_nop 5
	v_pk_add_f32 v[168:169], v[110:111], v[168:169]
	v_pk_add_f32 v[166:167], v[108:109], v[166:167]
	v_mul_f32_e32 v108, v169, v169
	v_pk_fma_f32 v[176:177], v[168:169], v[168:169], v[108:109] op_sel_hi:[1,1,0]
	v_mfma_f32_16x16x32_bf16 v[108:111], v[16:19], v[88:91], v[172:175]
	v_mul_f32_e64 v186, v166, v166
	v_mul_f32_e64 v187, v167, v167
	v_pk_add_f32 v[188:189], v[166:167], v[166:167] op_sel_hi:[0,1]
	v_mov_b32_e32 v187, v189
	v_pk_mov_b32 v[188:189], v[166:167], v[168:169] op_sel:[1,0]
	v_mov_b32_e32 v177, v115
	s_waitcnt vmcnt(14)
	s_nop 0
	v_pk_add_f32 v[110:111], v[106:107], v[110:111]
	v_pk_add_f32 v[108:109], v[104:105], v[108:109]
	v_mfma_f32_16x16x32_bf16 v[104:107], v[12:15], v[92:95], 0
	v_mul_f32_e64 v190, v188, v167
	v_mul_f32_e64 v191, v189, v166
	v_pk_add_f32 v[188:189], v[188:189], v[168:169]
	v_mul_f32_e32 v172, v108, v108
	v_mfma_f32_16x16x32_bf16 v[92:95], v[20:23], v[92:95], 0
	v_mul_f32_e32 v174, v109, v109
	v_mul_f32_e32 v178, v110, v110
	v_mul_f32_e32 v180, v111, v111
	v_mfma_f32_16x16x32_bf16 v[104:107], v[24:27], v[88:91], v[104:107]
	v_mov_b32_e32 v191, v189
	v_mov_b32_e32 v173, v108
	v_mov_b32_e32 v175, v109
	v_mfma_f32_16x16x32_bf16 v[88:91], v[28:31], v[88:91], v[92:95]
	v_mov_b32_e32 v179, v110
	s_waitcnt vmcnt(13)
	s_nop 1
	v_pk_add_f32 v[102:103], v[102:103], v[106:107]
	v_pk_add_f32 v[100:101], v[100:101], v[104:105]
	v_mov_b32_e32 v181, v111
	v_mul_f32_e32 v104, v100, v100
	v_mul_f32_e32 v106, v101, v101
	v_mul_f32_e32 v182, v102, v102
	v_mul_f32_e32 v184, v103, v103
	s_waitcnt vmcnt(12)
	v_pk_add_f32 v[90:91], v[98:99], v[90:91]
	v_pk_add_f32 v[88:89], v[96:97], v[88:89]
	v_pk_add_f32 v[186:187], v[186:187], v[190:191]
	v_pk_add_f32 v[172:173], v[172:173], v[174:175]
	v_pk_add_f32 v[174:175], v[178:179], v[180:181]
	v_mov_b32_e32 v105, v100
	v_mov_b32_e32 v107, v101
	v_mov_b32_e32 v183, v102
	v_mov_b32_e32 v185, v103
	v_mul_f32_e32 v92, v88, v88
	v_mul_f32_e32 v94, v89, v89
	v_mul_f32_e32 v96, v90, v90
	v_mul_f32_e32 v98, v91, v91
	v_pk_add_f32 v[176:177], v[186:187], v[176:177]
	v_pk_add_f32 v[172:173], v[172:173], v[174:175]
	v_pk_add_f32 v[104:105], v[104:105], v[106:107]
	v_pk_add_f32 v[106:107], v[182:183], v[184:185]
	v_mov_b32_e32 v93, v88
	v_mov_b32_e32 v95, v89
	v_mov_b32_e32 v97, v90
	v_mov_b32_e32 v99, v91
	v_pk_add_f32 v[172:173], v[176:177], v[172:173]
	v_pk_add_f32 v[104:105], v[104:105], v[106:107]
	v_pk_add_f32 v[92:93], v[92:93], v[94:95]
	v_pk_add_f32 v[94:95], v[96:97], v[98:99]
	v_pk_add_f32 v[104:105], v[172:173], v[104:105]
	v_pk_add_f32 v[92:93], v[92:93], v[94:95]
	s_waitcnt vmcnt(11)
	v_and_b32_e32 v99, 0xffff0000, v163
	v_pk_add_f32 v[92:93], v[104:105], v[92:93]
	ds_bpermute_b32 v95, v113, v93
	ds_bpermute_b32 v94, v113, v92
	s_waitcnt vmcnt(7)
	v_lshlrev_b32_e32 v104, 16, v164
	v_and_b32_e32 v105, 0xffff0000, v164
	v_lshlrev_b32_e32 v106, 16, v165
	v_and_b32_e32 v107, 0xffff0000, v165
	s_waitcnt lgkmcnt(0)
	v_pk_add_f32 v[92:93], v[92:93], v[94:95]
	ds_bpermute_b32 v95, v171, v93
	ds_bpermute_b32 v94, v171, v92
	s_waitcnt lgkmcnt(0)
	v_pk_add_f32 v[92:93], v[92:93], v[94:95]
	v_pk_mul_f32 v[92:93], v[92:93], s[54:55] op_sel_hi:[1,0]
	v_fma_f32 v92, -v93, v93, v92
	v_max_f32_e32 v92, 0, v92
	v_add_f32_e32 v92, 0x3a27c5ac, v92
	v_mul_f32_e32 v94, 0x4f800000, v92
	v_cmp_gt_f32_e32 vcc, s55, v92
	v_sub_f32_e32 v109, v109, v93
	v_sub_f32_e32 v108, v108, v93
	v_cndmask_b32_e32 v92, v92, v94, vcc
	v_sqrt_f32_e32 v94, v92
	v_sub_f32_e32 v111, v111, v93
	v_sub_f32_e32 v110, v110, v93
	v_sub_f32_e32 v101, v101, v93
	v_add_u32_e32 v95, -1, v94
	v_fma_f32 v96, -v95, v94, v92
	v_cmp_ge_f32_e64 s[0:1], 0, v96
	v_add_u32_e32 v96, 1, v94
	v_sub_f32_e32 v100, v100, v93
	v_cndmask_b32_e64 v95, v94, v95, s[0:1]
	v_fma_f32 v94, -v96, v94, v92
	v_cmp_lt_f32_e64 s[0:1], 0, v94
	v_sub_f32_e32 v103, v103, v93
	v_sub_f32_e32 v102, v102, v93
	v_cndmask_b32_e64 v94, v95, v96, s[0:1]
	v_mul_f32_e32 v95, 0x37800000, v94
	v_cndmask_b32_e32 v94, v94, v95, vcc
	v_cmp_class_f32_e32 vcc, v92, v121
	v_sub_f32_e32 v89, v89, v93
	v_sub_f32_e32 v88, v88, v93
	v_cndmask_b32_e32 v92, v94, v92, vcc
	v_div_scale_f32 v94, s[0:1], v92, v92, 1.0
	v_rcp_f32_e32 v95, v94
	v_sub_f32_e32 v91, v91, v93
	v_sub_f32_e32 v90, v90, v93
	v_fma_f32 v96, -v94, v95, 1.0
	v_fmac_f32_e32 v95, v96, v95
	v_div_scale_f32 v96, vcc, 1.0, v92, 1.0
	v_mul_f32_e32 v97, v96, v95
	v_fma_f32 v98, -v94, v97, v96
	v_fmac_f32_e32 v97, v98, v95
	v_fma_f32 v94, -v94, v97, v96
	v_div_fmas_f32 v94, v94, v95, v97
	v_div_fixup_f32 v92, v94, v92, 1.0
	v_lshlrev_b32_e32 v96, 16, v162
	v_and_b32_e32 v97, 0xffff0000, v162
	v_lshlrev_b32_e32 v98, 16, v163
	v_sub_f32_e32 v163, v167, v93
	v_sub_f32_e32 v162, v166, v93
	v_pk_mul_f32 v[162:163], v[162:163], v[92:93] op_sel_hi:[1,0]
	v_lshl_add_u64 v[94:95], v[150:151], 1, s[16:17]
	v_pk_fma_f32 v[162:163], v[32:33], v[162:163], v[40:41]
	v_sub_f32_e32 v151, v169, v93
	v_sub_f32_e32 v150, v168, v93
	v_pk_fma_f32 v[96:97], v[114:115], v[96:97], v[162:163] op_sel_hi:[0,1,1]
	v_pk_mul_f32 v[150:151], v[150:151], v[92:93] op_sel_hi:[1,0]
	v_pk_mul_f32 v[96:97], v[96:97], v[104:105]
	v_pk_fma_f32 v[150:151], v[34:35], v[150:151], v[42:43]
	v_bfe_u32 v104, v96, 16, 1
	v_pk_fma_f32 v[98:99], v[114:115], v[98:99], v[150:151] op_sel_hi:[0,1,1]
	v_add3_u32 v96, v96, v104, s33
	v_bfe_u32 v104, v97, 16, 1
	v_pk_mul_f32 v[98:99], v[98:99], v[106:107]
	v_lshrrev_b32_e32 v96, 16, v96
	v_add3_u32 v97, v97, v104, s33
	v_and_or_b32 v96, v97, s50, v96
	v_bfe_u32 v97, v98, 16, 1
	v_add3_u32 v97, v98, v97, s33
	v_bfe_u32 v98, v99, 16, 1
	v_lshrrev_b32_e32 v97, 16, v97
	v_add3_u32 v98, v99, v98, s33
	v_and_or_b32 v97, v98, s50, v97
	v_pk_mul_f32 v[108:109], v[108:109], v[92:93] op_sel_hi:[1,0]
	global_store_dwordx2 v[94:95], v[96:97], off
	v_lshlrev_b32_e32 v96, 16, v158
	v_and_b32_e32 v97, 0xffff0000, v158
	v_pk_fma_f32 v[108:109], v[36:37], v[108:109], v[44:45]
	s_waitcnt vmcnt(7)
; __device__ __forceinline__ void phase_scan2z(const Params& p) {
;     ...
;         for (int tt = 0; tt < CL / 16; tt += 2) {
;             P2_LOAD(B, tt + 1);
;             P2_COMP(A, tt);
;             if (tt + 2 < CL / 16) P2_LOAD(A, tt + 2);
;             P2_COMP(B, tt + 1);
;         }
	v_lshlrev_b32_e32 v104, 16, v160
	v_and_b32_e32 v105, 0xffff0000, v160
	v_pk_fma_f32 v[96:97], v[114:115], v[96:97], v[108:109] op_sel_hi:[0,1,1]
	v_pk_mul_f32 v[110:111], v[110:111], v[92:93] op_sel_hi:[1,0]
	v_pk_mul_f32 v[96:97], v[96:97], v[104:105]
	v_lshlrev_b32_e32 v98, 16, v159
	v_and_b32_e32 v99, 0xffff0000, v159
	v_pk_fma_f32 v[110:111], v[38:39], v[110:111], v[46:47]
	v_bfe_u32 v104, v96, 16, 1
	v_lshlrev_b32_e32 v106, 16, v161
	v_and_b32_e32 v107, 0xffff0000, v161
	v_pk_fma_f32 v[98:99], v[114:115], v[98:99], v[110:111] op_sel_hi:[0,1,1]
	v_add3_u32 v96, v96, v104, s33
	v_bfe_u32 v104, v97, 16, 1
	v_pk_mul_f32 v[98:99], v[98:99], v[106:107]
	v_lshrrev_b32_e32 v96, 16, v96
	v_add3_u32 v97, v97, v104, s33
	v_and_or_b32 v96, v97, s50, v96
	v_bfe_u32 v97, v98, 16, 1
	v_add3_u32 v97, v98, v97, s33
	v_bfe_u32 v98, v99, 16, 1
	v_lshrrev_b32_e32 v97, 16, v97
	v_add3_u32 v98, v99, v98, s33
	v_and_or_b32 v97, v98, s50, v97
	v_pk_mul_f32 v[100:101], v[100:101], v[92:93] op_sel_hi:[1,0]
	global_store_dwordx2 v[94:95], v[96:97], off offset:32
	v_lshlrev_b32_e32 v96, 16, v154
	v_and_b32_e32 v97, 0xffff0000, v154
	v_pk_fma_f32 v[100:101], v[48:49], v[100:101], v[56:57]
	s_waitcnt vmcnt(7)
	v_lshlrev_b32_e32 v104, 16, v156
	v_and_b32_e32 v105, 0xffff0000, v156
	v_pk_fma_f32 v[96:97], v[114:115], v[96:97], v[100:101] op_sel_hi:[0,1,1]
	v_pk_mul_f32 v[102:103], v[102:103], v[92:93] op_sel_hi:[1,0]
	v_pk_mul_f32 v[96:97], v[96:97], v[104:105]
	v_lshlrev_b32_e32 v98, 16, v155
	v_and_b32_e32 v99, 0xffff0000, v155
	v_pk_fma_f32 v[102:103], v[50:51], v[102:103], v[58:59]
	v_bfe_u32 v100, v96, 16, 1
	v_lshlrev_b32_e32 v106, 16, v157
	v_and_b32_e32 v107, 0xffff0000, v157
	v_pk_fma_f32 v[98:99], v[114:115], v[98:99], v[102:103] op_sel_hi:[0,1,1]
	v_add3_u32 v96, v96, v100, s33
	v_bfe_u32 v100, v97, 16, 1
	v_pk_mul_f32 v[98:99], v[98:99], v[106:107]
	v_lshrrev_b32_e32 v96, 16, v96
	v_add3_u32 v97, v97, v100, s33
	v_and_or_b32 v96, v97, s50, v96
	v_bfe_u32 v97, v98, 16, 1
	v_add3_u32 v97, v98, v97, s33
	v_bfe_u32 v98, v99, 16, 1
	v_lshrrev_b32_e32 v97, 16, v97
	v_add3_u32 v98, v99, v98, s33
	v_and_or_b32 v97, v98, s50, v97
	v_pk_mul_f32 v[88:89], v[88:89], v[92:93] op_sel_hi:[1,0]
	global_store_dwordx2 v[94:95], v[96:97], off offset:64
	v_lshlrev_b32_e32 v96, 16, v148
	v_and_b32_e32 v97, 0xffff0000, v148
	v_pk_fma_f32 v[88:89], v[52:53], v[88:89], v[60:61]
	s_waitcnt vmcnt(7)
	v_lshlrev_b32_e32 v100, 16, v152
	v_and_b32_e32 v101, 0xffff0000, v152
	v_pk_fma_f32 v[88:89], v[114:115], v[96:97], v[88:89] op_sel_hi:[0,1,1]
	v_pk_mul_f32 v[90:91], v[90:91], v[92:93] op_sel_hi:[1,0]
	v_pk_mul_f32 v[88:89], v[88:89], v[100:101]
	v_lshlrev_b32_e32 v98, 16, v149
	v_and_b32_e32 v99, 0xffff0000, v149
	v_pk_fma_f32 v[90:91], v[54:55], v[90:91], v[62:63]
	v_bfe_u32 v92, v88, 16, 1
	v_lshlrev_b32_e32 v102, 16, v153
	v_and_b32_e32 v103, 0xffff0000, v153
	v_pk_fma_f32 v[90:91], v[114:115], v[98:99], v[90:91] op_sel_hi:[0,1,1]
	v_add3_u32 v88, v88, v92, s33
	v_bfe_u32 v92, v89, 16, 1
	v_pk_mul_f32 v[90:91], v[90:91], v[102:103]
	v_lshrrev_b32_e32 v88, 16, v88
	v_add3_u32 v89, v89, v92, s33
	v_and_or_b32 v88, v89, s50, v88
	v_bfe_u32 v89, v90, 16, 1
	v_add3_u32 v89, v90, v89, s33
	v_bfe_u32 v90, v91, 16, 1
	v_lshrrev_b32_e32 v89, 16, v89
	v_add3_u32 v90, v91, v90, s33
	v_and_or_b32 v89, v90, s50, v89
	s_and_b64 vcc, exec, s[4:5]
	global_store_dwordx2 v[94:95], v[88:89], off offset:96
	s_cbranch_vccnz .LBB0_1350

;     __device__ __forceinline__ void operator()(f32x4 (&acc)[2][2][4][2], const Unit& u, int wr, int wc, int fr_, int fq_) const {
;     ...
;         if (tid < 256) { const f32x4* p = (const f32x4*)(ssq1 + (size_t)(u.pm * BM + tid) * 32); f32x4 s = p[0];
; #pragma unroll
;             for (int i = 1; i < 8; ++i) s += p[i];
;             rsL[tid] = 1.0f / sqrtf(((s[0] + s[1]) + (s[2] + s[3])) * (1.0f / 2048.0f) + 1e-6f); }
.LBB0_1704:
	v_mov_b32_e32 v178, v216
	v_mov_b32_e32 v128, v217
	s_mov_b64 s[8:9], exec
	v_readlane_b32 s0, v244, 2
	v_readlane_b32 s1, v244, 3
	s_and_b64 s[0:1], s[8:9], s[0:1]
	s_mov_b64 exec, s[0:1]
	s_cbranch_execz .LBB0_1706
	v_lshl_or_b32 v130, s90, 8, v144
	v_ashrrev_i32_e32 v131, 31, v130
	v_readlane_b32 s0, v244, 47
	v_lshlrev_b64 v[130:131], 7, v[130:131]
	v_readlane_b32 s1, v244, 48
	s_nop 1
	v_lshl_add_u64 v[142:143], s[0:1], 0, v[130:131]
	global_load_dwordx4 v[130:133], v[142:143], off offset:48
	global_load_dwordx4 v[134:137], v[142:143], off offset:32
	global_load_dwordx4 v[138:141], v[142:143], off
	global_load_dwordx4 v[164:167], v[142:143], off offset:16
	s_mov_b32 s0, 0xf800000
	s_waitcnt vmcnt(0)
	v_pk_add_f32 v[140:141], v[140:141], v[166:167]
	v_pk_add_f32 v[138:139], v[138:139], v[164:165]
	v_pk_add_f32 v[136:137], v[140:141], v[136:137]
	v_pk_add_f32 v[134:135], v[138:139], v[134:135]
	v_pk_add_f32 v[168:169], v[136:137], v[132:133]
	v_pk_add_f32 v[170:171], v[134:135], v[130:131]
	global_load_dwordx4 v[130:133], v[142:143], off offset:112
	global_load_dwordx4 v[134:137], v[142:143], off offset:96
	global_load_dwordx4 v[138:141], v[142:143], off offset:80
	global_load_dwordx4 v[164:167], v[142:143], off offset:64
	s_waitcnt vmcnt(0)
	v_pk_add_f32 v[142:143], v[168:169], v[166:167]
	v_pk_add_f32 v[164:165], v[170:171], v[164:165]
	v_pk_add_f32 v[140:141], v[142:143], v[140:141]
	v_pk_add_f32 v[138:139], v[164:165], v[138:139]
	v_pk_add_f32 v[136:137], v[140:141], v[136:137]
	v_pk_add_f32 v[134:135], v[138:139], v[134:135]
	v_pk_add_f32 v[132:133], v[136:137], v[132:133]
	v_pk_add_f32 v[130:131], v[134:135], v[130:131]
	v_pk_mov_b32 v[134:135], v[130:131], v[132:133] op_sel:[1,0]
	v_mov_b32_e32 v131, v133
	v_pk_add_f32 v[130:131], v[134:135], v[130:131]
	v_add_f32_e32 v129, v130, v131
	v_fmamk_f32 v129, v129, 0x3a000000, v223
	v_cmp_gt_f32_e32 vcc, s0, v129
	v_mul_f32_e32 v130, 0x4f800000, v129
	s_nop 0
	v_cndmask_b32_e32 v129, v129, v130, vcc
	v_sqrt_f32_e32 v130, v129
	s_nop 0
	v_add_u32_e32 v131, -1, v130
	v_fma_f32 v132, -v131, v130, v129
	v_cmp_ge_f32_e64 s[0:1], 0, v132
	v_add_u32_e32 v132, 1, v130
	s_nop 0
	v_cndmask_b32_e64 v131, v130, v131, s[0:1]
	v_fma_f32 v130, -v132, v130, v129
	v_cmp_lt_f32_e64 s[0:1], 0, v130
	s_nop 1
	v_cndmask_b32_e64 v130, v131, v132, s[0:1]
	v_mul_f32_e32 v131, 0x37800000, v130
	v_cndmask_b32_e32 v130, v130, v131, vcc
	v_cmp_class_f32_e32 vcc, v129, v224
	s_nop 1
	v_cndmask_b32_e32 v129, v130, v129, vcc
	v_div_scale_f32 v130, s[0:1], v129, v129, 1.0
	v_rcp_f32_e32 v131, v130
	s_nop 0
	v_fma_f32 v132, -v130, v131, 1.0
	v_fmac_f32_e32 v131, v132, v131
	v_div_scale_f32 v132, vcc, 1.0, v129, 1.0
	v_mul_f32_e32 v133, v132, v131
	v_fma_f32 v134, -v130, v133, v132
	v_fmac_f32_e32 v133, v134, v131
	v_fma_f32 v130, -v130, v133, v132
	v_div_fmas_f32 v130, v130, v131, v133
	v_div_fixup_f32 v129, v130, v129, 1.0
	ds_write_b32 v218, v129

; #define PG8_LAS __attribute__((address_space(3)))
; __device__ __forceinline__ float dpp_ror1(float x) { float r; asm volatile("s_nop 1\n\tv_mov_b32_dpp %0, %1 row_ror:1 row_mask:0xf bank_mask:0xf" : "=&v"(r) : "v"(x)); return r; }
; __device__ __forceinline__ float dpp_ror2(float x) { float r; asm volatile("s_nop 1\n\tv_mov_b32_dpp %0, %1 row_ror:2 row_mask:0xf bank_mask:0xf" : "=&v"(r) : "v"(x)); return r; }
;     __device__ __forceinline__ void operator()(f32x4 (&acc)[2][2][4][2], const Unit& u, int wr, int wc, int fr_, int fq_) const {
;     ...
;             for (int m = 0; m < 4; ++m) rsr[m] = rsL[blk * 64 + m * 16 + fr];
;             const float rs14 = blk ? rsL[blk * 64 - 2] : 0.f, rs15 = blk ? rsL[blk * 64 - 1] : 0.f;
; #pragma unroll
;             for (int bj = 0; bj < 2; ++bj)
; #pragma unroll
;                 for (int n = 0; n < 2; ++n) {
;                     const int ct = bj * HALF + wc * 32 + 8 * fq + 4 * n;
;                     const int cidx = bj * 5632 + jcol + 4 * n;
;                     const f32x4 w0 = *(const f32x4*)(cw + cidx), w1 = *(const f32x4*)(cw + 11264 + cidx), w2 = *(const f32x4*)(cw + 22528 + cidx), b4 = *(const f32x4*)(cb + cidx);
;                     f32x4 pR1 = (f32x4){0.f, 0.f, 0.f, 0.f}, pR2 = pR1;
;                     if (blk) { const f32x4 h14 = *(const PG8_LAS f32x4*)(hal + ((blk - 1) * 2 + 0) * 256 + ct) * rs14, h15 = *(const PG8_LAS f32x4*)(hal + ((blk - 1) * 2 + 1) * 256 + ct) * rs15;
;                         pR1 = h15; pR2 = (fr == 0) ? h14 : h15; }
; #pragma unroll
;                     for (int m = 0; m < 4; ++m) {
;                         const f32x4 U = acc[ai][bj][m][n] * rsr[m];
;                         f32x4 R1, R2;
; #pragma unroll
;                         for (int i = 0; i < 4; ++i) { R1[i] = dpp_ror1(U[i]); R2[i] = dpp_ror2(U[i]); }
;                         const f32x4 U1 = (fr >= 1) ? R1 : pR1, U2 = (fr >= 2) ? R2 : pR2;
;                         const f32x4 C = b4 + w0 * U2 + w1 * U1 + w2 * U;
;                         acc[ai][bj][m][n] = C; pR1 = R1; pR2 = R2;
;                         asm volatile("" : "+v"(acc[ai][bj][m][n]));
;                         __builtin_amdgcn_sched_barrier(0);
;                     }
;                     asm volatile("" ::: "memory");
.LBB0_1718:
	v_cmp_lt_i32_e64 s[8:9], 1, v178
	v_pk_mul_f32 v[126:127], v[126:127], v[192:193] op_sel_hi:[1,0]
	v_pk_mul_f32 v[124:125], v[124:125], v[192:193] op_sel_hi:[1,0]
	v_cmp_lt_i32_e64 s[6:7], 0, v178
	s_nop 1
	v_mov_b32_dpp v199, v124 row_ror:1 row_mask:0xf bank_mask:0xf
	v_mov_b32_dpp v204, v124 row_ror:2 row_mask:0xf bank_mask:0xf
	v_mov_b32_dpp v205, v125 row_ror:1 row_mask:0xf bank_mask:0xf
	v_mov_b32_dpp v206, v125 row_ror:2 row_mask:0xf bank_mask:0xf
	v_mov_b32_dpp v207, v126 row_ror:1 row_mask:0xf bank_mask:0xf
	v_mov_b32_dpp v208, v126 row_ror:2 row_mask:0xf bank_mask:0xf
	v_mov_b32_dpp v209, v127 row_ror:1 row_mask:0xf bank_mask:0xf
	v_mov_b32_dpp v210, v127 row_ror:2 row_mask:0xf bank_mask:0xf
	v_cndmask_b32_e64 v202, v187, v204, s[8:9]
	v_cndmask_b32_e64 v200, v189, v208, s[8:9]
	v_cndmask_b32_e64 v201, v193, v210, s[8:9]
	v_cndmask_b32_e64 v203, v191, v206, s[8:9]
	v_cndmask_b32_e64 v174, v174, v199, s[6:7]
	v_cndmask_b32_e64 v175, v175, v205, s[6:7]
	v_cndmask_b32_e64 v172, v172, v207, s[6:7]
	v_cndmask_b32_e64 v173, v173, v209, s[6:7]
	s_waitcnt vmcnt(0)
	v_pk_fma_f32 v[202:203], v[136:137], v[202:203], v[140:141]
	v_pk_fma_f32 v[200:201], v[138:139], v[200:201], v[142:143]
	v_pk_fma_f32 v[174:175], v[128:129], v[174:175], v[202:203]
	v_pk_fma_f32 v[172:173], v[130:131], v[172:173], v[200:201]
	v_pk_fma_f32 v[124:125], v[124:125], v[132:133], v[174:175]
	v_pk_fma_f32 v[126:127], v[126:127], v[134:135], v[172:173]
	v_pk_mul_f32 v[122:123], v[122:123], v[190:191] op_sel_hi:[1,0]
	v_pk_mul_f32 v[120:121], v[120:121], v[190:191] op_sel_hi:[1,0]
	s_nop 1
	v_mov_b32_dpp v187, v120 row_ror:1 row_mask:0xf bank_mask:0xf
	v_mov_b32_dpp v189, v120 row_ror:2 row_mask:0xf bank_mask:0xf
	v_mov_b32_dpp v191, v121 row_ror:1 row_mask:0xf bank_mask:0xf
	v_mov_b32_dpp v193, v121 row_ror:2 row_mask:0xf bank_mask:0xf
	v_mov_b32_dpp v211, v122 row_ror:1 row_mask:0xf bank_mask:0xf
	v_mov_b32_dpp v212, v122 row_ror:2 row_mask:0xf bank_mask:0xf
	v_mov_b32_dpp v213, v123 row_ror:1 row_mask:0xf bank_mask:0xf
	v_mov_b32_dpp v214, v123 row_ror:2 row_mask:0xf bank_mask:0xf
	v_cndmask_b32_e64 v202, v204, v189, s[8:9]
	v_cndmask_b32_e64 v200, v208, v212, s[8:9]
	v_cndmask_b32_e64 v201, v210, v214, s[8:9]
	v_cndmask_b32_e64 v203, v206, v193, s[8:9]
	v_cndmask_b32_e64 v172, v199, v187, s[6:7]
	v_cndmask_b32_e64 v173, v205, v191, s[6:7]
	v_cndmask_b32_e64 v174, v207, v211, s[6:7]
	v_cndmask_b32_e64 v175, v209, v213, s[6:7]
	v_pk_fma_f32 v[202:203], v[136:137], v[202:203], v[140:141]
	v_pk_fma_f32 v[200:201], v[138:139], v[200:201], v[142:143]
	v_pk_fma_f32 v[172:173], v[128:129], v[172:173], v[202:203]
	v_pk_fma_f32 v[174:175], v[130:131], v[174:175], v[200:201]
	v_pk_fma_f32 v[120:121], v[120:121], v[132:133], v[172:173]
	v_pk_fma_f32 v[122:123], v[122:123], v[134:135], v[174:175]
	v_pk_mul_f32 v[106:107], v[106:107], v[188:189] op_sel_hi:[1,0]
	v_pk_mul_f32 v[104:105], v[104:105], v[188:189] op_sel_hi:[1,0]
	s_nop 1
	v_mov_b32_dpp v199, v104 row_ror:1 row_mask:0xf bank_mask:0xf
	v_mov_b32_dpp v204, v104 row_ror:2 row_mask:0xf bank_mask:0xf
	v_mov_b32_dpp v205, v105 row_ror:1 row_mask:0xf bank_mask:0xf
	v_mov_b32_dpp v206, v105 row_ror:2 row_mask:0xf bank_mask:0xf
	v_mov_b32_dpp v207, v106 row_ror:1 row_mask:0xf bank_mask:0xf
	v_mov_b32_dpp v208, v106 row_ror:2 row_mask:0xf bank_mask:0xf
	v_mov_b32_dpp v209, v107 row_ror:1 row_mask:0xf bank_mask:0xf
	v_mov_b32_dpp v210, v107 row_ror:2 row_mask:0xf bank_mask:0xf
	v_cndmask_b32_e64 v202, v189, v204, s[8:9]
	v_cndmask_b32_e64 v200, v212, v208, s[8:9]
	v_cndmask_b32_e64 v201, v214, v210, s[8:9]
	v_cndmask_b32_e64 v203, v193, v206, s[8:9]
	v_cndmask_b32_e64 v172, v187, v199, s[6:7]
	v_cndmask_b32_e64 v173, v191, v205, s[6:7]
	v_cndmask_b32_e64 v174, v211, v207, s[6:7]
	v_cndmask_b32_e64 v175, v213, v209, s[6:7]
	v_pk_fma_f32 v[202:203], v[136:137], v[202:203], v[140:141]
	v_pk_fma_f32 v[200:201], v[138:139], v[200:201], v[142:143]
	v_pk_fma_f32 v[172:173], v[128:129], v[172:173], v[202:203]
	v_pk_fma_f32 v[174:175], v[130:131], v[174:175], v[200:201]
	v_pk_fma_f32 v[104:105], v[104:105], v[132:133], v[172:173]
	v_pk_fma_f32 v[106:107], v[106:107], v[134:135], v[174:175]
	v_pk_mul_f32 v[82:83], v[82:83], v[186:187] op_sel_hi:[1,0]
	v_pk_mul_f32 v[80:81], v[80:81], v[186:187] op_sel_hi:[1,0]
	s_nop 1
	v_mov_b32_dpp v172, v80 row_ror:1 row_mask:0xf bank_mask:0xf
	v_mov_b32_dpp v187, v80 row_ror:2 row_mask:0xf bank_mask:0xf
	v_mov_b32_dpp v173, v81 row_ror:1 row_mask:0xf bank_mask:0xf
	v_mov_b32_dpp v189, v81 row_ror:2 row_mask:0xf bank_mask:0xf
	v_mov_b32_dpp v174, v82 row_ror:1 row_mask:0xf bank_mask:0xf
	v_mov_b32_dpp v191, v82 row_ror:2 row_mask:0xf bank_mask:0xf
	v_mov_b32_dpp v175, v83 row_ror:1 row_mask:0xf bank_mask:0xf
	v_mov_b32_dpp v193, v83 row_ror:2 row_mask:0xf bank_mask:0xf
	v_cndmask_b32_e64 v202, v204, v187, s[8:9]
	v_cndmask_b32_e64 v200, v208, v191, s[8:9]
	v_cndmask_b32_e64 v201, v210, v193, s[8:9]
	v_cndmask_b32_e64 v203, v206, v189, s[8:9]
	v_cndmask_b32_e64 v172, v199, v172, s[6:7]
	v_cndmask_b32_e64 v173, v205, v173, s[6:7]
	v_cndmask_b32_e64 v174, v207, v174, s[6:7]
	v_cndmask_b32_e64 v175, v209, v175, s[6:7]
	v_pk_fma_f32 v[136:137], v[136:137], v[202:203], v[140:141]
	v_pk_fma_f32 v[138:139], v[138:139], v[200:201], v[142:143]
	v_pk_fma_f32 v[128:129], v[128:129], v[172:173], v[136:137]
	v_pk_fma_f32 v[130:131], v[130:131], v[174:175], v[138:139]
	v_pk_fma_f32 v[80:81], v[80:81], v[132:133], v[128:129]
	v_pk_fma_f32 v[82:83], v[82:83], v[134:135], v[130:131]
	v_or_b32_e32 v128, 4, v180
	v_ashrrev_i32_e32 v129, 31, v128
	v_lshlrev_b64 v[128:129], 2, v[128:129]
	v_lshl_add_u64 v[172:173], s[42:43], 0, v[128:129]
	global_load_dwordx4 v[136:139], v[164:165], off offset:16
	v_lshl_add_u64 v[174:175], s[44:45], 0, v[128:129]
	global_load_dwordx4 v[132:135], v[172:173], off
	global_load_dwordx4 v[128:131], v[174:175], off
	global_load_dwordx4 v[140:143], v[166:167], off offset:16
	s_and_b64 vcc, exec, s[12:13]
	v_mov_b32_e32 v199, 0
	v_mov_b32_e32 v202, 0
	v_mov_b32_e32 v203, 0
	v_mov_b32_e32 v204, 0
	v_mov_b32_e32 v206, 0
	v_mov_b32_e32 v205, 0
	v_mov_b32_e32 v207, 0
	s_cbranch_vccnz .LBB0_1720
	ds_read_b128 v[198:201], v226 offset:16
	ds_read_b128 v[204:207], v179 offset:16
	v_mov_b32_e32 v202, v196
	v_mov_b32_e32 v203, v196
	s_waitcnt lgkmcnt(1)
	v_pk_mul_f32 v[208:209], v[196:197], v[198:199]
	v_mov_b32_e32 v198, v194
	v_mov_b32_e32 v199, v194
	v_pk_mul_f32 v[200:201], v[202:203], v[200:201]
	s_waitcnt lgkmcnt(0)
	v_pk_mul_f32 v[202:203], v[198:199], v[206:207]
	v_pk_mul_f32 v[198:199], v[194:195], v[204:205]
	v_cndmask_b32_e64 v205, v202, v200, s[10:11]
	v_cndmask_b32_e64 v207, v203, v201, s[10:11]
	v_cndmask_b32_e64 v204, v198, v208, s[10:11]
	v_cndmask_b32_e64 v206, v199, v209, s[10:11]

; __device__ __forceinline__ u32x4 pack8(f32x4 v0, f32x4 v1) { u32x4 w; w.x = cvt_pk_bf16(v0[0], v0[1]); w.y = cvt_pk_bf16(v0[2], v0[3]); w.z = cvt_pk_bf16(v1[0], v1[1]); w.w = cvt_pk_bf16(v1[2], v1[3]); return w; }
; __device__ __forceinline__ f32x4 gelu4(f32x4 v) { f32x2 a = gelu_pk((f32x2){v[0], v[1]}), b = gelu_pk((f32x2){v[2], v[3]}); return (f32x4){a.x, a.y, b.x, b.y}; }
; __device__ __forceinline__ f32x2 gelu_pk(f32x2 v) {
;     const f32x2 av = __builtin_elementwise_abs(v), d = av * 0.2316418882f + 1.0f;
;     f32x2 t; t.x = __builtin_amdgcn_rcpf(d.x); t.y = __builtin_amdgcn_rcpf(d.y);
;     f32x2 q = t * 0.5307027145f + (-0.7265760135f); q = q * t + 0.7107068705f; q = q * t + (-0.142248368f); q = q * t + 0.127414796f; q = q * t;
;     const f32x2 s = (v * v) * (-0.72134752044f);
;     f32x2 e; e.x = __builtin_amdgcn_exp2f(s.x); e.y = __builtin_amdgcn_exp2f(s.y);
;     const f32x2 m = v * (q * e), r = v - m;
;     f32x2 o; o.x = v.x < 0.f ? m.x : r.x; o.y = v.y < 0.f ? m.y : r.y; return o;
;     __device__ __forceinline__ void operator()(f32x4 (&acc)[2][2][4][2], const Unit& u, int wr, int wc, int fr_, int fq_) const {
;     ...
;             for (int m = 0; m < 4; ++m) { const int row = u.pm * BM + blk * 64 + m * 16 + fr;
;                 const f32x4 g0 = gelu4(acc[ai][0][m][0]), g1 = gelu4(acc[ai][0][m][1]);
;                 *(u32x4*)(ACT + (size_t)row * 5632 + jcol) = pack8(g0 * acc[ai][1][m][0], g1 * acc[ai][1][m][1]); asm volatile("" ::: "memory"); __builtin_amdgcn_sched_barrier(0); }
.LBB0_1727:
	s_or_b64 exec, exec, s[12:13]
	v_and_b32_e32 v129, 0x7fffffff, v125
	v_and_b32_e32 v128, 0x7fffffff, v124
	v_pk_fma_f32 v[128:129], v[128:129], s[58:59], 1.0 op_sel_hi:[1,0,0]
	v_lshl_add_u32 v178, s90, 8, v178
	v_rcp_f32_e32 v182, v128
	v_rcp_f32_e32 v183, v129
	v_readlane_b32 s0, v244, 55
	v_pk_mul_f32 v[186:187], v[124:125], v[124:125]
	v_cmp_gt_f32_e32 vcc, 0, v124
	v_add_u32_e32 v179, s0, v178
	s_mov_b32 s0, 0xbf3a00e3
	v_mov_b64_e32 v[128:129], s[0:1]
	v_pk_fma_f32 v[184:185], v[182:183], s[60:61], v[128:129] op_sel_hi:[1,0,0]
	v_pk_mul_f32 v[186:187], v[186:187], s[50:51] op_sel_hi:[1,0]
	v_pk_fma_f32 v[184:185], v[182:183], v[184:185], s[62:63] op_sel_hi:[1,1,0]
	v_exp_f32_e32 v186, v186
	v_exp_f32_e32 v187, v187
	v_pk_fma_f32 v[184:185], v[182:183], v[184:185], s[64:65] op_sel_hi:[1,1,0]
	v_lshl_add_u64 v[138:139], v[164:165], 0, s[54:55]
	v_pk_fma_f32 v[184:185], v[182:183], v[184:185], s[66:67] op_sel_hi:[1,1,0]
	v_lshl_add_u64 v[140:141], v[168:169], 0, s[54:55]
	v_pk_mul_f32 v[182:183], v[182:183], v[184:185]
	v_pk_mul_f32 v[184:185], v[126:127], v[126:127]
	v_pk_mul_f32 v[182:183], v[186:187], v[182:183]
	v_pk_mul_f32 v[184:185], v[184:185], s[50:51] op_sel_hi:[1,0]
	v_pk_mul_f32 v[186:187], v[124:125], v[182:183]
	v_pk_fma_f32 v[182:183], v[124:125], v[182:183], v[124:125] neg_lo:[1,0,0] neg_hi:[1,0,0]
	v_exp_f32_e32 v184, v184
	v_cndmask_b32_e32 v124, v182, v186, vcc
	v_cmp_gt_f32_e32 vcc, 0, v125
	v_and_b32_e32 v182, 0x7fffffff, v126
	v_exp_f32_e32 v185, v185
	v_cndmask_b32_e32 v125, v183, v187, vcc
	v_and_b32_e32 v183, 0x7fffffff, v127
	v_pk_fma_f32 v[182:183], v[182:183], s[58:59], 1.0 op_sel_hi:[1,0,0]
	v_cmp_gt_f32_e32 vcc, 0, v126
	v_rcp_f32_e32 v182, v182
	v_rcp_f32_e32 v183, v183
	v_pk_mul_f32 v[100:101], v[124:125], v[100:101]
	v_lshl_add_u64 v[142:143], v[170:171], 0, s[54:55]
	v_cvt_pk_bf16_f32 v100, v100, v101
	v_pk_fma_f32 v[186:187], v[182:183], s[60:61], v[128:129] op_sel_hi:[1,0,0]
	v_lshl_add_u64 v[176:177], v[166:167], 0, s[54:55]
	v_pk_fma_f32 v[186:187], v[182:183], v[186:187], s[62:63] op_sel_hi:[1,1,0]
	v_lshl_add_u64 v[130:131], v[164:165], 0, s[56:57]
	v_pk_fma_f32 v[186:187], v[182:183], v[186:187], s[64:65] op_sel_hi:[1,1,0]
	v_lshl_add_u64 v[132:133], v[168:169], 0, s[56:57]
	v_pk_fma_f32 v[186:187], v[182:183], v[186:187], s[66:67] op_sel_hi:[1,1,0]
	v_lshl_add_u64 v[134:135], v[170:171], 0, s[56:57]
	v_pk_mul_f32 v[182:183], v[182:183], v[186:187]
	v_pk_mul_f32 v[186:187], v[116:117], v[116:117]
	v_pk_mul_f32 v[182:183], v[184:185], v[182:183]
	v_pk_mul_f32 v[186:187], v[186:187], s[50:51] op_sel_hi:[1,0]
	v_pk_mul_f32 v[184:185], v[126:127], v[182:183]
	v_pk_fma_f32 v[182:183], v[126:127], v[182:183], v[126:127] neg_lo:[1,0,0] neg_hi:[1,0,0]
	v_exp_f32_e32 v186, v186
	v_cndmask_b32_e32 v126, v182, v184, vcc
	v_cmp_gt_f32_e32 vcc, 0, v127
	v_and_b32_e32 v182, 0x7fffffff, v116
	v_exp_f32_e32 v187, v187
	v_cndmask_b32_e32 v127, v183, v185, vcc
	v_and_b32_e32 v183, 0x7fffffff, v117
	v_pk_fma_f32 v[182:183], v[182:183], s[58:59], 1.0 op_sel_hi:[1,0,0]
	v_cmp_gt_f32_e32 vcc, 0, v116
	v_rcp_f32_e32 v182, v182
	v_rcp_f32_e32 v183, v183
	v_pk_mul_f32 v[102:103], v[126:127], v[102:103]
	v_lshl_add_u64 v[136:137], v[166:167], 0, s[56:57]
	v_cvt_pk_bf16_f32 v101, v102, v103
	v_pk_fma_f32 v[184:185], v[182:183], s[60:61], v[128:129] op_sel_hi:[1,0,0]
	v_pk_fma_f32 v[184:185], v[182:183], v[184:185], s[62:63] op_sel_hi:[1,1,0]
	v_pk_fma_f32 v[184:185], v[182:183], v[184:185], s[64:65] op_sel_hi:[1,1,0]
	v_pk_fma_f32 v[184:185], v[182:183], v[184:185], s[66:67] op_sel_hi:[1,1,0]
	v_pk_mul_f32 v[182:183], v[182:183], v[184:185]
	v_pk_mul_f32 v[184:185], v[118:119], v[118:119]
	v_pk_mul_f32 v[182:183], v[186:187], v[182:183]
	v_pk_mul_f32 v[184:185], v[184:185], s[50:51] op_sel_hi:[1,0]
	v_pk_mul_f32 v[186:187], v[116:117], v[182:183]
	v_pk_fma_f32 v[182:183], v[116:117], v[182:183], v[116:117] neg_lo:[1,0,0] neg_hi:[1,0,0]
	v_exp_f32_e32 v184, v184
	v_cndmask_b32_e32 v116, v182, v186, vcc
	v_cmp_gt_f32_e32 vcc, 0, v117
	v_and_b32_e32 v182, 0x7fffffff, v118
	v_exp_f32_e32 v185, v185
	v_cndmask_b32_e32 v117, v183, v187, vcc
	v_and_b32_e32 v183, 0x7fffffff, v119
	v_pk_fma_f32 v[182:183], v[182:183], s[58:59], 1.0 op_sel_hi:[1,0,0]
	v_cmp_gt_f32_e32 vcc, 0, v118
	v_rcp_f32_e32 v182, v182
	v_rcp_f32_e32 v183, v183
	v_pk_mul_f32 v[76:77], v[116:117], v[76:77]
	v_pk_fma_f32 v[186:187], v[182:183], s[60:61], v[128:129] op_sel_hi:[1,0,0]
	v_pk_fma_f32 v[186:187], v[182:183], v[186:187], s[62:63] op_sel_hi:[1,1,0]
	v_cvt_pk_bf16_f32 v102, v76, v77
	v_pk_fma_f32 v[186:187], v[182:183], v[186:187], s[64:65] op_sel_hi:[1,1,0]
	v_mov_b64_e32 v[76:77], s[22:23]
	v_pk_fma_f32 v[186:187], v[182:183], v[186:187], s[66:67] op_sel_hi:[1,1,0]
	v_mad_i64_i32 v[116:117], s[0:1], v179, s93, v[76:77]
	v_pk_mul_f32 v[182:183], v[182:183], v[186:187]
	s_nop 0
	v_pk_mul_f32 v[182:183], v[184:185], v[182:183]
	s_nop 0
	v_pk_mul_f32 v[184:185], v[118:119], v[182:183]
	v_pk_fma_f32 v[182:183], v[118:119], v[182:183], v[118:119] neg_lo:[1,0,0] neg_hi:[1,0,0]
	v_cndmask_b32_e32 v118, v182, v184, vcc
	v_cmp_gt_f32_e32 vcc, 0, v119
	s_nop 1
	v_cndmask_b32_e32 v119, v183, v185, vcc
	v_pk_mul_f32 v[78:79], v[118:119], v[78:79]
	s_nop 0
	v_cvt_pk_bf16_f32 v103, v78, v79
	v_lshlrev_b64 v[78:79], 1, v[180:181]
	v_lshl_add_u64 v[116:117], v[116:117], 0, v[78:79]
	global_store_dwordx4 v[116:117], v[100:103], off
	s_nop 1
	v_and_b32_e32 v101, 0x7fffffff, v121
	v_and_b32_e32 v100, 0x7fffffff, v120
	v_pk_fma_f32 v[100:101], v[100:101], s[58:59], 1.0 op_sel_hi:[1,0,0]
	v_pk_mul_f32 v[116:117], v[120:121], v[120:121]
	v_rcp_f32_e32 v100, v100
; __device__ __forceinline__ u32x4 pack8(f32x4 v0, f32x4 v1) { u32x4 w; w.x = cvt_pk_bf16(v0[0], v0[1]); w.y = cvt_pk_bf16(v0[2], v0[3]); w.z = cvt_pk_bf16(v1[0], v1[1]); w.w = cvt_pk_bf16(v1[2], v1[3]); return w; }
; __device__ __forceinline__ f32x4 gelu4(f32x4 v) { f32x2 a = gelu_pk((f32x2){v[0], v[1]}), b = gelu_pk((f32x2){v[2], v[3]}); return (f32x4){a.x, a.y, b.x, b.y}; }
; __device__ __forceinline__ f32x2 gelu_pk(f32x2 v) {
;     const f32x2 av = __builtin_elementwise_abs(v), d = av * 0.2316418882f + 1.0f;
;     f32x2 t; t.x = __builtin_amdgcn_rcpf(d.x); t.y = __builtin_amdgcn_rcpf(d.y);
;     f32x2 q = t * 0.5307027145f + (-0.7265760135f); q = q * t + 0.7107068705f; q = q * t + (-0.142248368f); q = q * t + 0.127414796f; q = q * t;
;     const f32x2 s = (v * v) * (-0.72134752044f);
;     f32x2 e; e.x = __builtin_amdgcn_exp2f(s.x); e.y = __builtin_amdgcn_exp2f(s.y);
;     const f32x2 m = v * (q * e), r = v - m;
;     f32x2 o; o.x = v.x < 0.f ? m.x : r.x; o.y = v.y < 0.f ? m.y : r.y; return o;
;     __device__ __forceinline__ void operator()(f32x4 (&acc)[2][2][4][2], const Unit& u, int wr, int wc, int fr_, int fq_) const {
;     ...
;             for (int m = 0; m < 4; ++m) { const int row = u.pm * BM + blk * 64 + m * 16 + fr;
;                 const f32x4 g0 = gelu4(acc[ai][0][m][0]), g1 = gelu4(acc[ai][0][m][1]);
;                 *(u32x4*)(ACT + (size_t)row * 5632 + jcol) = pack8(g0 * acc[ai][1][m][0], g1 * acc[ai][1][m][1]); asm volatile("" ::: "memory"); __builtin_amdgcn_sched_barrier(0); }
	v_rcp_f32_e32 v101, v101
	v_pk_mul_f32 v[116:117], v[116:117], s[50:51] op_sel_hi:[1,0]
	v_cmp_gt_f32_e32 vcc, 0, v120
	v_exp_f32_e32 v116, v116
	v_pk_fma_f32 v[102:103], v[100:101], s[60:61], v[128:129] op_sel_hi:[1,0,0]
	v_exp_f32_e32 v117, v117
	v_pk_fma_f32 v[102:103], v[100:101], v[102:103], s[62:63] op_sel_hi:[1,1,0]
	v_add_u32_e32 v124, 16, v179
	v_pk_fma_f32 v[102:103], v[100:101], v[102:103], s[64:65] op_sel_hi:[1,1,0]
	v_pk_fma_f32 v[102:103], v[100:101], v[102:103], s[66:67] op_sel_hi:[1,1,0]
	v_pk_mul_f32 v[100:101], v[100:101], v[102:103]
	v_pk_mul_f32 v[102:103], v[122:123], v[122:123]
	v_pk_mul_f32 v[100:101], v[116:117], v[100:101]
	v_pk_mul_f32 v[102:103], v[102:103], s[50:51] op_sel_hi:[1,0]
	v_pk_mul_f32 v[116:117], v[120:121], v[100:101]
	v_pk_fma_f32 v[100:101], v[120:121], v[100:101], v[120:121] neg_lo:[1,0,0] neg_hi:[1,0,0]
	v_exp_f32_e32 v102, v102
	v_cndmask_b32_e32 v100, v100, v116, vcc
	v_cmp_gt_f32_e32 vcc, 0, v121
	v_and_b32_e32 v116, 0x7fffffff, v122
	v_exp_f32_e32 v103, v103
	v_cndmask_b32_e32 v101, v101, v117, vcc
	v_and_b32_e32 v117, 0x7fffffff, v123
	v_pk_fma_f32 v[116:117], v[116:117], s[58:59], 1.0 op_sel_hi:[1,0,0]
	v_cmp_gt_f32_e32 vcc, 0, v122
	v_rcp_f32_e32 v116, v116
	v_rcp_f32_e32 v117, v117
	v_pk_mul_f32 v[120:121], v[112:113], v[112:113]
	v_pk_mul_f32 v[96:97], v[100:101], v[96:97]
	v_pk_mul_f32 v[120:121], v[120:121], s[50:51] op_sel_hi:[1,0]
	v_pk_fma_f32 v[118:119], v[116:117], s[60:61], v[128:129] op_sel_hi:[1,0,0]
	v_exp_f32_e32 v120, v120
	v_pk_fma_f32 v[118:119], v[116:117], v[118:119], s[62:63] op_sel_hi:[1,1,0]
	v_exp_f32_e32 v121, v121
	v_pk_fma_f32 v[118:119], v[116:117], v[118:119], s[64:65] op_sel_hi:[1,1,0]
	v_pk_fma_f32 v[118:119], v[116:117], v[118:119], s[66:67] op_sel_hi:[1,1,0]
	v_pk_mul_f32 v[116:117], v[116:117], v[118:119]
	v_pk_mul_f32 v[102:103], v[102:103], v[116:117]
	v_pk_mul_f32 v[116:117], v[122:123], v[102:103]
	v_pk_fma_f32 v[102:103], v[122:123], v[102:103], v[122:123] neg_lo:[1,0,0] neg_hi:[1,0,0]
	v_cndmask_b32_e32 v102, v102, v116, vcc
	v_cmp_gt_f32_e32 vcc, 0, v123
	v_and_b32_e32 v116, 0x7fffffff, v112
	s_nop 0
	v_cndmask_b32_e32 v103, v103, v117, vcc
	v_and_b32_e32 v117, 0x7fffffff, v113
	v_pk_fma_f32 v[116:117], v[116:117], s[58:59], 1.0 op_sel_hi:[1,0,0]
	v_cmp_gt_f32_e32 vcc, 0, v112
	v_rcp_f32_e32 v116, v116
	v_rcp_f32_e32 v117, v117
	v_pk_mul_f32 v[98:99], v[102:103], v[98:99]
	v_pk_fma_f32 v[118:119], v[116:117], s[60:61], v[128:129] op_sel_hi:[1,0,0]
	v_pk_fma_f32 v[118:119], v[116:117], v[118:119], s[62:63] op_sel_hi:[1,1,0]
	v_pk_fma_f32 v[118:119], v[116:117], v[118:119], s[64:65] op_sel_hi:[1,1,0]
	v_pk_fma_f32 v[118:119], v[116:117], v[118:119], s[66:67] op_sel_hi:[1,1,0]
	v_pk_mul_f32 v[116:117], v[116:117], v[118:119]
	v_pk_mul_f32 v[118:119], v[114:115], v[114:115]
	v_pk_mul_f32 v[116:117], v[120:121], v[116:117]
	v_pk_mul_f32 v[118:119], v[118:119], s[50:51] op_sel_hi:[1,0]
	v_pk_mul_f32 v[120:121], v[112:113], v[116:117]
	v_pk_fma_f32 v[116:117], v[112:113], v[116:117], v[112:113] neg_lo:[1,0,0] neg_hi:[1,0,0]
	v_exp_f32_e32 v118, v118
	v_cndmask_b32_e32 v112, v116, v120, vcc
	v_cmp_gt_f32_e32 vcc, 0, v113
	v_and_b32_e32 v116, 0x7fffffff, v114
	v_exp_f32_e32 v119, v119
	v_cndmask_b32_e32 v113, v117, v121, vcc
	v_and_b32_e32 v117, 0x7fffffff, v115
	v_pk_fma_f32 v[116:117], v[116:117], s[58:59], 1.0 op_sel_hi:[1,0,0]
	v_cmp_gt_f32_e32 vcc, 0, v114
	v_rcp_f32_e32 v116, v116
	v_rcp_f32_e32 v117, v117
	s_nop 0
	v_pk_fma_f32 v[120:121], v[116:117], s[60:61], v[128:129] op_sel_hi:[1,0,0]
	v_pk_fma_f32 v[120:121], v[116:117], v[120:121], s[62:63] op_sel_hi:[1,1,0]
	v_pk_fma_f32 v[120:121], v[116:117], v[120:121], s[64:65] op_sel_hi:[1,1,0]
	v_pk_fma_f32 v[120:121], v[116:117], v[120:121], s[66:67] op_sel_hi:[1,1,0]
	v_pk_mul_f32 v[116:117], v[116:117], v[120:121]
	v_pk_mul_f32 v[116:117], v[118:119], v[116:117]
	v_pk_mul_f32 v[118:119], v[114:115], v[116:117]
	v_pk_fma_f32 v[116:117], v[114:115], v[116:117], v[114:115] neg_lo:[1,0,0] neg_hi:[1,0,0]
	v_cndmask_b32_e32 v114, v116, v118, vcc
	v_cmp_gt_f32_e32 vcc, 0, v115
	s_nop 1
	v_cndmask_b32_e32 v115, v117, v119, vcc
	v_pk_mul_f32 v[100:101], v[114:115], v[74:75]
	v_pk_mul_f32 v[74:75], v[112:113], v[72:73]
	v_cvt_pk_bf16_f32 v72, v96, v97
	v_mad_i64_i32 v[96:97], s[0:1], v124, s93, v[76:77]
	v_cvt_pk_bf16_f32 v73, v98, v99
	v_cvt_pk_bf16_f32 v74, v74, v75
	v_cvt_pk_bf16_f32 v75, v100, v101
	v_lshl_add_u64 v[96:97], v[96:97], 0, v[78:79]
	global_store_dwordx4 v[96:97], v[72:75], off
	s_nop 1
	v_and_b32_e32 v73, 0x7fffffff, v105
	v_and_b32_e32 v72, 0x7fffffff, v104
	v_pk_fma_f32 v[72:73], v[72:73], s[58:59], 1.0 op_sel_hi:[1,0,0]
	v_pk_mul_f32 v[96:97], v[104:105], v[104:105]
	v_rcp_f32_e32 v72, v72
	v_rcp_f32_e32 v73, v73
	v_pk_mul_f32 v[96:97], v[96:97], s[50:51] op_sel_hi:[1,0]
	v_cmp_gt_f32_e32 vcc, 0, v104
	v_exp_f32_e32 v96, v96
	v_pk_fma_f32 v[74:75], v[72:73], s[60:61], v[128:129] op_sel_hi:[1,0,0]
	v_exp_f32_e32 v97, v97
	v_pk_fma_f32 v[74:75], v[72:73], v[74:75], s[62:63] op_sel_hi:[1,1,0]
	v_pk_mul_f32 v[100:101], v[108:109], v[108:109]
	v_pk_fma_f32 v[74:75], v[72:73], v[74:75], s[64:65] op_sel_hi:[1,1,0]
	v_pk_mul_f32 v[100:101], v[100:101], s[50:51] op_sel_hi:[1,0]
	v_pk_fma_f32 v[74:75], v[72:73], v[74:75], s[66:67] op_sel_hi:[1,1,0]
	v_exp_f32_e32 v100, v100
	v_pk_mul_f32 v[72:73], v[72:73], v[74:75]
	v_pk_mul_f32 v[74:75], v[106:107], v[106:107]
	v_pk_mul_f32 v[72:73], v[96:97], v[72:73]
	v_pk_mul_f32 v[74:75], v[74:75], s[50:51] op_sel_hi:[1,0]
	v_pk_mul_f32 v[96:97], v[104:105], v[72:73]
	v_pk_fma_f32 v[72:73], v[104:105], v[72:73], v[104:105] neg_lo:[1,0,0] neg_hi:[1,0,0]
; __device__ __forceinline__ u32x4 pack8(f32x4 v0, f32x4 v1) { u32x4 w; w.x = cvt_pk_bf16(v0[0], v0[1]); w.y = cvt_pk_bf16(v0[2], v0[3]); w.z = cvt_pk_bf16(v1[0], v1[1]); w.w = cvt_pk_bf16(v1[2], v1[3]); return w; }
; __device__ __forceinline__ f32x4 gelu4(f32x4 v) { f32x2 a = gelu_pk((f32x2){v[0], v[1]}), b = gelu_pk((f32x2){v[2], v[3]}); return (f32x4){a.x, a.y, b.x, b.y}; }
; __device__ __forceinline__ f32x2 gelu_pk(f32x2 v) {
;     const f32x2 av = __builtin_elementwise_abs(v), d = av * 0.2316418882f + 1.0f;
;     f32x2 t; t.x = __builtin_amdgcn_rcpf(d.x); t.y = __builtin_amdgcn_rcpf(d.y);
;     f32x2 q = t * 0.5307027145f + (-0.7265760135f); q = q * t + 0.7107068705f; q = q * t + (-0.142248368f); q = q * t + 0.127414796f; q = q * t;
;     const f32x2 s = (v * v) * (-0.72134752044f);
;     f32x2 e; e.x = __builtin_amdgcn_exp2f(s.x); e.y = __builtin_amdgcn_exp2f(s.y);
;     const f32x2 m = v * (q * e), r = v - m;
;     f32x2 o; o.x = v.x < 0.f ? m.x : r.x; o.y = v.y < 0.f ? m.y : r.y; return o;
;     __device__ __forceinline__ void operator()(f32x4 (&acc)[2][2][4][2], const Unit& u, int wr, int wc, int fr_, int fq_) const {
;     ...
;             for (int m = 0; m < 4; ++m) { const int row = u.pm * BM + blk * 64 + m * 16 + fr;
;                 const f32x4 g0 = gelu4(acc[ai][0][m][0]), g1 = gelu4(acc[ai][0][m][1]);
;                 *(u32x4*)(ACT + (size_t)row * 5632 + jcol) = pack8(g0 * acc[ai][1][m][0], g1 * acc[ai][1][m][1]); asm volatile("" ::: "memory"); __builtin_amdgcn_sched_barrier(0); }
	v_exp_f32_e32 v74, v74
	v_cndmask_b32_e32 v72, v72, v96, vcc
	v_cmp_gt_f32_e32 vcc, 0, v105
	v_and_b32_e32 v96, 0x7fffffff, v106
	v_exp_f32_e32 v75, v75
	v_cndmask_b32_e32 v73, v73, v97, vcc
	v_and_b32_e32 v97, 0x7fffffff, v107
	v_pk_fma_f32 v[96:97], v[96:97], s[58:59], 1.0 op_sel_hi:[1,0,0]
	v_cmp_gt_f32_e32 vcc, 0, v106
	v_rcp_f32_e32 v96, v96
	v_rcp_f32_e32 v97, v97
	v_exp_f32_e32 v101, v101
	v_add_u32_e32 v112, 32, v179
	v_pk_mul_f32 v[72:73], v[72:73], v[88:89]
	v_pk_fma_f32 v[98:99], v[96:97], s[60:61], v[128:129] op_sel_hi:[1,0,0]
	v_pk_fma_f32 v[98:99], v[96:97], v[98:99], s[62:63] op_sel_hi:[1,1,0]
	v_pk_fma_f32 v[98:99], v[96:97], v[98:99], s[64:65] op_sel_hi:[1,1,0]
	v_pk_fma_f32 v[98:99], v[96:97], v[98:99], s[66:67] op_sel_hi:[1,1,0]
	v_pk_mul_f32 v[96:97], v[96:97], v[98:99]
	v_pk_mul_f32 v[74:75], v[74:75], v[96:97]
	v_pk_mul_f32 v[96:97], v[106:107], v[74:75]
	v_pk_fma_f32 v[74:75], v[106:107], v[74:75], v[106:107] neg_lo:[1,0,0] neg_hi:[1,0,0]
	v_cndmask_b32_e32 v74, v74, v96, vcc
	v_cmp_gt_f32_e32 vcc, 0, v107
	v_and_b32_e32 v96, 0x7fffffff, v108
	s_nop 0
	v_cndmask_b32_e32 v75, v75, v97, vcc
	v_and_b32_e32 v97, 0x7fffffff, v109
	v_pk_fma_f32 v[96:97], v[96:97], s[58:59], 1.0 op_sel_hi:[1,0,0]
	v_cmp_gt_f32_e32 vcc, 0, v108
	v_rcp_f32_e32 v96, v96
	v_rcp_f32_e32 v97, v97
	v_pk_mul_f32 v[74:75], v[74:75], v[90:91]
	v_pk_fma_f32 v[98:99], v[96:97], s[60:61], v[128:129] op_sel_hi:[1,0,0]
	v_pk_fma_f32 v[98:99], v[96:97], v[98:99], s[62:63] op_sel_hi:[1,1,0]
	v_pk_fma_f32 v[98:99], v[96:97], v[98:99], s[64:65] op_sel_hi:[1,1,0]
	v_pk_fma_f32 v[98:99], v[96:97], v[98:99], s[66:67] op_sel_hi:[1,1,0]
	v_pk_mul_f32 v[96:97], v[96:97], v[98:99]
	v_pk_mul_f32 v[98:99], v[110:111], v[110:111]
	v_pk_mul_f32 v[96:97], v[100:101], v[96:97]
	v_pk_mul_f32 v[98:99], v[98:99], s[50:51] op_sel_hi:[1,0]
	v_pk_mul_f32 v[100:101], v[108:109], v[96:97]
	v_pk_fma_f32 v[96:97], v[108:109], v[96:97], v[108:109] neg_lo:[1,0,0] neg_hi:[1,0,0]
	v_exp_f32_e32 v98, v98
	v_cndmask_b32_e32 v96, v96, v100, vcc
	v_cmp_gt_f32_e32 vcc, 0, v109
	v_and_b32_e32 v100, 0x7fffffff, v110
	v_exp_f32_e32 v99, v99
	v_cndmask_b32_e32 v97, v97, v101, vcc
	v_and_b32_e32 v101, 0x7fffffff, v111
	v_pk_fma_f32 v[100:101], v[100:101], s[58:59], 1.0 op_sel_hi:[1,0,0]
	v_cmp_gt_f32_e32 vcc, 0, v110
	v_rcp_f32_e32 v100, v100
	v_rcp_f32_e32 v101, v101
	s_nop 0
	v_pk_fma_f32 v[102:103], v[100:101], s[60:61], v[128:129] op_sel_hi:[1,0,0]
	v_pk_fma_f32 v[102:103], v[100:101], v[102:103], s[62:63] op_sel_hi:[1,1,0]
	v_pk_fma_f32 v[102:103], v[100:101], v[102:103], s[64:65] op_sel_hi:[1,1,0]
	v_pk_fma_f32 v[102:103], v[100:101], v[102:103], s[66:67] op_sel_hi:[1,1,0]
	v_pk_mul_f32 v[100:101], v[100:101], v[102:103]
	v_pk_mul_f32 v[98:99], v[98:99], v[100:101]
	v_pk_mul_f32 v[100:101], v[110:111], v[98:99]
	v_pk_fma_f32 v[98:99], v[110:111], v[98:99], v[110:111] neg_lo:[1,0,0] neg_hi:[1,0,0]
	v_cndmask_b32_e32 v98, v98, v100, vcc
	v_cmp_gt_f32_e32 vcc, 0, v111
	s_nop 1
	v_cndmask_b32_e32 v99, v99, v101, vcc
	v_pk_mul_f32 v[88:89], v[98:99], v[70:71]
	v_pk_mul_f32 v[70:71], v[96:97], v[68:69]
	v_cvt_pk_bf16_f32 v68, v72, v73
	v_mad_i64_i32 v[72:73], s[0:1], v112, s93, v[76:77]
	v_cvt_pk_bf16_f32 v69, v74, v75
	v_cvt_pk_bf16_f32 v70, v70, v71
	v_cvt_pk_bf16_f32 v71, v88, v89
	v_lshl_add_u64 v[72:73], v[72:73], 0, v[78:79]
	global_store_dwordx4 v[72:73], v[68:71], off
	s_nop 1
	v_and_b32_e32 v69, 0x7fffffff, v81
	v_and_b32_e32 v68, 0x7fffffff, v80
	v_pk_fma_f32 v[68:69], v[68:69], s[58:59], 1.0 op_sel_hi:[1,0,0]
	v_pk_mul_f32 v[72:73], v[80:81], v[80:81]
	v_rcp_f32_e32 v68, v68
	v_rcp_f32_e32 v69, v69
	v_pk_mul_f32 v[72:73], v[72:73], s[50:51] op_sel_hi:[1,0]
	v_cmp_gt_f32_e32 vcc, 0, v80
	v_exp_f32_e32 v72, v72
	v_pk_fma_f32 v[70:71], v[68:69], s[60:61], v[128:129] op_sel_hi:[1,0,0]
	v_exp_f32_e32 v73, v73
	v_pk_fma_f32 v[70:71], v[68:69], v[70:71], s[62:63] op_sel_hi:[1,1,0]
	v_add_u32_e32 v88, 48, v179
	v_pk_fma_f32 v[70:71], v[68:69], v[70:71], s[64:65] op_sel_hi:[1,1,0]
	v_pk_fma_f32 v[70:71], v[68:69], v[70:71], s[66:67] op_sel_hi:[1,1,0]
	v_pk_mul_f32 v[68:69], v[68:69], v[70:71]
	v_pk_mul_f32 v[70:71], v[82:83], v[82:83]
	v_pk_mul_f32 v[68:69], v[72:73], v[68:69]
	v_pk_mul_f32 v[70:71], v[70:71], s[50:51] op_sel_hi:[1,0]
	v_pk_mul_f32 v[72:73], v[80:81], v[68:69]
	v_pk_fma_f32 v[68:69], v[80:81], v[68:69], v[80:81] neg_lo:[1,0,0] neg_hi:[1,0,0]
	v_exp_f32_e32 v70, v70
	v_cndmask_b32_e32 v68, v68, v72, vcc
	v_cmp_gt_f32_e32 vcc, 0, v81
	v_and_b32_e32 v72, 0x7fffffff, v82
	v_exp_f32_e32 v71, v71
	v_cndmask_b32_e32 v69, v69, v73, vcc
	v_and_b32_e32 v73, 0x7fffffff, v83
	v_pk_fma_f32 v[72:73], v[72:73], s[58:59], 1.0 op_sel_hi:[1,0,0]
	v_cmp_gt_f32_e32 vcc, 0, v82
	v_rcp_f32_e32 v72, v72
	v_rcp_f32_e32 v73, v73
	v_pk_mul_f32 v[80:81], v[92:93], v[92:93]
	v_pk_mul_f32 v[68:69], v[68:69], v[84:85]
	v_pk_mul_f32 v[80:81], v[80:81], s[50:51] op_sel_hi:[1,0]
	v_pk_fma_f32 v[74:75], v[72:73], s[60:61], v[128:129] op_sel_hi:[1,0,0]
	v_exp_f32_e32 v80, v80
	v_pk_fma_f32 v[74:75], v[72:73], v[74:75], s[62:63] op_sel_hi:[1,1,0]
	v_exp_f32_e32 v81, v81
	v_pk_fma_f32 v[74:75], v[72:73], v[74:75], s[64:65] op_sel_hi:[1,1,0]
	v_pk_fma_f32 v[74:75], v[72:73], v[74:75], s[66:67] op_sel_hi:[1,1,0]
	v_pk_mul_f32 v[72:73], v[72:73], v[74:75]
	v_pk_mul_f32 v[70:71], v[70:71], v[72:73]
	v_pk_mul_f32 v[72:73], v[82:83], v[70:71]
	v_pk_fma_f32 v[70:71], v[82:83], v[70:71], v[82:83] neg_lo:[1,0,0] neg_hi:[1,0,0]
	v_cndmask_b32_e32 v70, v70, v72, vcc
	v_cmp_gt_f32_e32 vcc, 0, v83
	v_and_b32_e32 v72, 0x7fffffff, v92
	s_nop 0
	v_cndmask_b32_e32 v71, v71, v73, vcc
	v_and_b32_e32 v73, 0x7fffffff, v93
; #define PG8_LAS __attribute__((address_space(3)))
; __device__ __forceinline__ f32x2 gelu_pk(f32x2 v) {
;     const f32x2 av = __builtin_elementwise_abs(v), d = av * 0.2316418882f + 1.0f;
;     f32x2 t; t.x = __builtin_amdgcn_rcpf(d.x); t.y = __builtin_amdgcn_rcpf(d.y);
;     f32x2 q = t * 0.5307027145f + (-0.7265760135f); q = q * t + 0.7107068705f; q = q * t + (-0.142248368f); q = q * t + 0.127414796f; q = q * t;
;     const f32x2 s = (v * v) * (-0.72134752044f);
;     f32x2 e; e.x = __builtin_amdgcn_exp2f(s.x); e.y = __builtin_amdgcn_exp2f(s.y);
;     const f32x2 m = v * (q * e), r = v - m;
;     f32x2 o; o.x = v.x < 0.f ? m.x : r.x; o.y = v.y < 0.f ? m.y : r.y; return o;
;     __device__ __forceinline__ void operator()(f32x4 (&acc)[2][2][4][2], const Unit& u, int wr, int wc, int fr_, int fq_) const {
;     ...
;             for (int m = 0; m < 4; ++m) rsr[m] = rsL[blk * 64 + m * 16 + fr];
;             const float rs14 = blk ? rsL[blk * 64 - 2] : 0.f, rs15 = blk ? rsL[blk * 64 - 1] : 0.f;
; #pragma unroll
;             for (int bj = 0; bj < 2; ++bj)
; #pragma unroll
;                 for (int n = 0; n < 2; ++n) {
;                     const int ct = bj * HALF + wc * 32 + 8 * fq + 4 * n;
;                     const int cidx = bj * 5632 + jcol + 4 * n;
;                     const f32x4 w0 = *(const f32x4*)(cw + cidx), w1 = *(const f32x4*)(cw + 11264 + cidx), w2 = *(const f32x4*)(cw + 22528 + cidx), b4 = *(const f32x4*)(cb + cidx);
;                     f32x4 pR1 = (f32x4){0.f, 0.f, 0.f, 0.f}, pR2 = pR1;
;                     if (blk) { const f32x4 h14 = *(const PG8_LAS f32x4*)(hal + ((blk - 1) * 2 + 0) * 256 + ct) * rs14, h15 = *(const PG8_LAS f32x4*)(hal + ((blk - 1) * 2 + 1) * 256 + ct) * rs15;
;                         pR1 = h15; pR2 = (fr == 0) ? h14 : h15; }
; #pragma unroll
;                     for (int m = 0; m < 4; ++m) {
;                         const f32x4 U = acc[ai][bj][m][n] * rsr[m];
;                         f32x4 R1, R2;
; #pragma unroll
;                         for (int i = 0; i < 4; ++i) { R1[i] = dpp_ror1(U[i]); R2[i] = dpp_ror2(U[i]); }
;                         const f32x4 U1 = (fr >= 1) ? R1 : pR1, U2 = (fr >= 2) ? R2 : pR2;
;                         const f32x4 C = b4 + w0 * U2 + w1 * U1 + w2 * U;
;                         acc[ai][bj][m][n] = C; pR1 = R1; pR2 = R2;
	v_pk_fma_f32 v[72:73], v[72:73], s[58:59], 1.0 op_sel_hi:[1,0,0]
	v_cmp_gt_f32_e32 vcc, 0, v92
	v_rcp_f32_e32 v72, v72
	v_rcp_f32_e32 v73, v73
	v_pk_mul_f32 v[70:71], v[70:71], v[86:87]
	v_pk_fma_f32 v[74:75], v[72:73], s[60:61], v[128:129] op_sel_hi:[1,0,0]
	v_pk_fma_f32 v[74:75], v[72:73], v[74:75], s[62:63] op_sel_hi:[1,1,0]
	v_pk_fma_f32 v[74:75], v[72:73], v[74:75], s[64:65] op_sel_hi:[1,1,0]
	v_pk_fma_f32 v[74:75], v[72:73], v[74:75], s[66:67] op_sel_hi:[1,1,0]
	v_pk_mul_f32 v[72:73], v[72:73], v[74:75]
	v_pk_mul_f32 v[74:75], v[94:95], v[94:95]
	v_pk_mul_f32 v[72:73], v[80:81], v[72:73]
	v_pk_mul_f32 v[74:75], v[74:75], s[50:51] op_sel_hi:[1,0]
	v_pk_mul_f32 v[80:81], v[92:93], v[72:73]
	v_pk_fma_f32 v[72:73], v[92:93], v[72:73], v[92:93] neg_lo:[1,0,0] neg_hi:[1,0,0]
	v_exp_f32_e32 v74, v74
	v_cndmask_b32_e32 v72, v72, v80, vcc
	v_cmp_gt_f32_e32 vcc, 0, v93
	v_and_b32_e32 v80, 0x7fffffff, v94
	v_exp_f32_e32 v75, v75
	v_cndmask_b32_e32 v73, v73, v81, vcc
	v_and_b32_e32 v81, 0x7fffffff, v95
	v_pk_fma_f32 v[80:81], v[80:81], s[58:59], 1.0 op_sel_hi:[1,0,0]
	v_cmp_gt_f32_e32 vcc, 0, v94
	v_rcp_f32_e32 v80, v80
	v_rcp_f32_e32 v81, v81
	s_nop 0
	v_pk_fma_f32 v[82:83], v[80:81], s[60:61], v[128:129] op_sel_hi:[1,0,0]
	v_pk_fma_f32 v[82:83], v[80:81], v[82:83], s[62:63] op_sel_hi:[1,1,0]
	v_pk_fma_f32 v[82:83], v[80:81], v[82:83], s[64:65] op_sel_hi:[1,1,0]
	v_pk_fma_f32 v[82:83], v[80:81], v[82:83], s[66:67] op_sel_hi:[1,1,0]
	v_pk_mul_f32 v[80:81], v[80:81], v[82:83]
	v_pk_mul_f32 v[74:75], v[74:75], v[80:81]
	v_pk_mul_f32 v[80:81], v[94:95], v[74:75]
	v_pk_fma_f32 v[74:75], v[94:95], v[74:75], v[94:95] neg_lo:[1,0,0] neg_hi:[1,0,0]
	v_cndmask_b32_e32 v74, v74, v80, vcc
	v_cmp_gt_f32_e32 vcc, 0, v95
	s_nop 1
	v_cndmask_b32_e32 v75, v75, v81, vcc
	v_pk_mul_f32 v[74:75], v[74:75], v[66:67]
	v_pk_mul_f32 v[66:67], v[72:73], v[64:65]
	v_cvt_pk_bf16_f32 v64, v68, v69
	v_mad_i64_i32 v[68:69], s[0:1], v88, s93, v[76:77]
	v_cvt_pk_bf16_f32 v65, v70, v71
	v_cvt_pk_bf16_f32 v66, v66, v67
	v_cvt_pk_bf16_f32 v67, v74, v75
	v_lshl_add_u64 v[68:69], v[68:69], 0, v[78:79]
	global_store_dwordx4 v[68:69], v[64:67], off
	global_load_dwordx4 v[80:83], v[166:167], off
	global_load_dwordx4 v[84:87], v[164:165], off
	global_load_dwordx4 v[88:91], v[168:169], off
	global_load_dwordx4 v[92:95], v[170:171], off
	v_mov_b32_e32 v65, s96
	v_add_u32_e32 v71, s97, v154
	ds_read_b64 v[66:67], v65
	ds_read_b128 v[96:99], v71
	v_add_u32_e32 v64, s89, v225
	v_add_u32_e32 v73, s14, v154
	ds_read_b128 v[100:103], v73
	ds_read2_b32 v[68:69], v64 offset1:16
	ds_read2_b32 v[64:65], v64 offset0:32 offset1:48
	s_waitcnt lgkmcnt(3)
	v_pk_mul_f32 v[74:75], v[66:67], v[98:99] op_sel_hi:[0,1]
	v_pk_mul_f32 v[96:97], v[66:67], v[96:97] op_sel_hi:[0,1]
	s_waitcnt lgkmcnt(2)
	v_pk_mul_f32 v[98:99], v[66:67], v[102:103] op_sel:[1,0]
	v_pk_mul_f32 v[100:101], v[66:67], v[100:101] op_sel:[1,0]
	v_cndmask_b32_e64 v70, v99, v75, s[10:11]
	v_cndmask_b32_e64 v72, v98, v74, s[10:11]
	v_cndmask_b32_e64 v102, v101, v97, s[10:11]
	v_cndmask_b32_e64 v103, v100, v96, s[10:11]
	s_waitcnt lgkmcnt(1)
	v_pk_mul_f32 v[62:63], v[62:63], v[68:69] op_sel_hi:[1,0]
	v_pk_mul_f32 v[60:61], v[60:61], v[68:69] op_sel_hi:[1,0]
	s_nop 0
	s_nop 1
	v_mov_b32_dpp v104, v60 row_ror:1 row_mask:0xf bank_mask:0xf
	v_mov_b32_dpp v105, v60 row_ror:2 row_mask:0xf bank_mask:0xf
	v_mov_b32_dpp v106, v61 row_ror:1 row_mask:0xf bank_mask:0xf
	v_mov_b32_dpp v107, v61 row_ror:2 row_mask:0xf bank_mask:0xf
	v_mov_b32_dpp v108, v62 row_ror:1 row_mask:0xf bank_mask:0xf
	v_mov_b32_dpp v109, v62 row_ror:2 row_mask:0xf bank_mask:0xf
	v_mov_b32_dpp v110, v63 row_ror:1 row_mask:0xf bank_mask:0xf
	v_mov_b32_dpp v111, v63 row_ror:2 row_mask:0xf bank_mask:0xf
	v_cndmask_b32_e64 v96, v100, v104, s[6:7]
	v_cndmask_b32_e64 v74, v98, v108, s[6:7]
	v_cndmask_b32_e64 v75, v99, v110, s[6:7]
	v_cndmask_b32_e64 v97, v101, v106, s[6:7]
	v_cndmask_b32_e64 v98, v72, v109, s[8:9]
	v_cndmask_b32_e64 v99, v70, v111, s[8:9]
	v_cndmask_b32_e64 v100, v103, v105, s[8:9]
	v_cndmask_b32_e64 v101, v102, v107, s[8:9]
	s_waitcnt vmcnt(2)
	v_pk_fma_f32 v[98:99], v[86:87], v[98:99], v[82:83]
	v_pk_fma_f32 v[100:101], v[84:85], v[100:101], v[80:81]
	s_waitcnt vmcnt(1)
	v_pk_fma_f32 v[74:75], v[90:91], v[74:75], v[98:99]
	v_pk_fma_f32 v[96:97], v[88:89], v[96:97], v[100:101]
	s_waitcnt vmcnt(0)
	v_pk_fma_f32 v[62:63], v[62:63], v[94:95], v[74:75]
	v_pk_fma_f32 v[60:61], v[60:61], v[92:93], v[96:97]
	v_mov_b32_e32 v70, v69
	v_pk_mul_f32 v[58:59], v[58:59], v[70:71] op_sel_hi:[1,0]
	v_pk_mul_f32 v[56:57], v[56:57], v[70:71] op_sel_hi:[1,0]
	s_nop 1
	v_mov_b32_dpp v69, v56 row_ror:1 row_mask:0xf bank_mask:0xf
	v_mov_b32_dpp v72, v56 row_ror:2 row_mask:0xf bank_mask:0xf
	v_mov_b32_dpp v102, v57 row_ror:1 row_mask:0xf bank_mask:0xf
	v_mov_b32_dpp v103, v57 row_ror:2 row_mask:0xf bank_mask:0xf
	v_mov_b32_dpp v112, v58 row_ror:1 row_mask:0xf bank_mask:0xf
	v_mov_b32_dpp v113, v58 row_ror:2 row_mask:0xf bank_mask:0xf
	v_mov_b32_dpp v114, v59 row_ror:1 row_mask:0xf bank_mask:0xf
	v_mov_b32_dpp v115, v59 row_ror:2 row_mask:0xf bank_mask:0xf
	v_cndmask_b32_e64 v100, v105, v72, s[8:9]
	v_cndmask_b32_e64 v98, v109, v113, s[8:9]
	v_cndmask_b32_e64 v99, v111, v115, s[8:9]
	v_cndmask_b32_e64 v101, v107, v103, s[8:9]
	v_cndmask_b32_e64 v74, v108, v112, s[6:7]
	v_cndmask_b32_e64 v75, v110, v114, s[6:7]
	v_cndmask_b32_e64 v96, v104, v69, s[6:7]
	v_cndmask_b32_e64 v97, v106, v102, s[6:7]
	v_pk_fma_f32 v[98:99], v[86:87], v[98:99], v[82:83]
	v_pk_fma_f32 v[100:101], v[84:85], v[100:101], v[80:81]
	v_pk_fma_f32 v[74:75], v[90:91], v[74:75], v[98:99]
	v_pk_fma_f32 v[96:97], v[88:89], v[96:97], v[100:101]
	v_pk_fma_f32 v[58:59], v[58:59], v[94:95], v[74:75]
	v_pk_fma_f32 v[56:57], v[56:57], v[92:93], v[96:97]
	s_nop 0
	s_waitcnt lgkmcnt(0)
; #define PG8_LAS __attribute__((address_space(3)))
; __device__ __forceinline__ float dpp_ror1(float x) { float r; asm volatile("s_nop 1\n\tv_mov_b32_dpp %0, %1 row_ror:1 row_mask:0xf bank_mask:0xf" : "=&v"(r) : "v"(x)); return r; }
; __device__ __forceinline__ float dpp_ror2(float x) { float r; asm volatile("s_nop 1\n\tv_mov_b32_dpp %0, %1 row_ror:2 row_mask:0xf bank_mask:0xf" : "=&v"(r) : "v"(x)); return r; }
;     __device__ __forceinline__ void operator()(f32x4 (&acc)[2][2][4][2], const Unit& u, int wr, int wc, int fr_, int fq_) const {
;     ...
; #pragma unroll
;             for (int bj = 0; bj < 2; ++bj)
; #pragma unroll
;                 for (int n = 0; n < 2; ++n) {
;                     const int ct = bj * HALF + wc * 32 + 8 * fq + 4 * n;
;                     const int cidx = bj * 5632 + jcol + 4 * n;
;                     const f32x4 w0 = *(const f32x4*)(cw + cidx), w1 = *(const f32x4*)(cw + 11264 + cidx), w2 = *(const f32x4*)(cw + 22528 + cidx), b4 = *(const f32x4*)(cb + cidx);
;                     f32x4 pR1 = (f32x4){0.f, 0.f, 0.f, 0.f}, pR2 = pR1;
;                     if (blk) { const f32x4 h14 = *(const PG8_LAS f32x4*)(hal + ((blk - 1) * 2 + 0) * 256 + ct) * rs14, h15 = *(const PG8_LAS f32x4*)(hal + ((blk - 1) * 2 + 1) * 256 + ct) * rs15;
;                         pR1 = h15; pR2 = (fr == 0) ? h14 : h15; }
; #pragma unroll
;                     for (int m = 0; m < 4; ++m) {
;                         const f32x4 U = acc[ai][bj][m][n] * rsr[m];
;                         f32x4 R1, R2;
; #pragma unroll
;                         for (int i = 0; i < 4; ++i) { R1[i] = dpp_ror1(U[i]); R2[i] = dpp_ror2(U[i]); }
;                         const f32x4 U1 = (fr >= 1) ? R1 : pR1, U2 = (fr >= 2) ? R2 : pR2;
;                         const f32x4 C = b4 + w0 * U2 + w1 * U1 + w2 * U;
;                         acc[ai][bj][m][n] = C; pR1 = R1; pR2 = R2;
;                         asm volatile("" : "+v"(acc[ai][bj][m][n]));
;                         __builtin_amdgcn_sched_barrier(0);
;                     }
	v_pk_mul_f32 v[54:55], v[54:55], v[64:65] op_sel_hi:[1,0]
	v_pk_mul_f32 v[52:53], v[52:53], v[64:65] op_sel_hi:[1,0]
	s_nop 0
	s_nop 1
	v_mov_b32_dpp v104, v52 row_ror:1 row_mask:0xf bank_mask:0xf
	v_mov_b32_dpp v105, v52 row_ror:2 row_mask:0xf bank_mask:0xf
	v_mov_b32_dpp v106, v53 row_ror:1 row_mask:0xf bank_mask:0xf
	v_mov_b32_dpp v107, v53 row_ror:2 row_mask:0xf bank_mask:0xf
	v_mov_b32_dpp v108, v54 row_ror:1 row_mask:0xf bank_mask:0xf
	v_mov_b32_dpp v109, v54 row_ror:2 row_mask:0xf bank_mask:0xf
	v_mov_b32_dpp v110, v55 row_ror:1 row_mask:0xf bank_mask:0xf
	v_mov_b32_dpp v111, v55 row_ror:2 row_mask:0xf bank_mask:0xf
	v_cndmask_b32_e64 v100, v72, v105, s[8:9]
	v_cndmask_b32_e64 v98, v113, v109, s[8:9]
	v_cndmask_b32_e64 v99, v115, v111, s[8:9]
	v_cndmask_b32_e64 v101, v103, v107, s[8:9]
	v_cndmask_b32_e64 v74, v112, v108, s[6:7]
	v_cndmask_b32_e64 v75, v114, v110, s[6:7]
	v_cndmask_b32_e64 v96, v69, v104, s[6:7]
	v_cndmask_b32_e64 v97, v102, v106, s[6:7]
	v_pk_fma_f32 v[98:99], v[86:87], v[98:99], v[82:83]
	v_pk_fma_f32 v[100:101], v[84:85], v[100:101], v[80:81]
	v_pk_fma_f32 v[74:75], v[90:91], v[74:75], v[98:99]
	v_pk_fma_f32 v[96:97], v[88:89], v[96:97], v[100:101]
	v_pk_fma_f32 v[54:55], v[54:55], v[94:95], v[74:75]
	v_pk_fma_f32 v[52:53], v[52:53], v[92:93], v[96:97]
	v_mov_b32_e32 v72, v65
	v_pk_mul_f32 v[50:51], v[50:51], v[72:73] op_sel_hi:[1,0]
	v_pk_mul_f32 v[48:49], v[48:49], v[72:73] op_sel_hi:[1,0]
	s_nop 1
	v_mov_b32_dpp v65, v48 row_ror:1 row_mask:0xf bank_mask:0xf
	v_mov_b32_dpp v69, v48 row_ror:2 row_mask:0xf bank_mask:0xf
	v_mov_b32_dpp v97, v49 row_ror:1 row_mask:0xf bank_mask:0xf
	v_mov_b32_dpp v101, v49 row_ror:2 row_mask:0xf bank_mask:0xf
	v_mov_b32_dpp v74, v50 row_ror:1 row_mask:0xf bank_mask:0xf
	v_mov_b32_dpp v98, v50 row_ror:2 row_mask:0xf bank_mask:0xf
	v_mov_b32_dpp v75, v51 row_ror:1 row_mask:0xf bank_mask:0xf
	v_mov_b32_dpp v99, v51 row_ror:2 row_mask:0xf bank_mask:0xf
	v_cndmask_b32_e64 v100, v105, v69, s[8:9]
	v_cndmask_b32_e64 v98, v109, v98, s[8:9]
	v_cndmask_b32_e64 v99, v111, v99, s[8:9]
	v_cndmask_b32_e64 v101, v107, v101, s[8:9]
	v_cndmask_b32_e64 v74, v108, v74, s[6:7]
	v_cndmask_b32_e64 v75, v110, v75, s[6:7]
	v_cndmask_b32_e64 v96, v104, v65, s[6:7]
	v_cndmask_b32_e64 v97, v106, v97, s[6:7]
	v_pk_fma_f32 v[82:83], v[86:87], v[98:99], v[82:83]
	v_pk_fma_f32 v[80:81], v[84:85], v[100:101], v[80:81]
	v_pk_fma_f32 v[74:75], v[90:91], v[74:75], v[82:83]
	v_pk_fma_f32 v[80:81], v[88:89], v[96:97], v[80:81]
	v_pk_fma_f32 v[50:51], v[50:51], v[94:95], v[74:75]
	v_pk_fma_f32 v[48:49], v[48:49], v[92:93], v[80:81]
	s_nop 0
	global_load_dwordx4 v[80:83], v[164:165], off offset:16
	global_load_dwordx4 v[84:87], v[166:167], off offset:16
	global_load_dwordx4 v[88:91], v[172:173], off
	global_load_dwordx4 v[92:95], v[174:175], off
	v_pk_mul_f32 v[74:75], v[46:47], v[68:69] op_sel_hi:[1,0]
	v_pk_mul_f32 v[100:101], v[44:45], v[68:69] op_sel_hi:[1,0]
	ds_read_b128 v[44:47], v71 offset:16
	ds_read_b128 v[96:99], v73 offset:16
	s_nop 1
	v_mov_b32_dpp v65, v100 row_ror:1 row_mask:0xf bank_mask:0xf
	v_mov_b32_dpp v69, v100 row_ror:2 row_mask:0xf bank_mask:0xf
	v_mov_b32_dpp v102, v101 row_ror:1 row_mask:0xf bank_mask:0xf
	s_waitcnt lgkmcnt(1)
	v_pk_mul_f32 v[46:47], v[66:67], v[46:47] op_sel_hi:[0,1]
	v_pk_mul_f32 v[44:45], v[66:67], v[44:45] op_sel_hi:[0,1]
	s_waitcnt lgkmcnt(0)
	v_pk_mul_f32 v[98:99], v[66:67], v[98:99] op_sel:[1,0]
	v_pk_mul_f32 v[96:97], v[66:67], v[96:97] op_sel:[1,0]
	v_cndmask_b32_e64 v108, v99, v47, s[10:11]
	v_cndmask_b32_e64 v109, v98, v46, s[10:11]
	v_cndmask_b32_e64 v110, v96, v44, s[10:11]
	v_cndmask_b32_e64 v111, v97, v45, s[10:11]
	s_nop 1
	v_mov_b32_dpp v103, v101 row_ror:2 row_mask:0xf bank_mask:0xf
	v_mov_b32_dpp v104, v74 row_ror:1 row_mask:0xf bank_mask:0xf
	v_mov_b32_dpp v105, v74 row_ror:2 row_mask:0xf bank_mask:0xf
	v_mov_b32_dpp v106, v75 row_ror:1 row_mask:0xf bank_mask:0xf
	v_mov_b32_dpp v107, v75 row_ror:2 row_mask:0xf bank_mask:0xf
	v_cndmask_b32_e64 v47, v97, v102, s[6:7]
	v_cndmask_b32_e64 v44, v98, v104, s[6:7]
	v_cndmask_b32_e64 v45, v99, v106, s[6:7]
	v_cndmask_b32_e64 v46, v96, v65, s[6:7]
	v_cndmask_b32_e64 v96, v109, v105, s[8:9]
	v_cndmask_b32_e64 v97, v108, v107, s[8:9]
	v_cndmask_b32_e64 v99, v111, v103, s[8:9]
	v_cndmask_b32_e64 v98, v110, v69, s[8:9]
	s_waitcnt vmcnt(2)
	v_pk_fma_f32 v[96:97], v[82:83], v[96:97], v[86:87]
	v_pk_fma_f32 v[98:99], v[80:81], v[98:99], v[84:85]
	s_waitcnt vmcnt(1)
	v_pk_fma_f32 v[44:45], v[90:91], v[44:45], v[96:97]
	v_pk_fma_f32 v[96:97], v[88:89], v[46:47], v[98:99]
	s_waitcnt vmcnt(0)
; #define PG8_LAS __attribute__((address_space(3)))
; __device__ __forceinline__ float dpp_ror1(float x) { float r; asm volatile("s_nop 1\n\tv_mov_b32_dpp %0, %1 row_ror:1 row_mask:0xf bank_mask:0xf" : "=&v"(r) : "v"(x)); return r; }
; __device__ __forceinline__ float dpp_ror2(float x) { float r; asm volatile("s_nop 1\n\tv_mov_b32_dpp %0, %1 row_ror:2 row_mask:0xf bank_mask:0xf" : "=&v"(r) : "v"(x)); return r; }
;     __device__ __forceinline__ void operator()(f32x4 (&acc)[2][2][4][2], const Unit& u, int wr, int wc, int fr_, int fq_) const {
;     ...
; #pragma unroll
;             for (int bj = 0; bj < 2; ++bj)
; #pragma unroll
;                 for (int n = 0; n < 2; ++n) {
;                     const int ct = bj * HALF + wc * 32 + 8 * fq + 4 * n;
;                     const int cidx = bj * 5632 + jcol + 4 * n;
;                     const f32x4 w0 = *(const f32x4*)(cw + cidx), w1 = *(const f32x4*)(cw + 11264 + cidx), w2 = *(const f32x4*)(cw + 22528 + cidx), b4 = *(const f32x4*)(cb + cidx);
;                     f32x4 pR1 = (f32x4){0.f, 0.f, 0.f, 0.f}, pR2 = pR1;
;                     if (blk) { const f32x4 h14 = *(const PG8_LAS f32x4*)(hal + ((blk - 1) * 2 + 0) * 256 + ct) * rs14, h15 = *(const PG8_LAS f32x4*)(hal + ((blk - 1) * 2 + 1) * 256 + ct) * rs15;
;                         pR1 = h15; pR2 = (fr == 0) ? h14 : h15; }
; #pragma unroll
;                     for (int m = 0; m < 4; ++m) {
;                         const f32x4 U = acc[ai][bj][m][n] * rsr[m];
;                         f32x4 R1, R2;
; #pragma unroll
;                         for (int i = 0; i < 4; ++i) { R1[i] = dpp_ror1(U[i]); R2[i] = dpp_ror2(U[i]); }
;                         const f32x4 U1 = (fr >= 1) ? R1 : pR1, U2 = (fr >= 2) ? R2 : pR2;
;                         const f32x4 C = b4 + w0 * U2 + w1 * U1 + w2 * U;
;                         acc[ai][bj][m][n] = C; pR1 = R1; pR2 = R2;
;                         asm volatile("" : "+v"(acc[ai][bj][m][n]));
;                         __builtin_amdgcn_sched_barrier(0);
;                     }
	v_pk_fma_f32 v[46:47], v[74:75], v[94:95], v[44:45]
	v_pk_fma_f32 v[44:45], v[100:101], v[92:93], v[96:97]
	v_pk_mul_f32 v[42:43], v[42:43], v[70:71] op_sel_hi:[1,0]
	v_pk_mul_f32 v[40:41], v[40:41], v[70:71] op_sel_hi:[1,0]
	s_nop 1
	v_mov_b32_dpp v108, v40 row_ror:1 row_mask:0xf bank_mask:0xf
	v_mov_b32_dpp v109, v40 row_ror:2 row_mask:0xf bank_mask:0xf
	v_mov_b32_dpp v110, v41 row_ror:1 row_mask:0xf bank_mask:0xf
	v_mov_b32_dpp v111, v41 row_ror:2 row_mask:0xf bank_mask:0xf
	v_mov_b32_dpp v112, v42 row_ror:1 row_mask:0xf bank_mask:0xf
	v_mov_b32_dpp v113, v42 row_ror:2 row_mask:0xf bank_mask:0xf
	v_mov_b32_dpp v114, v43 row_ror:1 row_mask:0xf bank_mask:0xf
	v_mov_b32_dpp v115, v43 row_ror:2 row_mask:0xf bank_mask:0xf
	v_cndmask_b32_e64 v100, v69, v109, s[8:9]
	v_cndmask_b32_e64 v98, v105, v113, s[8:9]
	v_cndmask_b32_e64 v99, v107, v115, s[8:9]
	v_cndmask_b32_e64 v101, v103, v111, s[8:9]
	v_cndmask_b32_e64 v74, v104, v112, s[6:7]
	v_cndmask_b32_e64 v75, v106, v114, s[6:7]
	v_cndmask_b32_e64 v96, v65, v108, s[6:7]
	v_cndmask_b32_e64 v97, v102, v110, s[6:7]
	v_pk_fma_f32 v[98:99], v[82:83], v[98:99], v[86:87]
	v_pk_fma_f32 v[100:101], v[80:81], v[100:101], v[84:85]
	v_pk_fma_f32 v[74:75], v[90:91], v[74:75], v[98:99]
	v_pk_fma_f32 v[96:97], v[88:89], v[96:97], v[100:101]
	v_pk_fma_f32 v[42:43], v[42:43], v[94:95], v[74:75]
	v_pk_fma_f32 v[40:41], v[40:41], v[92:93], v[96:97]
	v_pk_mul_f32 v[38:39], v[38:39], v[64:65] op_sel_hi:[1,0]
	v_pk_mul_f32 v[36:37], v[36:37], v[64:65] op_sel_hi:[1,0]
	s_nop 1
	v_mov_b32_dpp v65, v36 row_ror:1 row_mask:0xf bank_mask:0xf
	v_mov_b32_dpp v69, v36 row_ror:2 row_mask:0xf bank_mask:0xf
	v_mov_b32_dpp v102, v37 row_ror:1 row_mask:0xf bank_mask:0xf
	v_mov_b32_dpp v103, v37 row_ror:2 row_mask:0xf bank_mask:0xf
	v_mov_b32_dpp v104, v38 row_ror:1 row_mask:0xf bank_mask:0xf
	v_mov_b32_dpp v105, v38 row_ror:2 row_mask:0xf bank_mask:0xf
	v_mov_b32_dpp v106, v39 row_ror:1 row_mask:0xf bank_mask:0xf
	v_mov_b32_dpp v107, v39 row_ror:2 row_mask:0xf bank_mask:0xf
	v_cndmask_b32_e64 v100, v109, v69, s[8:9]
	v_cndmask_b32_e64 v98, v113, v105, s[8:9]
	v_cndmask_b32_e64 v99, v115, v107, s[8:9]
	v_cndmask_b32_e64 v101, v111, v103, s[8:9]
	v_cndmask_b32_e64 v74, v112, v104, s[6:7]
	v_cndmask_b32_e64 v75, v114, v106, s[6:7]
	v_cndmask_b32_e64 v96, v108, v65, s[6:7]
	v_cndmask_b32_e64 v97, v110, v102, s[6:7]
	v_pk_fma_f32 v[98:99], v[82:83], v[98:99], v[86:87]
	v_pk_fma_f32 v[100:101], v[80:81], v[100:101], v[84:85]
	v_pk_fma_f32 v[74:75], v[90:91], v[74:75], v[98:99]
	v_pk_fma_f32 v[96:97], v[88:89], v[96:97], v[100:101]
	v_pk_fma_f32 v[38:39], v[38:39], v[94:95], v[74:75]
	v_pk_fma_f32 v[36:37], v[36:37], v[92:93], v[96:97]
	v_pk_mul_f32 v[34:35], v[34:35], v[72:73] op_sel_hi:[1,0]
	v_pk_mul_f32 v[32:33], v[32:33], v[72:73] op_sel_hi:[1,0]
	s_nop 1
	v_mov_b32_dpp v96, v32 row_ror:1 row_mask:0xf bank_mask:0xf
	v_mov_b32_dpp v100, v32 row_ror:2 row_mask:0xf bank_mask:0xf
	v_mov_b32_dpp v97, v33 row_ror:1 row_mask:0xf bank_mask:0xf
	v_mov_b32_dpp v101, v33 row_ror:2 row_mask:0xf bank_mask:0xf
	v_mov_b32_dpp v74, v34 row_ror:1 row_mask:0xf bank_mask:0xf
	v_mov_b32_dpp v98, v34 row_ror:2 row_mask:0xf bank_mask:0xf
	v_mov_b32_dpp v75, v35 row_ror:1 row_mask:0xf bank_mask:0xf
	v_mov_b32_dpp v99, v35 row_ror:2 row_mask:0xf bank_mask:0xf
	v_cndmask_b32_e64 v100, v69, v100, s[8:9]
	v_cndmask_b32_e64 v98, v105, v98, s[8:9]
	v_cndmask_b32_e64 v99, v107, v99, s[8:9]
	v_cndmask_b32_e64 v101, v103, v101, s[8:9]
	v_cndmask_b32_e64 v74, v104, v74, s[6:7]
	v_cndmask_b32_e64 v75, v106, v75, s[6:7]
	v_cndmask_b32_e64 v96, v65, v96, s[6:7]
	v_cndmask_b32_e64 v97, v102, v97, s[6:7]
	v_pk_fma_f32 v[82:83], v[82:83], v[98:99], v[86:87]
	v_pk_fma_f32 v[80:81], v[80:81], v[100:101], v[84:85]
	v_pk_fma_f32 v[74:75], v[90:91], v[74:75], v[82:83]
	v_pk_fma_f32 v[80:81], v[88:89], v[96:97], v[80:81]
	v_pk_fma_f32 v[34:35], v[34:35], v[94:95], v[74:75]
	v_pk_fma_f32 v[32:33], v[32:33], v[92:93], v[80:81]
	s_nop 0
	global_load_dwordx4 v[80:83], v[176:177], off
	global_load_dwordx4 v[84:87], v[138:139], off
	global_load_dwordx4 v[88:91], v[140:141], off
	global_load_dwordx4 v[92:95], v[142:143], off
	v_pk_mul_f32 v[74:75], v[30:31], v[68:69] op_sel_hi:[1,0]
	v_pk_mul_f32 v[100:101], v[28:29], v[68:69] op_sel_hi:[1,0]
	ds_read_b128 v[28:31], v71 offset:512
	ds_read_b128 v[96:99], v73 offset:512
	s_nop 1
	v_mov_b32_dpp v65, v100 row_ror:1 row_mask:0xf bank_mask:0xf
	v_mov_b32_dpp v69, v100 row_ror:2 row_mask:0xf bank_mask:0xf
	v_mov_b32_dpp v102, v101 row_ror:1 row_mask:0xf bank_mask:0xf
	s_waitcnt lgkmcnt(1)
	v_pk_mul_f32 v[30:31], v[66:67], v[30:31] op_sel_hi:[0,1]
	v_pk_mul_f32 v[28:29], v[66:67], v[28:29] op_sel_hi:[0,1]
	s_waitcnt lgkmcnt(0)
	v_pk_mul_f32 v[98:99], v[66:67], v[98:99] op_sel:[1,0]
	v_pk_mul_f32 v[96:97], v[66:67], v[96:97] op_sel:[1,0]
	v_cndmask_b32_e64 v108, v99, v31, s[10:11]
	v_cndmask_b32_e64 v109, v98, v30, s[10:11]
	v_cndmask_b32_e64 v110, v96, v28, s[10:11]
	v_cndmask_b32_e64 v111, v97, v29, s[10:11]
	s_nop 1
	v_mov_b32_dpp v103, v101 row_ror:2 row_mask:0xf bank_mask:0xf
	v_mov_b32_dpp v104, v74 row_ror:1 row_mask:0xf bank_mask:0xf
	v_mov_b32_dpp v105, v74 row_ror:2 row_mask:0xf bank_mask:0xf
	v_mov_b32_dpp v106, v75 row_ror:1 row_mask:0xf bank_mask:0xf
	v_mov_b32_dpp v107, v75 row_ror:2 row_mask:0xf bank_mask:0xf
	v_cndmask_b32_e64 v31, v97, v102, s[6:7]
	v_cndmask_b32_e64 v28, v98, v104, s[6:7]
	v_cndmask_b32_e64 v29, v99, v106, s[6:7]
	v_cndmask_b32_e64 v30, v96, v65, s[6:7]
	v_cndmask_b32_e64 v96, v109, v105, s[8:9]
	v_cndmask_b32_e64 v97, v108, v107, s[8:9]
	v_cndmask_b32_e64 v99, v111, v103, s[8:9]
	v_cndmask_b32_e64 v98, v110, v69, s[8:9]
	s_waitcnt vmcnt(2)
; #define PG8_LAS __attribute__((address_space(3)))
; __device__ __forceinline__ float dpp_ror1(float x) { float r; asm volatile("s_nop 1\n\tv_mov_b32_dpp %0, %1 row_ror:1 row_mask:0xf bank_mask:0xf" : "=&v"(r) : "v"(x)); return r; }
; __device__ __forceinline__ float dpp_ror2(float x) { float r; asm volatile("s_nop 1\n\tv_mov_b32_dpp %0, %1 row_ror:2 row_mask:0xf bank_mask:0xf" : "=&v"(r) : "v"(x)); return r; }
;     __device__ __forceinline__ void operator()(f32x4 (&acc)[2][2][4][2], const Unit& u, int wr, int wc, int fr_, int fq_) const {
;     ...
; #pragma unroll
;             for (int bj = 0; bj < 2; ++bj)
; #pragma unroll
;                 for (int n = 0; n < 2; ++n) {
;                     const int ct = bj * HALF + wc * 32 + 8 * fq + 4 * n;
;                     const int cidx = bj * 5632 + jcol + 4 * n;
;                     const f32x4 w0 = *(const f32x4*)(cw + cidx), w1 = *(const f32x4*)(cw + 11264 + cidx), w2 = *(const f32x4*)(cw + 22528 + cidx), b4 = *(const f32x4*)(cb + cidx);
;                     f32x4 pR1 = (f32x4){0.f, 0.f, 0.f, 0.f}, pR2 = pR1;
;                     if (blk) { const f32x4 h14 = *(const PG8_LAS f32x4*)(hal + ((blk - 1) * 2 + 0) * 256 + ct) * rs14, h15 = *(const PG8_LAS f32x4*)(hal + ((blk - 1) * 2 + 1) * 256 + ct) * rs15;
;                         pR1 = h15; pR2 = (fr == 0) ? h14 : h15; }
; #pragma unroll
;                     for (int m = 0; m < 4; ++m) {
;                         const f32x4 U = acc[ai][bj][m][n] * rsr[m];
;                         f32x4 R1, R2;
; #pragma unroll
;                         for (int i = 0; i < 4; ++i) { R1[i] = dpp_ror1(U[i]); R2[i] = dpp_ror2(U[i]); }
;                         const f32x4 U1 = (fr >= 1) ? R1 : pR1, U2 = (fr >= 2) ? R2 : pR2;
;                         const f32x4 C = b4 + w0 * U2 + w1 * U1 + w2 * U;
;                         acc[ai][bj][m][n] = C; pR1 = R1; pR2 = R2;
;                         asm volatile("" : "+v"(acc[ai][bj][m][n]));
;                         __builtin_amdgcn_sched_barrier(0);
;                     }
	v_pk_fma_f32 v[96:97], v[86:87], v[96:97], v[82:83]
	v_pk_fma_f32 v[98:99], v[84:85], v[98:99], v[80:81]
	s_waitcnt vmcnt(1)
	v_pk_fma_f32 v[28:29], v[90:91], v[28:29], v[96:97]
	v_pk_fma_f32 v[96:97], v[88:89], v[30:31], v[98:99]
	s_waitcnt vmcnt(0)
	v_pk_fma_f32 v[30:31], v[74:75], v[94:95], v[28:29]
	v_pk_fma_f32 v[28:29], v[100:101], v[92:93], v[96:97]
	v_pk_mul_f32 v[26:27], v[26:27], v[70:71] op_sel_hi:[1,0]
	v_pk_mul_f32 v[24:25], v[24:25], v[70:71] op_sel_hi:[1,0]
	s_nop 1
	v_mov_b32_dpp v108, v24 row_ror:1 row_mask:0xf bank_mask:0xf
	v_mov_b32_dpp v109, v24 row_ror:2 row_mask:0xf bank_mask:0xf
	v_mov_b32_dpp v110, v25 row_ror:1 row_mask:0xf bank_mask:0xf
	v_mov_b32_dpp v111, v25 row_ror:2 row_mask:0xf bank_mask:0xf
	v_mov_b32_dpp v112, v26 row_ror:1 row_mask:0xf bank_mask:0xf
	v_mov_b32_dpp v113, v26 row_ror:2 row_mask:0xf bank_mask:0xf
	v_mov_b32_dpp v114, v27 row_ror:1 row_mask:0xf bank_mask:0xf
	v_mov_b32_dpp v115, v27 row_ror:2 row_mask:0xf bank_mask:0xf
	v_cndmask_b32_e64 v100, v69, v109, s[8:9]
	v_cndmask_b32_e64 v98, v105, v113, s[8:9]
	v_cndmask_b32_e64 v99, v107, v115, s[8:9]
	v_cndmask_b32_e64 v101, v103, v111, s[8:9]
	v_cndmask_b32_e64 v74, v104, v112, s[6:7]
	v_cndmask_b32_e64 v75, v106, v114, s[6:7]
	v_cndmask_b32_e64 v96, v65, v108, s[6:7]
	v_cndmask_b32_e64 v97, v102, v110, s[6:7]
	v_pk_fma_f32 v[98:99], v[86:87], v[98:99], v[82:83]
	v_pk_fma_f32 v[100:101], v[84:85], v[100:101], v[80:81]
	v_pk_fma_f32 v[74:75], v[90:91], v[74:75], v[98:99]
	v_pk_fma_f32 v[96:97], v[88:89], v[96:97], v[100:101]
	v_pk_fma_f32 v[26:27], v[26:27], v[94:95], v[74:75]
	v_pk_fma_f32 v[24:25], v[24:25], v[92:93], v[96:97]
	v_pk_mul_f32 v[22:23], v[22:23], v[64:65] op_sel_hi:[1,0]
	v_pk_mul_f32 v[20:21], v[20:21], v[64:65] op_sel_hi:[1,0]
	s_nop 1
	v_mov_b32_dpp v65, v20 row_ror:1 row_mask:0xf bank_mask:0xf
	v_mov_b32_dpp v69, v20 row_ror:2 row_mask:0xf bank_mask:0xf
	v_mov_b32_dpp v102, v21 row_ror:1 row_mask:0xf bank_mask:0xf
	v_mov_b32_dpp v103, v21 row_ror:2 row_mask:0xf bank_mask:0xf
	v_mov_b32_dpp v104, v22 row_ror:1 row_mask:0xf bank_mask:0xf
	v_mov_b32_dpp v105, v22 row_ror:2 row_mask:0xf bank_mask:0xf
	v_mov_b32_dpp v106, v23 row_ror:1 row_mask:0xf bank_mask:0xf
	v_mov_b32_dpp v107, v23 row_ror:2 row_mask:0xf bank_mask:0xf
	v_cndmask_b32_e64 v100, v109, v69, s[8:9]
	v_cndmask_b32_e64 v98, v113, v105, s[8:9]
	v_cndmask_b32_e64 v99, v115, v107, s[8:9]
	v_cndmask_b32_e64 v101, v111, v103, s[8:9]
	v_cndmask_b32_e64 v74, v112, v104, s[6:7]
	v_cndmask_b32_e64 v75, v114, v106, s[6:7]
	v_cndmask_b32_e64 v96, v108, v65, s[6:7]
	v_cndmask_b32_e64 v97, v110, v102, s[6:7]
	v_pk_fma_f32 v[98:99], v[86:87], v[98:99], v[82:83]
	v_pk_fma_f32 v[100:101], v[84:85], v[100:101], v[80:81]
	v_pk_fma_f32 v[74:75], v[90:91], v[74:75], v[98:99]
	v_pk_fma_f32 v[96:97], v[88:89], v[96:97], v[100:101]
	v_pk_fma_f32 v[22:23], v[22:23], v[94:95], v[74:75]
	v_pk_fma_f32 v[20:21], v[20:21], v[92:93], v[96:97]
	v_pk_mul_f32 v[18:19], v[18:19], v[72:73] op_sel_hi:[1,0]
	v_pk_mul_f32 v[16:17], v[16:17], v[72:73] op_sel_hi:[1,0]
	s_nop 1
	v_mov_b32_dpp v96, v16 row_ror:1 row_mask:0xf bank_mask:0xf
	v_mov_b32_dpp v100, v16 row_ror:2 row_mask:0xf bank_mask:0xf
	v_mov_b32_dpp v97, v17 row_ror:1 row_mask:0xf bank_mask:0xf
	v_mov_b32_dpp v101, v17 row_ror:2 row_mask:0xf bank_mask:0xf
	v_mov_b32_dpp v74, v18 row_ror:1 row_mask:0xf bank_mask:0xf
	v_mov_b32_dpp v98, v18 row_ror:2 row_mask:0xf bank_mask:0xf
	v_mov_b32_dpp v75, v19 row_ror:1 row_mask:0xf bank_mask:0xf
	v_mov_b32_dpp v99, v19 row_ror:2 row_mask:0xf bank_mask:0xf
	v_cndmask_b32_e64 v100, v69, v100, s[8:9]
	v_cndmask_b32_e64 v98, v105, v98, s[8:9]
	v_cndmask_b32_e64 v99, v107, v99, s[8:9]
	v_cndmask_b32_e64 v101, v103, v101, s[8:9]
	v_cndmask_b32_e64 v74, v104, v74, s[6:7]
	v_cndmask_b32_e64 v75, v106, v75, s[6:7]
	v_cndmask_b32_e64 v96, v65, v96, s[6:7]
	v_cndmask_b32_e64 v97, v102, v97, s[6:7]
	v_pk_fma_f32 v[82:83], v[86:87], v[98:99], v[82:83]
	v_pk_fma_f32 v[80:81], v[84:85], v[100:101], v[80:81]
	v_pk_fma_f32 v[74:75], v[90:91], v[74:75], v[82:83]
	v_pk_fma_f32 v[80:81], v[88:89], v[96:97], v[80:81]
	v_pk_fma_f32 v[18:19], v[18:19], v[94:95], v[74:75]
	v_pk_fma_f32 v[16:17], v[16:17], v[92:93], v[80:81]
	s_nop 0
	global_load_dwordx4 v[80:83], v[136:137], off
	global_load_dwordx4 v[84:87], v[130:131], off
	global_load_dwordx4 v[88:91], v[132:133], off
	global_load_dwordx4 v[92:95], v[134:135], off
	v_pk_mul_f32 v[74:75], v[14:15], v[68:69] op_sel_hi:[1,0]
	v_pk_mul_f32 v[68:69], v[12:13], v[68:69] op_sel_hi:[1,0]
	ds_read_b128 v[12:15], v71 offset:528
	ds_read_b128 v[96:99], v73 offset:528
	s_nop 1
	v_mov_b32_dpp v65, v68 row_ror:1 row_mask:0xf bank_mask:0xf
	v_mov_b32_dpp v73, v68 row_ror:2 row_mask:0xf bank_mask:0xf
	v_mov_b32_dpp v71, v69 row_ror:1 row_mask:0xf bank_mask:0xf
	s_waitcnt lgkmcnt(1)
	v_pk_mul_f32 v[14:15], v[66:67], v[14:15] op_sel_hi:[0,1]
	v_pk_mul_f32 v[12:13], v[66:67], v[12:13] op_sel_hi:[0,1]
	s_waitcnt lgkmcnt(0)
	v_pk_mul_f32 v[98:99], v[66:67], v[98:99] op_sel:[1,0]
	v_pk_mul_f32 v[66:67], v[66:67], v[96:97] op_sel:[1,0]
	v_cndmask_b32_e64 v96, v99, v15, s[10:11]
	v_cndmask_b32_e64 v97, v98, v14, s[10:11]
	v_cndmask_b32_e64 v105, v66, v12, s[10:11]
	v_cndmask_b32_e64 v106, v67, v13, s[10:11]
	s_nop 1
	v_mov_b32_dpp v100, v69 row_ror:2 row_mask:0xf bank_mask:0xf
	v_mov_b32_dpp v101, v74 row_ror:1 row_mask:0xf bank_mask:0xf
	v_mov_b32_dpp v102, v74 row_ror:2 row_mask:0xf bank_mask:0xf
	v_mov_b32_dpp v103, v75 row_ror:1 row_mask:0xf bank_mask:0xf
	v_mov_b32_dpp v104, v75 row_ror:2 row_mask:0xf bank_mask:0xf
	v_cndmask_b32_e64 v15, v67, v71, s[6:7]
	v_cndmask_b32_e64 v14, v66, v65, s[6:7]
	v_cndmask_b32_e64 v66, v97, v102, s[8:9]
	v_cndmask_b32_e64 v67, v96, v104, s[8:9]
	v_cndmask_b32_e64 v97, v106, v100, s[8:9]
	v_cndmask_b32_e64 v96, v105, v73, s[8:9]
	v_cndmask_b32_e64 v12, v98, v101, s[6:7]
	v_cndmask_b32_e64 v13, v99, v103, s[6:7]
	s_waitcnt vmcnt(2)
; __device__ __forceinline__ u32x4 pack8(f32x4 v0, f32x4 v1) { u32x4 w; w.x = cvt_pk_bf16(v0[0], v0[1]); w.y = cvt_pk_bf16(v0[2], v0[3]); w.z = cvt_pk_bf16(v1[0], v1[1]); w.w = cvt_pk_bf16(v1[2], v1[3]); return w; }
; __device__ __forceinline__ f32x4 gelu4(f32x4 v) { f32x2 a = gelu_pk((f32x2){v[0], v[1]}), b = gelu_pk((f32x2){v[2], v[3]}); return (f32x4){a.x, a.y, b.x, b.y}; }
; __device__ __forceinline__ float dpp_ror1(float x) { float r; asm volatile("s_nop 1\n\tv_mov_b32_dpp %0, %1 row_ror:1 row_mask:0xf bank_mask:0xf" : "=&v"(r) : "v"(x)); return r; }
; __device__ __forceinline__ f32x2 gelu_pk(f32x2 v) {
;     const f32x2 av = __builtin_elementwise_abs(v), d = av * 0.2316418882f + 1.0f;
;     f32x2 t; t.x = __builtin_amdgcn_rcpf(d.x); t.y = __builtin_amdgcn_rcpf(d.y);
;     f32x2 q = t * 0.5307027145f + (-0.7265760135f); q = q * t + 0.7107068705f; q = q * t + (-0.142248368f); q = q * t + 0.127414796f; q = q * t;
;     const f32x2 s = (v * v) * (-0.72134752044f);
;     f32x2 e; e.x = __builtin_amdgcn_exp2f(s.x); e.y = __builtin_amdgcn_exp2f(s.y);
;     const f32x2 m = v * (q * e), r = v - m;
;     f32x2 o; o.x = v.x < 0.f ? m.x : r.x; o.y = v.y < 0.f ? m.y : r.y; return o;
;     __device__ __forceinline__ void operator()(f32x4 (&acc)[2][2][4][2], const Unit& u, int wr, int wc, int fr_, int fq_) const {
;     ...
;                     for (int m = 0; m < 4; ++m) {
;                         const f32x4 U = acc[ai][bj][m][n] * rsr[m];
;                         f32x4 R1, R2;
; #pragma unroll
;                         for (int i = 0; i < 4; ++i) { R1[i] = dpp_ror1(U[i]); R2[i] = dpp_ror2(U[i]); }
;                         const f32x4 U1 = (fr >= 1) ? R1 : pR1, U2 = (fr >= 2) ? R2 : pR2;
;                         const f32x4 C = b4 + w0 * U2 + w1 * U1 + w2 * U;
;                         acc[ai][bj][m][n] = C; pR1 = R1; pR2 = R2;
;                         asm volatile("" : "+v"(acc[ai][bj][m][n]));
;                         __builtin_amdgcn_sched_barrier(0);
;                     }
;     ...
;             for (int m = 0; m < 4; ++m) { const int row = u.pm * BM + blk * 64 + m * 16 + fr;
;                 const f32x4 g0 = gelu4(acc[ai][0][m][0]), g1 = gelu4(acc[ai][0][m][1]);
;                 *(u32x4*)(ACT + (size_t)row * 5632 + jcol) = pack8(g0 * acc[ai][1][m][0], g1 * acc[ai][1][m][1]); asm volatile("" ::: "memory"); __builtin_amdgcn_sched_barrier(0); }
	v_pk_fma_f32 v[66:67], v[86:87], v[66:67], v[82:83]
	v_pk_fma_f32 v[96:97], v[84:85], v[96:97], v[80:81]
	s_waitcnt vmcnt(1)
	v_pk_fma_f32 v[12:13], v[90:91], v[12:13], v[66:67]
	v_pk_fma_f32 v[66:67], v[88:89], v[14:15], v[96:97]
	s_waitcnt vmcnt(0)
	v_pk_fma_f32 v[14:15], v[74:75], v[94:95], v[12:13]
	v_pk_fma_f32 v[12:13], v[68:69], v[92:93], v[66:67]
	v_pk_mul_f32 v[10:11], v[10:11], v[70:71] op_sel_hi:[1,0]
	v_pk_mul_f32 v[8:9], v[8:9], v[70:71] op_sel_hi:[1,0]
	s_nop 1
	v_mov_b32_dpp v96, v8 row_ror:1 row_mask:0xf bank_mask:0xf
	v_mov_b32_dpp v97, v8 row_ror:2 row_mask:0xf bank_mask:0xf
	v_mov_b32_dpp v98, v9 row_ror:1 row_mask:0xf bank_mask:0xf
	v_mov_b32_dpp v99, v9 row_ror:2 row_mask:0xf bank_mask:0xf
	v_mov_b32_dpp v105, v10 row_ror:1 row_mask:0xf bank_mask:0xf
	v_mov_b32_dpp v106, v10 row_ror:2 row_mask:0xf bank_mask:0xf
	v_mov_b32_dpp v107, v11 row_ror:1 row_mask:0xf bank_mask:0xf
	v_mov_b32_dpp v108, v11 row_ror:2 row_mask:0xf bank_mask:0xf
	v_cndmask_b32_e64 v69, v71, v98, s[6:7]
	v_cndmask_b32_e64 v70, v102, v106, s[8:9]
	v_cndmask_b32_e64 v71, v104, v108, s[8:9]
	v_cndmask_b32_e64 v74, v73, v97, s[8:9]
	v_cndmask_b32_e64 v75, v100, v99, s[8:9]
	v_cndmask_b32_e64 v66, v101, v105, s[6:7]
	v_cndmask_b32_e64 v67, v103, v107, s[6:7]
	v_cndmask_b32_e64 v68, v65, v96, s[6:7]
	v_pk_fma_f32 v[70:71], v[86:87], v[70:71], v[82:83]
	v_pk_fma_f32 v[74:75], v[84:85], v[74:75], v[80:81]
	v_pk_fma_f32 v[66:67], v[90:91], v[66:67], v[70:71]
	v_pk_fma_f32 v[68:69], v[88:89], v[68:69], v[74:75]
	v_pk_fma_f32 v[10:11], v[10:11], v[94:95], v[66:67]
	v_pk_fma_f32 v[8:9], v[8:9], v[92:93], v[68:69]
	v_pk_mul_f32 v[6:7], v[6:7], v[64:65] op_sel_hi:[1,0]
	v_pk_mul_f32 v[4:5], v[4:5], v[64:65] op_sel_hi:[1,0]
	s_nop 1
	v_mov_b32_dpp v73, v4 row_ror:1 row_mask:0xf bank_mask:0xf
	v_mov_b32_dpp v74, v4 row_ror:2 row_mask:0xf bank_mask:0xf
	v_mov_b32_dpp v75, v5 row_ror:1 row_mask:0xf bank_mask:0xf
	v_mov_b32_dpp v100, v5 row_ror:2 row_mask:0xf bank_mask:0xf
	v_mov_b32_dpp v101, v6 row_ror:1 row_mask:0xf bank_mask:0xf
	v_mov_b32_dpp v102, v6 row_ror:2 row_mask:0xf bank_mask:0xf
	v_mov_b32_dpp v103, v7 row_ror:1 row_mask:0xf bank_mask:0xf
	v_mov_b32_dpp v104, v7 row_ror:2 row_mask:0xf bank_mask:0xf
	v_cndmask_b32_e64 v70, v97, v74, s[8:9]
	v_cndmask_b32_e64 v68, v106, v102, s[8:9]
	v_cndmask_b32_e64 v69, v108, v104, s[8:9]
	v_cndmask_b32_e64 v71, v99, v100, s[8:9]
	v_cndmask_b32_e64 v64, v105, v101, s[6:7]
	v_cndmask_b32_e64 v65, v107, v103, s[6:7]
	v_cndmask_b32_e64 v66, v96, v73, s[6:7]
	v_cndmask_b32_e64 v67, v98, v75, s[6:7]
	v_pk_fma_f32 v[68:69], v[86:87], v[68:69], v[82:83]
	v_pk_fma_f32 v[70:71], v[84:85], v[70:71], v[80:81]
	v_pk_fma_f32 v[64:65], v[90:91], v[64:65], v[68:69]
	v_pk_fma_f32 v[66:67], v[88:89], v[66:67], v[70:71]
	v_pk_fma_f32 v[6:7], v[6:7], v[94:95], v[64:65]
	v_pk_fma_f32 v[4:5], v[4:5], v[92:93], v[66:67]
	v_pk_mul_f32 v[2:3], v[2:3], v[72:73] op_sel_hi:[1,0]
	v_pk_mul_f32 v[0:1], v[0:1], v[72:73] op_sel_hi:[1,0]
	s_nop 1
	v_mov_b32_dpp v66, v0 row_ror:1 row_mask:0xf bank_mask:0xf
	v_mov_b32_dpp v70, v0 row_ror:2 row_mask:0xf bank_mask:0xf
	v_mov_b32_dpp v67, v1 row_ror:1 row_mask:0xf bank_mask:0xf
	v_mov_b32_dpp v71, v1 row_ror:2 row_mask:0xf bank_mask:0xf
	v_mov_b32_dpp v64, v2 row_ror:1 row_mask:0xf bank_mask:0xf
	v_mov_b32_dpp v68, v2 row_ror:2 row_mask:0xf bank_mask:0xf
	v_mov_b32_dpp v65, v3 row_ror:1 row_mask:0xf bank_mask:0xf
	v_mov_b32_dpp v69, v3 row_ror:2 row_mask:0xf bank_mask:0xf
	v_cndmask_b32_e64 v70, v74, v70, s[8:9]
	v_cndmask_b32_e64 v68, v102, v68, s[8:9]
	v_cndmask_b32_e64 v69, v104, v69, s[8:9]
	v_cndmask_b32_e64 v71, v100, v71, s[8:9]
	v_cndmask_b32_e64 v64, v101, v64, s[6:7]
	v_cndmask_b32_e64 v65, v103, v65, s[6:7]
	v_cndmask_b32_e64 v66, v73, v66, s[6:7]
	v_cndmask_b32_e64 v67, v75, v67, s[6:7]
	v_pk_fma_f32 v[68:69], v[86:87], v[68:69], v[82:83]
	v_pk_fma_f32 v[70:71], v[84:85], v[70:71], v[80:81]
	v_pk_fma_f32 v[64:65], v[90:91], v[64:65], v[68:69]
	v_pk_fma_f32 v[66:67], v[88:89], v[66:67], v[70:71]
	v_pk_fma_f32 v[2:3], v[2:3], v[94:95], v[64:65]
	v_pk_fma_f32 v[0:1], v[0:1], v[92:93], v[66:67]
	v_and_b32_e32 v67, 0x7fffffff, v61
	v_and_b32_e32 v66, 0x7fffffff, v60
	v_pk_fma_f32 v[66:67], v[66:67], s[58:59], 1.0 op_sel_hi:[1,0,0]
	v_pk_mul_f32 v[70:71], v[60:61], v[60:61]
	v_rcp_f32_e32 v66, v66
	v_rcp_f32_e32 v67, v67
	v_pk_mul_f32 v[70:71], v[70:71], s[50:51] op_sel_hi:[1,0]
	v_cmp_gt_f32_e32 vcc, 0, v60
	v_exp_f32_e32 v70, v70
	v_pk_fma_f32 v[68:69], v[66:67], s[60:61], v[128:129] op_sel_hi:[1,0,0]
	v_exp_f32_e32 v71, v71
	v_pk_fma_f32 v[68:69], v[66:67], v[68:69], s[62:63] op_sel_hi:[1,1,0]
	v_readlane_b32 s0, v244, 59
	v_pk_fma_f32 v[68:69], v[66:67], v[68:69], s[64:65] op_sel_hi:[1,1,0]
	s_nop 0
	v_pk_fma_f32 v[68:69], v[66:67], v[68:69], s[66:67] op_sel_hi:[1,1,0]
	v_add_u32_e32 v64, s0, v178
	v_pk_mul_f32 v[66:67], v[66:67], v[68:69]
	v_pk_mul_f32 v[68:69], v[62:63], v[62:63]
	v_pk_mul_f32 v[66:67], v[70:71], v[66:67]
	v_pk_mul_f32 v[68:69], v[68:69], s[50:51] op_sel_hi:[1,0]
	v_pk_mul_f32 v[70:71], v[60:61], v[66:67]
	v_pk_fma_f32 v[66:67], v[60:61], v[66:67], v[60:61] neg_lo:[1,0,0] neg_hi:[1,0,0]
	v_exp_f32_e32 v68, v68
	v_cndmask_b32_e32 v60, v66, v70, vcc
	v_cmp_gt_f32_e32 vcc, 0, v61
	v_and_b32_e32 v66, 0x7fffffff, v62
	v_exp_f32_e32 v69, v69
	v_cndmask_b32_e32 v61, v67, v71, vcc
	v_and_b32_e32 v67, 0x7fffffff, v63
	v_pk_fma_f32 v[66:67], v[66:67], s[58:59], 1.0 op_sel_hi:[1,0,0]
	v_cmp_gt_f32_e32 vcc, 0, v62
	v_rcp_f32_e32 v66, v66
	v_rcp_f32_e32 v67, v67
	v_pk_mul_f32 v[28:29], v[60:61], v[28:29]
	v_pk_fma_f32 v[70:71], v[66:67], s[60:61], v[128:129] op_sel_hi:[1,0,0]
; __device__ __forceinline__ u32x4 pack8(f32x4 v0, f32x4 v1) { u32x4 w; w.x = cvt_pk_bf16(v0[0], v0[1]); w.y = cvt_pk_bf16(v0[2], v0[3]); w.z = cvt_pk_bf16(v1[0], v1[1]); w.w = cvt_pk_bf16(v1[2], v1[3]); return w; }
; __device__ __forceinline__ f32x4 gelu4(f32x4 v) { f32x2 a = gelu_pk((f32x2){v[0], v[1]}), b = gelu_pk((f32x2){v[2], v[3]}); return (f32x4){a.x, a.y, b.x, b.y}; }
; __device__ __forceinline__ f32x2 gelu_pk(f32x2 v) {
;     const f32x2 av = __builtin_elementwise_abs(v), d = av * 0.2316418882f + 1.0f;
;     f32x2 t; t.x = __builtin_amdgcn_rcpf(d.x); t.y = __builtin_amdgcn_rcpf(d.y);
;     f32x2 q = t * 0.5307027145f + (-0.7265760135f); q = q * t + 0.7107068705f; q = q * t + (-0.142248368f); q = q * t + 0.127414796f; q = q * t;
;     const f32x2 s = (v * v) * (-0.72134752044f);
;     f32x2 e; e.x = __builtin_amdgcn_exp2f(s.x); e.y = __builtin_amdgcn_exp2f(s.y);
;     const f32x2 m = v * (q * e), r = v - m;
;     f32x2 o; o.x = v.x < 0.f ? m.x : r.x; o.y = v.y < 0.f ? m.y : r.y; return o;
;     __device__ __forceinline__ void operator()(f32x4 (&acc)[2][2][4][2], const Unit& u, int wr, int wc, int fr_, int fq_) const {
;     ...
;             for (int m = 0; m < 4; ++m) { const int row = u.pm * BM + blk * 64 + m * 16 + fr;
;                 const f32x4 g0 = gelu4(acc[ai][0][m][0]), g1 = gelu4(acc[ai][0][m][1]);
;                 *(u32x4*)(ACT + (size_t)row * 5632 + jcol) = pack8(g0 * acc[ai][1][m][0], g1 * acc[ai][1][m][1]); asm volatile("" ::: "memory"); __builtin_amdgcn_sched_barrier(0); }
	v_pk_fma_f32 v[70:71], v[66:67], v[70:71], s[62:63] op_sel_hi:[1,1,0]
	v_pk_fma_f32 v[70:71], v[66:67], v[70:71], s[64:65] op_sel_hi:[1,1,0]
	v_pk_fma_f32 v[70:71], v[66:67], v[70:71], s[66:67] op_sel_hi:[1,1,0]
	v_pk_mul_f32 v[66:67], v[66:67], v[70:71]
	v_pk_mul_f32 v[70:71], v[44:45], v[44:45]
	v_pk_mul_f32 v[66:67], v[68:69], v[66:67]
	v_pk_mul_f32 v[70:71], v[70:71], s[50:51] op_sel_hi:[1,0]
	v_pk_mul_f32 v[68:69], v[62:63], v[66:67]
	v_pk_fma_f32 v[66:67], v[62:63], v[66:67], v[62:63] neg_lo:[1,0,0] neg_hi:[1,0,0]
	v_exp_f32_e32 v70, v70
	v_cndmask_b32_e32 v62, v66, v68, vcc
	v_cmp_gt_f32_e32 vcc, 0, v63
	v_and_b32_e32 v66, 0x7fffffff, v44
	v_exp_f32_e32 v71, v71
	v_cndmask_b32_e32 v63, v67, v69, vcc
	v_and_b32_e32 v67, 0x7fffffff, v45
	v_pk_fma_f32 v[66:67], v[66:67], s[58:59], 1.0 op_sel_hi:[1,0,0]
	v_cmp_gt_f32_e32 vcc, 0, v44
	v_rcp_f32_e32 v66, v66
	v_rcp_f32_e32 v67, v67
	v_pk_mul_f32 v[30:31], v[62:63], v[30:31]
	v_pk_fma_f32 v[68:69], v[66:67], s[60:61], v[128:129] op_sel_hi:[1,0,0]
	v_pk_fma_f32 v[68:69], v[66:67], v[68:69], s[62:63] op_sel_hi:[1,1,0]
	v_pk_fma_f32 v[68:69], v[66:67], v[68:69], s[64:65] op_sel_hi:[1,1,0]
	v_pk_fma_f32 v[68:69], v[66:67], v[68:69], s[66:67] op_sel_hi:[1,1,0]
	v_pk_mul_f32 v[66:67], v[66:67], v[68:69]
	v_pk_mul_f32 v[68:69], v[46:47], v[46:47]
	v_pk_mul_f32 v[66:67], v[70:71], v[66:67]
	v_pk_mul_f32 v[68:69], v[68:69], s[50:51] op_sel_hi:[1,0]
	v_pk_mul_f32 v[70:71], v[44:45], v[66:67]
	v_pk_fma_f32 v[66:67], v[44:45], v[66:67], v[44:45] neg_lo:[1,0,0] neg_hi:[1,0,0]
	v_exp_f32_e32 v68, v68
	v_cndmask_b32_e32 v44, v66, v70, vcc
	v_cmp_gt_f32_e32 vcc, 0, v45
	v_and_b32_e32 v66, 0x7fffffff, v46
	v_exp_f32_e32 v69, v69
	v_cndmask_b32_e32 v45, v67, v71, vcc
	v_and_b32_e32 v67, 0x7fffffff, v47
	v_pk_fma_f32 v[66:67], v[66:67], s[58:59], 1.0 op_sel_hi:[1,0,0]
	v_cmp_gt_f32_e32 vcc, 0, v46
	v_rcp_f32_e32 v66, v66
	v_rcp_f32_e32 v67, v67
	s_nop 0
	v_pk_fma_f32 v[70:71], v[66:67], s[60:61], v[128:129] op_sel_hi:[1,0,0]
	v_pk_fma_f32 v[70:71], v[66:67], v[70:71], s[62:63] op_sel_hi:[1,1,0]
	v_pk_fma_f32 v[70:71], v[66:67], v[70:71], s[64:65] op_sel_hi:[1,1,0]
	v_pk_fma_f32 v[70:71], v[66:67], v[70:71], s[66:67] op_sel_hi:[1,1,0]
	v_pk_mul_f32 v[66:67], v[66:67], v[70:71]
	v_pk_mul_f32 v[66:67], v[68:69], v[66:67]
	v_pk_mul_f32 v[68:69], v[46:47], v[66:67]
	v_pk_fma_f32 v[66:67], v[46:47], v[66:67], v[46:47] neg_lo:[1,0,0] neg_hi:[1,0,0]
	v_cndmask_b32_e32 v46, v66, v68, vcc
	v_cmp_gt_f32_e32 vcc, 0, v47
	s_nop 1
	v_cndmask_b32_e32 v47, v67, v69, vcc
	v_pk_mul_f32 v[46:47], v[46:47], v[14:15]
	v_pk_mul_f32 v[14:15], v[44:45], v[12:13]
	v_cvt_pk_bf16_f32 v12, v28, v29
	v_mad_i64_i32 v[28:29], s[0:1], v64, s93, v[76:77]
	v_cvt_pk_bf16_f32 v13, v30, v31
	v_cvt_pk_bf16_f32 v14, v14, v15
	v_cvt_pk_bf16_f32 v15, v46, v47
	v_lshl_add_u64 v[28:29], v[28:29], 0, v[78:79]
	global_store_dwordx4 v[28:29], v[12:15], off
	s_nop 1
	v_and_b32_e32 v13, 0x7fffffff, v57
	v_and_b32_e32 v12, 0x7fffffff, v56
	v_pk_fma_f32 v[12:13], v[12:13], s[58:59], 1.0 op_sel_hi:[1,0,0]
	v_pk_mul_f32 v[28:29], v[56:57], v[56:57]
	v_rcp_f32_e32 v12, v12
	v_rcp_f32_e32 v13, v13
	v_pk_mul_f32 v[28:29], v[28:29], s[50:51] op_sel_hi:[1,0]
	v_cmp_gt_f32_e32 vcc, 0, v56
	v_exp_f32_e32 v28, v28
	v_pk_fma_f32 v[14:15], v[12:13], s[60:61], v[128:129] op_sel_hi:[1,0,0]
	v_exp_f32_e32 v29, v29
	v_pk_fma_f32 v[14:15], v[12:13], v[14:15], s[62:63] op_sel_hi:[1,1,0]
	v_pk_mul_f32 v[44:45], v[40:41], v[40:41]
	v_pk_fma_f32 v[14:15], v[12:13], v[14:15], s[64:65] op_sel_hi:[1,1,0]
	v_pk_mul_f32 v[44:45], v[44:45], s[50:51] op_sel_hi:[1,0]
	v_pk_fma_f32 v[14:15], v[12:13], v[14:15], s[66:67] op_sel_hi:[1,1,0]
	v_exp_f32_e32 v44, v44
	v_pk_mul_f32 v[12:13], v[12:13], v[14:15]
	v_pk_mul_f32 v[14:15], v[58:59], v[58:59]
	v_pk_mul_f32 v[12:13], v[28:29], v[12:13]
	v_pk_mul_f32 v[14:15], v[14:15], s[50:51] op_sel_hi:[1,0]
	v_pk_mul_f32 v[28:29], v[56:57], v[12:13]
	v_pk_fma_f32 v[12:13], v[56:57], v[12:13], v[56:57] neg_lo:[1,0,0] neg_hi:[1,0,0]
	v_exp_f32_e32 v14, v14
	v_cndmask_b32_e32 v12, v12, v28, vcc
	v_cmp_gt_f32_e32 vcc, 0, v57
	v_and_b32_e32 v28, 0x7fffffff, v58
	v_exp_f32_e32 v15, v15
	v_cndmask_b32_e32 v13, v13, v29, vcc
	v_and_b32_e32 v29, 0x7fffffff, v59
	v_pk_fma_f32 v[28:29], v[28:29], s[58:59], 1.0 op_sel_hi:[1,0,0]
	v_cmp_gt_f32_e32 vcc, 0, v58
	v_rcp_f32_e32 v28, v28
	v_rcp_f32_e32 v29, v29
	v_exp_f32_e32 v45, v45
	v_add_u32_e32 v46, 16, v64
	v_pk_mul_f32 v[12:13], v[12:13], v[24:25]
	v_pk_fma_f32 v[30:31], v[28:29], s[60:61], v[128:129] op_sel_hi:[1,0,0]
	v_pk_fma_f32 v[30:31], v[28:29], v[30:31], s[62:63] op_sel_hi:[1,1,0]
	v_pk_fma_f32 v[30:31], v[28:29], v[30:31], s[64:65] op_sel_hi:[1,1,0]
	v_pk_fma_f32 v[30:31], v[28:29], v[30:31], s[66:67] op_sel_hi:[1,1,0]
	v_pk_mul_f32 v[28:29], v[28:29], v[30:31]
	v_pk_mul_f32 v[14:15], v[14:15], v[28:29]
	v_pk_mul_f32 v[28:29], v[58:59], v[14:15]
	v_pk_fma_f32 v[14:15], v[58:59], v[14:15], v[58:59] neg_lo:[1,0,0] neg_hi:[1,0,0]
	v_cndmask_b32_e32 v14, v14, v28, vcc
	v_cmp_gt_f32_e32 vcc, 0, v59
	v_and_b32_e32 v28, 0x7fffffff, v40
	s_nop 0
	v_cndmask_b32_e32 v15, v15, v29, vcc
	v_and_b32_e32 v29, 0x7fffffff, v41
	v_pk_fma_f32 v[28:29], v[28:29], s[58:59], 1.0 op_sel_hi:[1,0,0]
	v_cmp_gt_f32_e32 vcc, 0, v40
	v_rcp_f32_e32 v28, v28
	v_rcp_f32_e32 v29, v29
	v_pk_mul_f32 v[14:15], v[14:15], v[26:27]
	v_pk_fma_f32 v[30:31], v[28:29], s[60:61], v[128:129] op_sel_hi:[1,0,0]
	v_pk_fma_f32 v[30:31], v[28:29], v[30:31], s[62:63] op_sel_hi:[1,1,0]
	v_pk_fma_f32 v[30:31], v[28:29], v[30:31], s[64:65] op_sel_hi:[1,1,0]
	v_pk_fma_f32 v[30:31], v[28:29], v[30:31], s[66:67] op_sel_hi:[1,1,0]
; __device__ __forceinline__ u32x4 pack8(f32x4 v0, f32x4 v1) { u32x4 w; w.x = cvt_pk_bf16(v0[0], v0[1]); w.y = cvt_pk_bf16(v0[2], v0[3]); w.z = cvt_pk_bf16(v1[0], v1[1]); w.w = cvt_pk_bf16(v1[2], v1[3]); return w; }
; __device__ __forceinline__ f32x4 gelu4(f32x4 v) { f32x2 a = gelu_pk((f32x2){v[0], v[1]}), b = gelu_pk((f32x2){v[2], v[3]}); return (f32x4){a.x, a.y, b.x, b.y}; }
; __device__ __forceinline__ f32x2 gelu_pk(f32x2 v) {
;     const f32x2 av = __builtin_elementwise_abs(v), d = av * 0.2316418882f + 1.0f;
;     f32x2 t; t.x = __builtin_amdgcn_rcpf(d.x); t.y = __builtin_amdgcn_rcpf(d.y);
;     f32x2 q = t * 0.5307027145f + (-0.7265760135f); q = q * t + 0.7107068705f; q = q * t + (-0.142248368f); q = q * t + 0.127414796f; q = q * t;
;     const f32x2 s = (v * v) * (-0.72134752044f);
;     f32x2 e; e.x = __builtin_amdgcn_exp2f(s.x); e.y = __builtin_amdgcn_exp2f(s.y);
;     const f32x2 m = v * (q * e), r = v - m;
;     f32x2 o; o.x = v.x < 0.f ? m.x : r.x; o.y = v.y < 0.f ? m.y : r.y; return o;
;     __device__ __forceinline__ void operator()(f32x4 (&acc)[2][2][4][2], const Unit& u, int wr, int wc, int fr_, int fq_) const {
;     ...
;             for (int m = 0; m < 4; ++m) { const int row = u.pm * BM + blk * 64 + m * 16 + fr;
;                 const f32x4 g0 = gelu4(acc[ai][0][m][0]), g1 = gelu4(acc[ai][0][m][1]);
;                 *(u32x4*)(ACT + (size_t)row * 5632 + jcol) = pack8(g0 * acc[ai][1][m][0], g1 * acc[ai][1][m][1]); asm volatile("" ::: "memory"); __builtin_amdgcn_sched_barrier(0); }
	v_pk_mul_f32 v[28:29], v[28:29], v[30:31]
	v_pk_mul_f32 v[30:31], v[42:43], v[42:43]
	v_pk_mul_f32 v[28:29], v[44:45], v[28:29]
	v_pk_mul_f32 v[30:31], v[30:31], s[50:51] op_sel_hi:[1,0]
	v_pk_mul_f32 v[44:45], v[40:41], v[28:29]
	v_pk_fma_f32 v[28:29], v[40:41], v[28:29], v[40:41] neg_lo:[1,0,0] neg_hi:[1,0,0]
	v_and_b32_e32 v40, 0x7fffffff, v42
	v_cndmask_b32_e32 v28, v28, v44, vcc
	v_cmp_gt_f32_e32 vcc, 0, v41
	v_and_b32_e32 v41, 0x7fffffff, v43
	v_pk_fma_f32 v[40:41], v[40:41], s[58:59], 1.0 op_sel_hi:[1,0,0]
	v_cndmask_b32_e32 v29, v29, v45, vcc
	v_rcp_f32_e32 v40, v40
	v_rcp_f32_e32 v41, v41
	v_exp_f32_e32 v30, v30
	v_exp_f32_e32 v31, v31
	v_cmp_gt_f32_e32 vcc, 0, v42
	v_pk_fma_f32 v[44:45], v[40:41], s[60:61], v[128:129] op_sel_hi:[1,0,0]
	s_nop 0
	v_pk_fma_f32 v[44:45], v[40:41], v[44:45], s[62:63] op_sel_hi:[1,1,0]
	s_nop 0
	v_pk_fma_f32 v[44:45], v[40:41], v[44:45], s[64:65] op_sel_hi:[1,1,0]
	v_pk_fma_f32 v[44:45], v[40:41], v[44:45], s[66:67] op_sel_hi:[1,1,0]
	v_pk_mul_f32 v[40:41], v[40:41], v[44:45]
	v_pk_mul_f32 v[30:31], v[30:31], v[40:41]
	v_pk_mul_f32 v[40:41], v[42:43], v[30:31]
	v_pk_fma_f32 v[30:31], v[42:43], v[30:31], v[42:43] neg_lo:[1,0,0] neg_hi:[1,0,0]
	v_cndmask_b32_e32 v30, v30, v40, vcc
	v_cmp_gt_f32_e32 vcc, 0, v43
	s_nop 1
	v_cndmask_b32_e32 v31, v31, v41, vcc
	v_pk_mul_f32 v[24:25], v[30:31], v[10:11]
	v_pk_mul_f32 v[10:11], v[28:29], v[8:9]
	v_cvt_pk_bf16_f32 v8, v12, v13
	v_mad_i64_i32 v[12:13], s[0:1], v46, s93, v[76:77]
	v_cvt_pk_bf16_f32 v9, v14, v15
	v_cvt_pk_bf16_f32 v10, v10, v11
	v_cvt_pk_bf16_f32 v11, v24, v25
	v_lshl_add_u64 v[12:13], v[12:13], 0, v[78:79]
	global_store_dwordx4 v[12:13], v[8:11], off
	s_nop 1
	v_and_b32_e32 v9, 0x7fffffff, v53
	v_and_b32_e32 v8, 0x7fffffff, v52
	v_pk_fma_f32 v[8:9], v[8:9], s[58:59], 1.0 op_sel_hi:[1,0,0]
	v_pk_mul_f32 v[12:13], v[52:53], v[52:53]
	v_rcp_f32_e32 v8, v8
	v_rcp_f32_e32 v9, v9
	v_pk_mul_f32 v[12:13], v[12:13], s[50:51] op_sel_hi:[1,0]
	v_cmp_gt_f32_e32 vcc, 0, v52
	v_exp_f32_e32 v12, v12
	v_pk_fma_f32 v[10:11], v[8:9], s[60:61], v[128:129] op_sel_hi:[1,0,0]
	v_exp_f32_e32 v13, v13
	v_pk_fma_f32 v[10:11], v[8:9], v[10:11], s[62:63] op_sel_hi:[1,1,0]
	v_pk_mul_f32 v[24:25], v[36:37], v[36:37]
	v_pk_fma_f32 v[10:11], v[8:9], v[10:11], s[64:65] op_sel_hi:[1,1,0]
	v_pk_mul_f32 v[24:25], v[24:25], s[50:51] op_sel_hi:[1,0]
	v_pk_fma_f32 v[10:11], v[8:9], v[10:11], s[66:67] op_sel_hi:[1,1,0]
	v_exp_f32_e32 v24, v24
	v_pk_mul_f32 v[8:9], v[8:9], v[10:11]
	v_pk_mul_f32 v[10:11], v[54:55], v[54:55]
	v_pk_mul_f32 v[8:9], v[12:13], v[8:9]
	v_pk_mul_f32 v[10:11], v[10:11], s[50:51] op_sel_hi:[1,0]
	v_pk_mul_f32 v[12:13], v[52:53], v[8:9]
	v_pk_fma_f32 v[8:9], v[52:53], v[8:9], v[52:53] neg_lo:[1,0,0] neg_hi:[1,0,0]
	v_exp_f32_e32 v10, v10
	v_cndmask_b32_e32 v8, v8, v12, vcc
	v_cmp_gt_f32_e32 vcc, 0, v53
	v_and_b32_e32 v12, 0x7fffffff, v54
	v_exp_f32_e32 v11, v11
	v_cndmask_b32_e32 v9, v9, v13, vcc
	v_and_b32_e32 v13, 0x7fffffff, v55
	v_pk_fma_f32 v[12:13], v[12:13], s[58:59], 1.0 op_sel_hi:[1,0,0]
	v_cmp_gt_f32_e32 vcc, 0, v54
	v_rcp_f32_e32 v12, v12
	v_rcp_f32_e32 v13, v13
	v_exp_f32_e32 v25, v25
	v_add_u32_e32 v28, 32, v64
	v_pk_mul_f32 v[8:9], v[8:9], v[20:21]
	v_pk_fma_f32 v[14:15], v[12:13], s[60:61], v[128:129] op_sel_hi:[1,0,0]
	v_pk_fma_f32 v[14:15], v[12:13], v[14:15], s[62:63] op_sel_hi:[1,1,0]
	v_pk_fma_f32 v[14:15], v[12:13], v[14:15], s[64:65] op_sel_hi:[1,1,0]
	v_pk_fma_f32 v[14:15], v[12:13], v[14:15], s[66:67] op_sel_hi:[1,1,0]
	v_pk_mul_f32 v[12:13], v[12:13], v[14:15]
	v_pk_mul_f32 v[10:11], v[10:11], v[12:13]
	v_pk_mul_f32 v[12:13], v[54:55], v[10:11]
	v_pk_fma_f32 v[10:11], v[54:55], v[10:11], v[54:55] neg_lo:[1,0,0] neg_hi:[1,0,0]
	v_cndmask_b32_e32 v10, v10, v12, vcc
	v_cmp_gt_f32_e32 vcc, 0, v55
	v_and_b32_e32 v12, 0x7fffffff, v36
	s_nop 0
	v_cndmask_b32_e32 v11, v11, v13, vcc
	v_and_b32_e32 v13, 0x7fffffff, v37
	v_pk_fma_f32 v[12:13], v[12:13], s[58:59], 1.0 op_sel_hi:[1,0,0]
	v_cmp_gt_f32_e32 vcc, 0, v36
	v_rcp_f32_e32 v12, v12
	v_rcp_f32_e32 v13, v13
	v_pk_mul_f32 v[10:11], v[10:11], v[22:23]
	v_pk_fma_f32 v[14:15], v[12:13], s[60:61], v[128:129] op_sel_hi:[1,0,0]
	v_pk_fma_f32 v[14:15], v[12:13], v[14:15], s[62:63] op_sel_hi:[1,1,0]
	v_pk_fma_f32 v[14:15], v[12:13], v[14:15], s[64:65] op_sel_hi:[1,1,0]
	v_pk_fma_f32 v[14:15], v[12:13], v[14:15], s[66:67] op_sel_hi:[1,1,0]
	v_pk_mul_f32 v[12:13], v[12:13], v[14:15]
	v_pk_mul_f32 v[14:15], v[38:39], v[38:39]
	v_pk_mul_f32 v[12:13], v[24:25], v[12:13]
	v_pk_mul_f32 v[14:15], v[14:15], s[50:51] op_sel_hi:[1,0]
	v_pk_mul_f32 v[24:25], v[36:37], v[12:13]
	v_pk_fma_f32 v[12:13], v[36:37], v[12:13], v[36:37] neg_lo:[1,0,0] neg_hi:[1,0,0]
	v_exp_f32_e32 v14, v14
	v_cndmask_b32_e32 v12, v12, v24, vcc
	v_cmp_gt_f32_e32 vcc, 0, v37
	v_and_b32_e32 v24, 0x7fffffff, v38
	v_exp_f32_e32 v15, v15
	v_cndmask_b32_e32 v13, v13, v25, vcc
	v_and_b32_e32 v25, 0x7fffffff, v39
	v_pk_fma_f32 v[24:25], v[24:25], s[58:59], 1.0 op_sel_hi:[1,0,0]
	v_cmp_gt_f32_e32 vcc, 0, v38
	v_rcp_f32_e32 v24, v24
	v_rcp_f32_e32 v25, v25
	s_nop 0
	v_pk_fma_f32 v[26:27], v[24:25], s[60:61], v[128:129] op_sel_hi:[1,0,0]
	v_pk_fma_f32 v[26:27], v[24:25], v[26:27], s[62:63] op_sel_hi:[1,1,0]
; __device__ __forceinline__ u32x4 pack8(f32x4 v0, f32x4 v1) { u32x4 w; w.x = cvt_pk_bf16(v0[0], v0[1]); w.y = cvt_pk_bf16(v0[2], v0[3]); w.z = cvt_pk_bf16(v1[0], v1[1]); w.w = cvt_pk_bf16(v1[2], v1[3]); return w; }
; __device__ __forceinline__ f32x4 gelu4(f32x4 v) { f32x2 a = gelu_pk((f32x2){v[0], v[1]}), b = gelu_pk((f32x2){v[2], v[3]}); return (f32x4){a.x, a.y, b.x, b.y}; }
; #define PG8_BAR __builtin_amdgcn_s_barrier()
; __device__ __forceinline__ f32x2 gelu_pk(f32x2 v) {
;     const f32x2 av = __builtin_elementwise_abs(v), d = av * 0.2316418882f + 1.0f;
;     f32x2 t; t.x = __builtin_amdgcn_rcpf(d.x); t.y = __builtin_amdgcn_rcpf(d.y);
;     f32x2 q = t * 0.5307027145f + (-0.7265760135f); q = q * t + 0.7107068705f; q = q * t + (-0.142248368f); q = q * t + 0.127414796f; q = q * t;
;     const f32x2 s = (v * v) * (-0.72134752044f);
;     f32x2 e; e.x = __builtin_amdgcn_exp2f(s.x); e.y = __builtin_amdgcn_exp2f(s.y);
;     const f32x2 m = v * (q * e), r = v - m;
;     f32x2 o; o.x = v.x < 0.f ? m.x : r.x; o.y = v.y < 0.f ? m.y : r.y; return o;
;     __device__ __forceinline__ void operator()(f32x4 (&acc)[2][2][4][2], const Unit& u, int wr, int wc, int fr_, int fq_) const {
;     ...
;             for (int m = 0; m < 4; ++m) { const int row = u.pm * BM + blk * 64 + m * 16 + fr;
;                 const f32x4 g0 = gelu4(acc[ai][0][m][0]), g1 = gelu4(acc[ai][0][m][1]);
;                 *(u32x4*)(ACT + (size_t)row * 5632 + jcol) = pack8(g0 * acc[ai][1][m][0], g1 * acc[ai][1][m][1]); asm volatile("" ::: "memory"); __builtin_amdgcn_sched_barrier(0); }
; template <class Epi, class Sched, bool ALIGN_EPI = false, bool SP2 = false>
; __device__ __forceinline__ void gemm_phase(PG8_LAS unsigned char* lds, const Gemm g, const Sched& S, const Epi& E) {
;     ...
;         if constexpr (ALIGN_EPI) { if (wr == 0) PG8_BAR; }
;         if constexpr (!Epi::AFTER_DRAIN) { E(acc, cur, wr, wc, fr, fq); S.done(cur); }
;         if (!has_next) break;
; #pragma unroll
;         for (int a = 0; a < 2; ++a)
; #pragma unroll
;             for (int b = 0; b < 2; ++b)
; #pragma unroll
;                 for (int m = 0; m < 4; ++m)
; #pragma unroll
;                     for (int n = 0; n < 2; ++n) acc[a][b][m][n] = (f32x4){0.f, 0.f, 0.f, 0.f};
;         cur = nxt; cA = nA; cB = nB; ++ui;
;         if constexpr (ALIGN_EPI) { if (wr == 1) PG8_BAR; }
;     }
	v_pk_fma_f32 v[26:27], v[24:25], v[26:27], s[64:65] op_sel_hi:[1,1,0]
	v_pk_fma_f32 v[26:27], v[24:25], v[26:27], s[66:67] op_sel_hi:[1,1,0]
	v_pk_mul_f32 v[24:25], v[24:25], v[26:27]
	v_pk_mul_f32 v[14:15], v[14:15], v[24:25]
	v_pk_mul_f32 v[24:25], v[38:39], v[14:15]
	v_pk_fma_f32 v[14:15], v[38:39], v[14:15], v[38:39] neg_lo:[1,0,0] neg_hi:[1,0,0]
	v_cndmask_b32_e32 v14, v14, v24, vcc
	v_cmp_gt_f32_e32 vcc, 0, v39
	s_nop 1
	v_cndmask_b32_e32 v15, v15, v25, vcc
	v_pk_mul_f32 v[14:15], v[14:15], v[6:7]
	v_pk_mul_f32 v[6:7], v[12:13], v[4:5]
	v_cvt_pk_bf16_f32 v4, v8, v9
	v_mad_i64_i32 v[8:9], s[0:1], v28, s93, v[76:77]
	v_cvt_pk_bf16_f32 v5, v10, v11
	v_cvt_pk_bf16_f32 v6, v6, v7
	v_cvt_pk_bf16_f32 v7, v14, v15
	v_lshl_add_u64 v[8:9], v[8:9], 0, v[78:79]
	global_store_dwordx4 v[8:9], v[4:7], off
	s_nop 1
	v_and_b32_e32 v5, 0x7fffffff, v49
	v_and_b32_e32 v4, 0x7fffffff, v48
	v_pk_fma_f32 v[4:5], v[4:5], s[58:59], 1.0 op_sel_hi:[1,0,0]
	v_pk_mul_f32 v[8:9], v[48:49], v[48:49]
	v_rcp_f32_e32 v4, v4
	v_rcp_f32_e32 v5, v5
	v_pk_mul_f32 v[8:9], v[8:9], s[50:51] op_sel_hi:[1,0]
	v_cmp_gt_f32_e32 vcc, 0, v48
	v_exp_f32_e32 v8, v8
	v_pk_fma_f32 v[6:7], v[4:5], s[60:61], v[128:129] op_sel_hi:[1,0,0]
	v_exp_f32_e32 v9, v9
	v_pk_fma_f32 v[6:7], v[4:5], v[6:7], s[62:63] op_sel_hi:[1,1,0]
	v_pk_mul_f32 v[12:13], v[32:33], v[32:33]
	v_pk_fma_f32 v[6:7], v[4:5], v[6:7], s[64:65] op_sel_hi:[1,1,0]
	v_pk_mul_f32 v[12:13], v[12:13], s[50:51] op_sel_hi:[1,0]
	v_pk_fma_f32 v[6:7], v[4:5], v[6:7], s[66:67] op_sel_hi:[1,1,0]
	v_exp_f32_e32 v12, v12
	v_pk_mul_f32 v[4:5], v[4:5], v[6:7]
	v_pk_mul_f32 v[6:7], v[50:51], v[50:51]
	v_pk_mul_f32 v[4:5], v[8:9], v[4:5]
	v_pk_mul_f32 v[6:7], v[6:7], s[50:51] op_sel_hi:[1,0]
	v_pk_mul_f32 v[8:9], v[48:49], v[4:5]
	v_pk_fma_f32 v[4:5], v[48:49], v[4:5], v[48:49] neg_lo:[1,0,0] neg_hi:[1,0,0]
	v_exp_f32_e32 v6, v6
	v_cndmask_b32_e32 v4, v4, v8, vcc
	v_cmp_gt_f32_e32 vcc, 0, v49
	v_and_b32_e32 v8, 0x7fffffff, v50
	v_exp_f32_e32 v7, v7
	v_cndmask_b32_e32 v5, v5, v9, vcc
	v_and_b32_e32 v9, 0x7fffffff, v51
	v_pk_fma_f32 v[8:9], v[8:9], s[58:59], 1.0 op_sel_hi:[1,0,0]
	v_cmp_gt_f32_e32 vcc, 0, v50
	v_rcp_f32_e32 v8, v8
	v_rcp_f32_e32 v9, v9
	v_exp_f32_e32 v13, v13
	v_add_u32_e32 v20, 48, v64
	v_pk_mul_f32 v[4:5], v[4:5], v[16:17]
	v_pk_fma_f32 v[10:11], v[8:9], s[60:61], v[128:129] op_sel_hi:[1,0,0]
	v_pk_fma_f32 v[10:11], v[8:9], v[10:11], s[62:63] op_sel_hi:[1,1,0]
	v_pk_fma_f32 v[10:11], v[8:9], v[10:11], s[64:65] op_sel_hi:[1,1,0]
	v_pk_fma_f32 v[10:11], v[8:9], v[10:11], s[66:67] op_sel_hi:[1,1,0]
	v_pk_mul_f32 v[8:9], v[8:9], v[10:11]
	v_pk_mul_f32 v[6:7], v[6:7], v[8:9]
	v_pk_mul_f32 v[8:9], v[50:51], v[6:7]
	v_pk_fma_f32 v[6:7], v[50:51], v[6:7], v[50:51] neg_lo:[1,0,0] neg_hi:[1,0,0]
	v_cndmask_b32_e32 v6, v6, v8, vcc
	v_cmp_gt_f32_e32 vcc, 0, v51
	v_and_b32_e32 v8, 0x7fffffff, v32
	s_nop 0
	v_cndmask_b32_e32 v7, v7, v9, vcc
	v_and_b32_e32 v9, 0x7fffffff, v33
	v_pk_fma_f32 v[8:9], v[8:9], s[58:59], 1.0 op_sel_hi:[1,0,0]
	v_cmp_gt_f32_e32 vcc, 0, v32
	v_rcp_f32_e32 v8, v8
	v_rcp_f32_e32 v9, v9
	v_pk_mul_f32 v[6:7], v[6:7], v[18:19]
	v_pk_fma_f32 v[10:11], v[8:9], s[60:61], v[128:129] op_sel_hi:[1,0,0]
	v_pk_fma_f32 v[10:11], v[8:9], v[10:11], s[62:63] op_sel_hi:[1,1,0]
	v_pk_fma_f32 v[10:11], v[8:9], v[10:11], s[64:65] op_sel_hi:[1,1,0]
	v_pk_fma_f32 v[10:11], v[8:9], v[10:11], s[66:67] op_sel_hi:[1,1,0]
	v_pk_mul_f32 v[8:9], v[8:9], v[10:11]
	v_pk_mul_f32 v[10:11], v[34:35], v[34:35]
	v_pk_mul_f32 v[8:9], v[12:13], v[8:9]
	v_pk_mul_f32 v[10:11], v[10:11], s[50:51] op_sel_hi:[1,0]
	v_pk_mul_f32 v[12:13], v[32:33], v[8:9]
	v_pk_fma_f32 v[8:9], v[32:33], v[8:9], v[32:33] neg_lo:[1,0,0] neg_hi:[1,0,0]
	v_exp_f32_e32 v10, v10
	v_cndmask_b32_e32 v8, v8, v12, vcc
	v_cmp_gt_f32_e32 vcc, 0, v33
	v_and_b32_e32 v12, 0x7fffffff, v34
	v_exp_f32_e32 v11, v11
	v_cndmask_b32_e32 v9, v9, v13, vcc
	v_and_b32_e32 v13, 0x7fffffff, v35
	v_pk_fma_f32 v[12:13], v[12:13], s[58:59], 1.0 op_sel_hi:[1,0,0]
	v_cmp_gt_f32_e32 vcc, 0, v34
	v_rcp_f32_e32 v12, v12
	v_rcp_f32_e32 v13, v13
	s_nop 0
	v_pk_fma_f32 v[14:15], v[12:13], s[60:61], v[128:129] op_sel_hi:[1,0,0]
	v_pk_fma_f32 v[14:15], v[12:13], v[14:15], s[62:63] op_sel_hi:[1,1,0]
	v_pk_fma_f32 v[14:15], v[12:13], v[14:15], s[64:65] op_sel_hi:[1,1,0]
	v_pk_fma_f32 v[14:15], v[12:13], v[14:15], s[66:67] op_sel_hi:[1,1,0]
	v_pk_mul_f32 v[12:13], v[12:13], v[14:15]
	v_pk_mul_f32 v[10:11], v[10:11], v[12:13]
	v_pk_mul_f32 v[12:13], v[34:35], v[10:11]
	v_pk_fma_f32 v[10:11], v[34:35], v[10:11], v[34:35] neg_lo:[1,0,0] neg_hi:[1,0,0]
	v_cndmask_b32_e32 v10, v10, v12, vcc
	v_cmp_gt_f32_e32 vcc, 0, v35
	s_nop 1
	v_cndmask_b32_e32 v11, v11, v13, vcc
	v_pk_mul_f32 v[10:11], v[10:11], v[2:3]
	v_pk_mul_f32 v[2:3], v[8:9], v[0:1]
	v_cvt_pk_bf16_f32 v0, v4, v5
	v_mad_i64_i32 v[4:5], s[0:1], v20, s93, v[76:77]
	v_cvt_pk_bf16_f32 v1, v6, v7
	v_cvt_pk_bf16_f32 v2, v2, v3
	v_cvt_pk_bf16_f32 v3, v10, v11
	v_lshl_add_u64 v[4:5], v[4:5], 0, v[78:79]
	global_store_dwordx4 v[4:5], v[0:3], off
	s_andn2_b64 vcc, exec, s[4:5]
	s_mov_b64 s[0:1], -1
	s_cbranch_vccnz .LBB0_1697
	s_andn2_b64 vcc, exec, s[18:19]
	s_cbranch_vccnz .LBB0_1696
	s_barrier
	s_branch .LBB0_1696

; __device__ __forceinline__ unsigned f2bf(float f) { unsigned u = __float_as_uint(f); return (u + 0x7fffu + ((u >> 16) & 1u)) >> 16; }
; __device__ __forceinline__ float gelu_f(float x) { return 0.5f * x * (1.0f + erff(x * 0.70710678118654752f)); }
; __device__ __forceinline__ void phase_fixup(const Params& p) {
;     ...
;             if (i < 128 * 2 * DFF) { const int j = i % DFF, row = (i / DFF) & 1, pm = i / (2 * DFF); const int cg_ = (j >> 7) * 256 + (j & 127), cv_ = cg_ + 128;
;                 Cg[u] = TOP[((size_t)pm * 2 + row) * 11264 + cg_]; Cv[u] = TOP[((size_t)pm * 2 + row) * 11264 + cv_];
;                 if (pm % 64) { const float* b0 = BOT + ((size_t)(pm - 1) * 2) * 11264; const float* b1 = b0 + 11264; bg0[u] = b0[cg_]; bg1[u] = b1[cg_]; bv0[u] = b0[cv_]; bv1[u] = b1[cv_]; } } }
; #pragma unroll
;         for (int u = 0; u < 4; ++u) { const int i = i0 + u * NGT;
;             if (i < 128 * 2 * DFF) { const int j = i % DFF, row = (i / DFF) & 1, pm = i / (2 * DFF); float g = Cg[u], v = Cv[u];
;                 if (pm % 64) { if (row == 0) { g += cw[j] * bg0[u] + cw[11264 + j] * bg1[u]; v += cw[5632 + j] * bv0[u] + cw[11264 + 5632 + j] * bv1[u]; }
;                                else { g += cw[j] * bg1[u]; v += cw[5632 + j] * bv1[u]; } }
;                 ACT[(size_t)(pm * 256 + row) * DFF + j] = (bf16)f2bf(gelu_f(g) * v); } } }
.LBB0_1804:
	s_or_b64 exec, exec, s[36:37]
	v_ashrrev_i32_e32 v25, 31, v24
	s_and_saveexec_b64 s[8:9], vcc
	s_cbranch_execz .LBB0_1810
	v_readlane_b32 s60, v244, 4
	v_readlane_b32 s74, v244, 18
	v_readlane_b32 s75, v244, 19
	s_waitcnt vmcnt(0)
	v_mov_b32_e32 v28, v0
	v_mov_b32_e32 v29, v14
	v_lshl_add_u64 v[30:31], v[24:25], 2, s[74:75]
	global_load_dword v27, v[30:31], off
	v_cmp_ne_u32_e32 vcc, 0, v45
	v_readlane_b32 s61, v244, 5
	v_readlane_b32 s62, v244, 6
	v_readlane_b32 s63, v244, 7
	v_readlane_b32 s64, v244, 8
	v_readlane_b32 s65, v244, 9
	v_readlane_b32 s66, v244, 10
	v_readlane_b32 s67, v244, 11
	v_readlane_b32 s68, v244, 12
	v_readlane_b32 s69, v244, 13
	v_readlane_b32 s70, v244, 14
	v_readlane_b32 s71, v244, 15
	v_readlane_b32 s72, v244, 16
	v_readlane_b32 s73, v244, 17
	s_and_saveexec_b64 s[36:37], vcc
	s_xor_b64 s[36:37], exec, s[36:37]
	s_cbranch_execz .LBB0_1807
	v_add_co_u32_e32 v30, vcc, 0x5000, v30
	s_nop 1
	v_addc_co_u32_e32 v31, vcc, 0, v31, vcc
	global_load_dword v26, v[30:31], off offset:2048
	v_mov_b32_e32 v30, v16
	v_mov_b32_e32 v31, v18
	s_waitcnt vmcnt(0)
	v_pk_fma_f32 v[26:27], v[30:31], v[26:27], v[28:29]
	v_mov_b32_e32 v14, v27
	v_mov_b32_e32 v0, v26
.LBB0_1807:
	s_andn2_saveexec_b64 s[36:37], s[36:37]
	s_cbranch_execz .LBB0_1809
	v_add_co_u32_e32 v52, vcc, 0xb000, v30
	s_nop 1
	v_addc_co_u32_e32 v53, vcc, 0, v31, vcc
	v_add_co_u32_e32 v54, vcc, 0x5000, v30
	s_nop 1
	v_addc_co_u32_e32 v55, vcc, 0, v31, vcc
	v_add_co_u32_e32 v30, vcc, 0x10000, v30
	s_nop 1
	v_addc_co_u32_e32 v31, vcc, 0, v31, vcc
	global_load_dword v53, v[52:53], off
	s_nop 0
	global_load_dword v52, v[30:31], off offset:2048
	global_load_dword v26, v[54:55], off offset:2048
	v_mov_b32_e32 v54, v16
	v_mov_b32_e32 v55, v18
	v_mov_b32_e32 v30, v22
	v_mov_b32_e32 v31, v20
	s_waitcnt vmcnt(1)
	v_pk_mul_f32 v[52:53], v[54:55], v[52:53]
	s_waitcnt vmcnt(0)
	v_pk_fma_f32 v[26:27], v[30:31], v[26:27], v[52:53]
	v_pk_add_f32 v[26:27], v[28:29], v[26:27]
	v_mov_b32_e32 v14, v27
	v_mov_b32_e32 v0, v26

; __device__ __forceinline__ void phase_final(const Params& p) {
;     ...
;     for (int row0 = gw; row0 < T; row0 += UR * NGW) { f32x4 v[UR][8]; float rs[UR];
; #pragma unroll
;         for (int u = 0; u < UR; ++u) { const int row = row0 + u * NGW; const f32x4* xr = (const f32x4*)(p.out + (size_t)row * DM) + lane;
; #pragma unroll
;             for (int j = 0; j < 8; ++j) v[u][j] = xr[64 * j];
;             const f32x4* sp = (const f32x4*)(ssq + (size_t)row * 32); f32x4 s = sp[0];
; #pragma unroll
;             for (int i = 1; i < 8; ++i) s += sp[i];
;             rs[u] = 1.0f / sqrtf(((s[0] + s[1]) + (s[2] + s[3])) * (1.0f / DM) + 1e-6f); }
.LBB0_2004:
	v_ashrrev_i32_e32 v97, 31, v96
	v_lshlrev_b64 v[32:33], 7, v[96:97]
	v_lshl_add_u64 v[32:33], s[2:3], 0, v[32:33]
	global_load_dwordx4 v[52:55], v[32:33], off offset:32
	global_load_dwordx4 v[64:67], v[32:33], off
	global_load_dwordx4 v[76:79], v[32:33], off offset:16
	v_add_u32_e32 v162, s6, v96
	v_ashrrev_i32_e32 v163, 31, v162
	v_lshlrev_b64 v[34:35], 7, v[162:163]
	v_lshl_add_u64 v[34:35], s[2:3], 0, v[34:35]
	global_load_dwordx4 v[88:91], v[34:35], off
	global_load_dwordx4 v[100:103], v[34:35], off offset:16
	global_load_dwordx4 v[104:107], v[32:33], off offset:48
	global_load_dwordx4 v[108:111], v[34:35], off offset:32
	global_load_dwordx4 v[112:115], v[32:33], off offset:64
	global_load_dwordx4 v[116:119], v[34:35], off offset:48
	global_load_dwordx4 v[120:123], v[32:33], off offset:80
	global_load_dwordx4 v[124:127], v[34:35], off offset:64
	global_load_dwordx4 v[128:131], v[32:33], off offset:96
	global_load_dwordx4 v[132:135], v[34:35], off offset:80
	global_load_dwordx4 v[136:139], v[32:33], off offset:112
	global_load_dwordx4 v[140:143], v[34:35], off offset:96
	global_load_dwordx4 v[144:147], v[34:35], off offset:112
	v_lshlrev_b64 v[32:33], 13, v[96:97]
	v_lshl_add_u64 v[170:171], v[160:161], 0, v[32:33]
	v_add_co_u32_e32 v166, vcc, 0x1000, v170
	v_add_u32_e32 v98, s8, v96
	s_nop 0
	v_addc_co_u32_e32 v167, vcc, 0, v171, vcc
	v_ashrrev_i32_e32 v99, 31, v98
	v_lshlrev_b64 v[32:33], 13, v[162:163]
	v_lshlrev_b64 v[34:35], 7, v[98:99]
	v_lshl_add_u64 v[164:165], v[160:161], 0, v[32:33]
	v_lshl_add_u64 v[48:49], s[2:3], 0, v[34:35]
	global_load_dwordx4 v[92:95], v[170:171], off
	global_load_dwordx4 v[80:83], v[170:171], off offset:1024
	global_load_dwordx4 v[68:71], v[170:171], off offset:2048
	global_load_dwordx4 v[56:59], v[170:171], off offset:3072
	global_load_dwordx4 v[44:47], v[164:165], off
	global_load_dwordx4 v[40:43], v[164:165], off offset:1024
	global_load_dwordx4 v[36:39], v[164:165], off offset:2048
	global_load_dwordx4 v[32:35], v[164:165], off offset:3072
	global_load_dwordx4 v[152:155], v[48:49], off offset:48
	global_load_dwordx4 v[172:175], v[48:49], off offset:32
	global_load_dwordx4 v[188:191], v[48:49], off
	global_load_dwordx4 v[192:195], v[48:49], off offset:16
	global_load_dwordx4 v[196:199], v[48:49], off offset:112
	global_load_dwordx4 v[200:203], v[48:49], off offset:96
	global_load_dwordx4 v[204:207], v[48:49], off offset:80
	global_load_dwordx4 v[208:211], v[48:49], off offset:64
	global_load_dwordx4 v[84:87], v[166:167], off
	global_load_dwordx4 v[72:75], v[166:167], off offset:1024
	global_load_dwordx4 v[60:63], v[166:167], off offset:2048
	s_nop 0
	global_load_dwordx4 v[48:51], v[166:167], off offset:3072
	v_add_u32_e32 v96, s9, v96
	v_lshlrev_b64 v[98:99], 13, v[98:99]
	v_lshl_add_u64 v[178:179], v[160:161], 0, v[98:99]
	s_waitcnt vmcnt(0)
	v_pk_add_f32 v[66:67], v[66:67], v[78:79]
	v_pk_add_f32 v[64:65], v[64:65], v[76:77]
	v_pk_add_f32 v[54:55], v[66:67], v[54:55]
	v_pk_add_f32 v[52:53], v[64:65], v[52:53]
	v_pk_add_f32 v[54:55], v[54:55], v[106:107]
	v_pk_add_f32 v[52:53], v[52:53], v[104:105]
	v_pk_add_f32 v[54:55], v[54:55], v[114:115]
	v_pk_add_f32 v[52:53], v[52:53], v[112:113]
	v_pk_add_f32 v[54:55], v[54:55], v[122:123]
	v_pk_add_f32 v[52:53], v[52:53], v[120:121]
	v_pk_add_f32 v[54:55], v[54:55], v[130:131]
	v_pk_add_f32 v[52:53], v[52:53], v[128:129]
	v_pk_add_f32 v[54:55], v[54:55], v[138:139]
	v_pk_add_f32 v[52:53], v[52:53], v[136:137]
	v_pk_add_f32 v[64:65], v[90:91], v[102:103]
	v_pk_mov_b32 v[76:77], v[52:53], v[54:55] op_sel:[1,0]
	v_mov_b32_e32 v53, v55
	v_pk_add_f32 v[52:53], v[76:77], v[52:53]
	v_pk_add_f32 v[64:65], v[64:65], v[110:111]
	v_add_f32_e32 v52, v52, v53
	v_fmamk_f32 v52, v52, 0x3a000000, v181
	v_mul_f32_e32 v53, 0x4f800000, v52
	v_cmp_gt_f32_e32 vcc, s10, v52
	v_pk_add_f32 v[66:67], v[88:89], v[100:101]
	v_pk_add_f32 v[64:65], v[64:65], v[118:119]
	v_cndmask_b32_e32 v76, v52, v53, vcc
	v_sqrt_f32_e32 v77, v76
	v_pk_add_f32 v[66:67], v[66:67], v[108:109]
	v_pk_add_f32 v[64:65], v[64:65], v[126:127]
	v_pk_add_f32 v[66:67], v[66:67], v[116:117]
	v_pk_add_f32 v[64:65], v[64:65], v[134:135]
	v_pk_add_f32 v[66:67], v[66:67], v[124:125]
	v_pk_add_f32 v[64:65], v[64:65], v[142:143]
	v_pk_add_f32 v[66:67], v[66:67], v[132:133]
	v_pk_add_f32 v[54:55], v[64:65], v[146:147]
	v_add_u32_e32 v64, -1, v77
	v_pk_add_f32 v[52:53], v[66:67], v[140:141]
	v_add_u32_e32 v65, 1, v77
	v_fma_f32 v66, -v64, v77, v76
	v_fma_f32 v67, -v65, v77, v76
	v_cmp_ge_f32_e64 s[0:1], 0, v66
	v_pk_add_f32 v[52:53], v[52:53], v[144:145]
	v_pk_add_f32 v[98:99], v[190:191], v[194:195]
	v_cndmask_b32_e64 v64, v77, v64, s[0:1]
	v_cmp_lt_f32_e64 s[0:1], 0, v67
	v_pk_add_f32 v[98:99], v[98:99], v[174:175]
	s_nop 0
	v_cndmask_b32_e64 v64, v64, v65, s[0:1]
	v_mul_f32_e32 v65, 0x37800000, v64
	v_cndmask_b32_e32 v64, v64, v65, vcc
	v_cmp_class_f32_e32 vcc, v76, v183
	v_pk_add_f32 v[98:99], v[98:99], v[154:155]
	s_nop 0
	v_cndmask_b32_e32 v66, v64, v76, vcc
	v_div_scale_f32 v67, s[0:1], v66, v66, 1.0
	v_rcp_f32_e32 v76, v67
	v_pk_mov_b32 v[64:65], v[52:53], v[54:55] op_sel:[1,0]
	v_div_scale_f32 v53, vcc, 1.0, v66, 1.0
	v_fma_f32 v54, -v67, v76, 1.0
	v_fmac_f32_e32 v76, v54, v76
	v_mul_f32_e32 v54, v53, v76
	v_fma_f32 v77, -v67, v54, v53
	v_fmac_f32_e32 v54, v77, v76
	v_fma_f32 v53, -v67, v54, v53
	v_div_fmas_f32 v53, v53, v76, v54
	v_div_fixup_f32 v182, v53, v66, 1.0
	v_mov_b32_e32 v53, v55
	v_pk_add_f32 v[52:53], v[64:65], v[52:53]
	v_add_co_u32_e64 v168, s[0:1], s7, v164
	v_add_f32_e32 v52, v52, v53
	v_fmamk_f32 v52, v52, 0x3a000000, v181
	v_mul_f32_e32 v53, 0x4f800000, v52
	v_cmp_gt_f32_e32 vcc, s10, v52
; __device__ __forceinline__ void phase_final(const Params& p) {
;     ...
;     for (int row0 = gw; row0 < T; row0 += UR * NGW) { f32x4 v[UR][8]; float rs[UR];
; #pragma unroll
;         for (int u = 0; u < UR; ++u) { const int row = row0 + u * NGW; const f32x4* xr = (const f32x4*)(p.out + (size_t)row * DM) + lane;
; #pragma unroll
;             for (int j = 0; j < 8; ++j) v[u][j] = xr[64 * j];
;             const f32x4* sp = (const f32x4*)(ssq + (size_t)row * 32); f32x4 s = sp[0];
; #pragma unroll
;             for (int i = 1; i < 8; ++i) s += sp[i];
;             rs[u] = 1.0f / sqrtf(((s[0] + s[1]) + (s[2] + s[3])) * (1.0f / DM) + 1e-6f); }
; #pragma unroll
;         for (int u = 0; u < UR; ++u) { f32x4* xr = (f32x4*)(p.out + (size_t)(row0 + u * NGW) * DM) + lane;
; #pragma unroll
;             for (int j = 0; j < 8; ++j) __builtin_nontemporal_store(v[u][j] * rs[u] * g4[j], xr + 64 * j); } }
	v_addc_co_u32_e64 v169, s[0:1], 0, v165, s[0:1]
	s_nop 0
	v_cndmask_b32_e32 v52, v52, v53, vcc
	v_sqrt_f32_e32 v53, v52
	v_pk_add_f32 v[98:99], v[98:99], v[210:211]
	v_pk_mul_f32 v[56:57], v[56:57], v[182:183] op_sel_hi:[1,0]
	v_pk_add_f32 v[98:99], v[98:99], v[206:207]
	v_add_u32_e32 v54, -1, v53
	v_fma_f32 v55, -v54, v53, v52
	v_cmp_ge_f32_e64 s[0:1], 0, v55
	v_add_u32_e32 v55, 1, v53
	v_pk_add_f32 v[98:99], v[98:99], v[202:203]
	v_cndmask_b32_e64 v54, v53, v54, s[0:1]
	v_fma_f32 v53, -v55, v53, v52
	v_cmp_lt_f32_e64 s[0:1], 0, v53
	v_pk_add_f32 v[98:99], v[98:99], v[198:199]
	v_pk_mul_f32 v[58:59], v[58:59], v[182:183] op_sel_hi:[1,0]
	v_cndmask_b32_e64 v53, v54, v55, s[0:1]
	v_mul_f32_e32 v54, 0x37800000, v53
	v_cndmask_b32_e32 v53, v53, v54, vcc
	v_cmp_class_f32_e32 vcc, v52, v183
	v_pk_mul_f32 v[58:59], v[14:15], v[58:59]
	v_pk_mul_f32 v[56:57], v[12:13], v[56:57]
	v_cndmask_b32_e32 v106, v53, v52, vcc
	v_div_scale_f32 v107, s[0:1], v106, v106, 1.0
	v_rcp_f32_e32 v112, v107
	v_div_scale_f32 v113, vcc, 1.0, v106, 1.0
	global_load_dwordx4 v[88:91], v[168:169], off
	global_load_dwordx4 v[76:79], v[168:169], off offset:1024
	global_load_dwordx4 v[64:67], v[168:169], off offset:2048
	global_load_dwordx4 v[52:55], v[168:169], off offset:3072
	v_fma_f32 v97, -v107, v112, 1.0
	v_fmac_f32_e32 v112, v97, v112
	v_mul_f32_e32 v114, v113, v112
	v_fma_f32 v97, -v107, v114, v113
	v_fmac_f32_e32 v114, v97, v112
	v_ashrrev_i32_e32 v97, 31, v96
	v_lshlrev_b64 v[100:101], 7, v[96:97]
	v_lshl_add_u64 v[104:105], s[2:3], 0, v[100:101]
	global_load_dwordx4 v[100:103], v[104:105], off
	global_load_dwordx4 v[108:111], v[104:105], off offset:16
	global_load_dwordx4 v[120:123], v[104:105], off offset:48
	global_load_dwordx4 v[136:139], v[104:105], off offset:32
	global_load_dwordx4 v[212:215], v[104:105], off offset:80
	global_load_dwordx4 v[216:219], v[104:105], off offset:64
	global_load_dwordx4 v[220:223], v[104:105], off offset:112
	global_load_dwordx4 v[224:227], v[104:105], off offset:96
	v_pk_add_f32 v[104:105], v[188:189], v[192:193]
	v_fma_f32 v107, -v107, v114, v113
	v_pk_add_f32 v[104:105], v[104:105], v[172:173]
	v_div_fmas_f32 v107, v107, v112, v114
	v_pk_add_f32 v[104:105], v[104:105], v[152:153]
	v_div_fixup_f32 v186, v107, v106, 1.0
	v_pk_add_f32 v[104:105], v[104:105], v[208:209]
	v_add_co_u32_e64 v176, s[0:1], s7, v178
	v_pk_add_f32 v[104:105], v[104:105], v[204:205]
	s_nop 0
	v_addc_co_u32_e64 v177, s[0:1], 0, v179, s[0:1]
	v_pk_add_f32 v[104:105], v[104:105], v[200:201]
	global_load_dwordx4 v[156:159], v[178:179], off
	global_load_dwordx4 v[148:151], v[178:179], off offset:1024
	global_load_dwordx4 v[140:143], v[178:179], off offset:2048
	global_load_dwordx4 v[124:127], v[178:179], off offset:3072
	v_pk_add_f32 v[104:105], v[104:105], v[196:197]
	global_load_dwordx4 v[152:155], v[176:177], off
	global_load_dwordx4 v[144:147], v[176:177], off offset:1024
	global_load_dwordx4 v[132:135], v[176:177], off offset:2048
	global_load_dwordx4 v[116:119], v[176:177], off offset:3072
	v_pk_mov_b32 v[106:107], v[104:105], v[98:99] op_sel:[1,0]
	v_mov_b32_e32 v105, v99
	v_pk_add_f32 v[98:99], v[106:107], v[104:105]
	v_lshlrev_b64 v[96:97], 13, v[96:97]
	v_add_f32_e32 v98, v98, v99
	v_fmamk_f32 v98, v98, 0x3a000000, v181
	v_mul_f32_e32 v99, 0x4f800000, v98
	v_cmp_gt_f32_e32 vcc, s10, v98
	v_lshl_add_u64 v[174:175], v[160:161], 0, v[96:97]
	v_pk_mul_f32 v[48:49], v[48:49], v[182:183] op_sel_hi:[1,0]
	v_cndmask_b32_e32 v98, v98, v99, vcc
	v_sqrt_f32_e32 v99, v98
	v_pk_mul_f32 v[50:51], v[50:51], v[182:183] op_sel_hi:[1,0]
	v_pk_mul_f32 v[48:49], v[28:29], v[48:49]
	v_pk_mul_f32 v[50:51], v[30:31], v[50:51]
	v_add_u32_e32 v104, -1, v99
	v_fma_f32 v105, -v104, v99, v98
	v_cmp_ge_f32_e64 s[0:1], 0, v105
	v_add_u32_e32 v105, 1, v99
	v_pk_mul_f32 v[92:93], v[92:93], v[182:183] op_sel_hi:[1,0]
	v_cndmask_b32_e64 v104, v99, v104, s[0:1]
	v_fma_f32 v99, -v105, v99, v98
	v_cmp_lt_f32_e64 s[0:1], 0, v99
	v_pk_mul_f32 v[94:95], v[94:95], v[182:183] op_sel_hi:[1,0]
	v_pk_mul_f32 v[92:93], v[0:1], v[92:93]
	v_cndmask_b32_e64 v99, v104, v105, s[0:1]
	v_mul_f32_e32 v104, 0x37800000, v99
	v_cndmask_b32_e32 v99, v99, v104, vcc
	v_cmp_class_f32_e32 vcc, v98, v183
	v_pk_mul_f32 v[94:95], v[2:3], v[94:95]
	v_pk_mul_f32 v[80:81], v[80:81], v[182:183] op_sel_hi:[1,0]
	v_cndmask_b32_e32 v98, v99, v98, vcc
	v_div_scale_f32 v99, s[0:1], v98, v98, 1.0
	v_rcp_f32_e32 v104, v99
	v_add_co_u32_e64 v172, s[0:1], s7, v174
	v_pk_mul_f32 v[82:83], v[82:83], v[182:183] op_sel_hi:[1,0]
	v_fma_f32 v105, -v99, v104, 1.0
	v_fmac_f32_e32 v104, v105, v104
	v_div_scale_f32 v105, vcc, 1.0, v98, 1.0
	v_mul_f32_e32 v106, v105, v104
	v_fma_f32 v107, -v99, v106, v105
	v_fmac_f32_e32 v106, v107, v104
	v_fma_f32 v99, -v99, v106, v105
	v_div_fmas_f32 v99, v99, v104, v106
	v_div_fixup_f32 v184, v99, v98, 1.0
	global_load_dwordx4 v[128:131], v[174:175], off
	global_load_dwordx4 v[112:115], v[174:175], off offset:1024
	global_load_dwordx4 v[104:107], v[174:175], off offset:2048
	global_load_dwordx4 v[96:99], v[174:175], off offset:3072
	v_addc_co_u32_e64 v173, s[0:1], 0, v175, s[0:1]
	v_pk_mul_f32 v[82:83], v[6:7], v[82:83]
	v_pk_mul_f32 v[80:81], v[4:5], v[80:81]
	v_pk_mul_f32 v[68:69], v[68:69], v[182:183] op_sel_hi:[1,0]
	v_pk_mul_f32 v[70:71], v[70:71], v[182:183] op_sel_hi:[1,0]
	v_pk_mul_f32 v[68:69], v[8:9], v[68:69]
	v_pk_mul_f32 v[70:71], v[10:11], v[70:71]
	s_waitcnt vmcnt(18)
	v_pk_add_f32 v[102:103], v[102:103], v[110:111]
	v_pk_add_f32 v[100:101], v[100:101], v[108:109]
	s_waitcnt vmcnt(16)
; __device__ __forceinline__ void phase_final(const Params& p) {
;     ...
;     for (int row0 = gw; row0 < T; row0 += UR * NGW) { f32x4 v[UR][8]; float rs[UR];
; #pragma unroll
;         for (int u = 0; u < UR; ++u) { const int row = row0 + u * NGW; const f32x4* xr = (const f32x4*)(p.out + (size_t)row * DM) + lane;
; #pragma unroll
;             for (int j = 0; j < 8; ++j) v[u][j] = xr[64 * j];
;             const f32x4* sp = (const f32x4*)(ssq + (size_t)row * 32); f32x4 s = sp[0];
; #pragma unroll
;             for (int i = 1; i < 8; ++i) s += sp[i];
;             rs[u] = 1.0f / sqrtf(((s[0] + s[1]) + (s[2] + s[3])) * (1.0f / DM) + 1e-6f); }
; #pragma unroll
;         for (int u = 0; u < UR; ++u) { f32x4* xr = (f32x4*)(p.out + (size_t)(row0 + u * NGW) * DM) + lane;
; #pragma unroll
;             for (int j = 0; j < 8; ++j) __builtin_nontemporal_store(v[u][j] * rs[u] * g4[j], xr + 64 * j); } }
	v_pk_add_f32 v[102:103], v[102:103], v[138:139]
	v_pk_add_f32 v[100:101], v[100:101], v[136:137]
	v_pk_add_f32 v[102:103], v[102:103], v[122:123]
	v_pk_add_f32 v[100:101], v[100:101], v[120:121]
	s_waitcnt vmcnt(14)
	v_pk_add_f32 v[102:103], v[102:103], v[218:219]
	v_pk_add_f32 v[100:101], v[100:101], v[216:217]
	v_pk_add_f32 v[102:103], v[102:103], v[214:215]
	v_pk_add_f32 v[100:101], v[100:101], v[212:213]
	s_waitcnt vmcnt(12)
	v_pk_add_f32 v[102:103], v[102:103], v[226:227]
	v_pk_add_f32 v[100:101], v[100:101], v[224:225]
	v_pk_add_f32 v[102:103], v[102:103], v[222:223]
	v_pk_add_f32 v[100:101], v[100:101], v[220:221]
	v_pk_mov_b32 v[108:109], v[100:101], v[102:103] op_sel:[1,0]
	v_mov_b32_e32 v101, v103
	v_pk_add_f32 v[100:101], v[108:109], v[100:101]
	v_add_f32_e32 v100, v100, v101
	v_fmamk_f32 v100, v100, 0x3a000000, v181
	v_mul_f32_e32 v101, 0x4f800000, v100
	v_cmp_gt_f32_e32 vcc, s10, v100
	s_nop 1
	v_cndmask_b32_e32 v100, v100, v101, vcc
	v_sqrt_f32_e32 v101, v100
	s_nop 0
	v_add_u32_e32 v102, -1, v101
	v_fma_f32 v103, -v102, v101, v100
	v_cmp_ge_f32_e64 s[0:1], 0, v103
	v_add_u32_e32 v103, 1, v101
	s_nop 0
	v_cndmask_b32_e64 v102, v101, v102, s[0:1]
	v_fma_f32 v101, -v103, v101, v100
	v_cmp_lt_f32_e64 s[0:1], 0, v101
	s_nop 1
	v_cndmask_b32_e64 v101, v102, v103, s[0:1]
	v_mul_f32_e32 v102, 0x37800000, v101
	v_cndmask_b32_e32 v101, v101, v102, vcc
	v_cmp_class_f32_e32 vcc, v100, v183
	s_nop 1
	v_cndmask_b32_e32 v163, v101, v100, vcc
	global_load_dwordx4 v[136:139], v[172:173], off
	global_load_dwordx4 v[120:123], v[172:173], off offset:1024
	global_load_dwordx4 v[108:111], v[172:173], off offset:2048
	global_load_dwordx4 v[100:103], v[172:173], off offset:3072
	v_div_scale_f32 v180, s[0:1], v163, v163, 1.0
	v_rcp_f32_e32 v185, v180
	global_store_dwordx4 v[170:171], v[56:59], off offset:3072 nt
	global_store_dwordx4 v[166:167], v[48:51], off offset:3072 nt
	global_store_dwordx4 v[170:171], v[92:95], off nt
	v_fma_f32 v187, -v180, v185, 1.0
	v_fmac_f32_e32 v185, v187, v185
	v_div_scale_f32 v187, vcc, 1.0, v163, 1.0
	v_pk_mul_f32 v[32:33], v[32:33], v[186:187] op_sel_hi:[1,0]
	v_pk_mul_f32 v[34:35], v[34:35], v[186:187] op_sel_hi:[1,0]
	v_pk_mul_f32 v[32:33], v[12:13], v[32:33]
	v_pk_mul_f32 v[34:35], v[14:15], v[34:35]
	v_pk_mul_f32 v[56:57], v[84:85], v[182:183] op_sel_hi:[1,0]
	v_pk_mul_f32 v[58:59], v[86:87], v[182:183] op_sel_hi:[1,0]
	global_store_dwordx4 v[164:165], v[32:35], off offset:3072 nt
	v_pk_mul_f32 v[58:59], v[18:19], v[58:59]
	v_pk_mul_f32 v[56:57], v[16:17], v[56:57]
	v_pk_mul_f32 v[32:33], v[88:89], v[186:187] op_sel_hi:[1,0]
	v_pk_mul_f32 v[34:35], v[90:91], v[186:187] op_sel_hi:[1,0]
	v_pk_mul_f32 v[32:33], v[16:17], v[32:33]
	v_pk_mul_f32 v[34:35], v[18:19], v[34:35]
	global_store_dwordx4 v[166:167], v[56:59], off nt
	global_store_dwordx4 v[168:169], v[32:35], off nt
	v_pk_mul_f32 v[44:45], v[44:45], v[186:187] op_sel_hi:[1,0]
	v_pk_mul_f32 v[56:57], v[72:73], v[182:183] op_sel_hi:[1,0]
	v_pk_mul_f32 v[58:59], v[74:75], v[182:183] op_sel_hi:[1,0]
	v_pk_mul_f32 v[32:33], v[76:77], v[186:187] op_sel_hi:[1,0]
	v_pk_mul_f32 v[34:35], v[78:79], v[186:187] op_sel_hi:[1,0]
	v_pk_mul_f32 v[58:59], v[22:23], v[58:59]
	v_pk_mul_f32 v[56:57], v[20:21], v[56:57]
	v_pk_mul_f32 v[34:35], v[22:23], v[34:35]
	v_pk_mul_f32 v[32:33], v[20:21], v[32:33]
	global_store_dwordx4 v[166:167], v[56:59], off offset:1024 nt
	global_store_dwordx4 v[168:169], v[32:35], off offset:1024 nt
	v_pk_mul_f32 v[46:47], v[46:47], v[186:187] op_sel_hi:[1,0]
	v_pk_mul_f32 v[56:57], v[60:61], v[182:183] op_sel_hi:[1,0]
	v_pk_mul_f32 v[58:59], v[62:63], v[182:183] op_sel_hi:[1,0]
	v_pk_mul_f32 v[32:33], v[64:65], v[186:187] op_sel_hi:[1,0]
	v_pk_mul_f32 v[34:35], v[66:67], v[186:187] op_sel_hi:[1,0]
	v_pk_mul_f32 v[58:59], v[26:27], v[58:59]
	v_pk_mul_f32 v[56:57], v[24:25], v[56:57]
	v_pk_mul_f32 v[34:35], v[26:27], v[34:35]
	v_pk_mul_f32 v[32:33], v[24:25], v[32:33]
	global_store_dwordx4 v[166:167], v[56:59], off offset:2048 nt
	global_store_dwordx4 v[168:169], v[32:35], off offset:2048 nt
	v_pk_mul_f32 v[46:47], v[2:3], v[46:47]
	v_pk_mul_f32 v[44:45], v[0:1], v[44:45]
	v_pk_mul_f32 v[32:33], v[52:53], v[186:187] op_sel_hi:[1,0]
	v_pk_mul_f32 v[34:35], v[54:55], v[186:187] op_sel_hi:[1,0]
	v_pk_mul_f32 v[32:33], v[28:29], v[32:33]
	v_pk_mul_f32 v[34:35], v[30:31], v[34:35]
	global_store_dwordx4 v[168:169], v[32:35], off offset:3072 nt
	global_store_dwordx4 v[164:165], v[44:47], off nt
	v_pk_mul_f32 v[40:41], v[40:41], v[186:187] op_sel_hi:[1,0]
	s_waitcnt vmcnt(27)
	v_pk_mul_f32 v[32:33], v[156:157], v[184:185] op_sel_hi:[1,0]
	v_pk_mul_f32 v[34:35], v[158:159], v[184:185] op_sel_hi:[1,0]
	v_pk_mul_f32 v[32:33], v[0:1], v[32:33]
	v_pk_mul_f32 v[34:35], v[2:3], v[34:35]
	v_pk_mul_f32 v[42:43], v[42:43], v[186:187] op_sel_hi:[1,0]
	global_store_dwordx4 v[178:179], v[32:35], off nt
	v_pk_mul_f32 v[42:43], v[6:7], v[42:43]
	v_pk_mul_f32 v[40:41], v[4:5], v[40:41]
	s_waitcnt vmcnt(27)
; __device__ __forceinline__ void phase_final(const Params& p) {
;     ...
;         for (int u = 0; u < UR; ++u) { const int row = row0 + u * NGW; const f32x4* xr = (const f32x4*)(p.out + (size_t)row * DM) + lane;
; #pragma unroll
;             for (int j = 0; j < 8; ++j) v[u][j] = xr[64 * j];
;             const f32x4* sp = (const f32x4*)(ssq + (size_t)row * 32); f32x4 s = sp[0];
; #pragma unroll
;             for (int i = 1; i < 8; ++i) s += sp[i];
;             rs[u] = 1.0f / sqrtf(((s[0] + s[1]) + (s[2] + s[3])) * (1.0f / DM) + 1e-6f); }
; #pragma unroll
;         for (int u = 0; u < UR; ++u) { f32x4* xr = (f32x4*)(p.out + (size_t)(row0 + u * NGW) * DM) + lane;
; #pragma unroll
;             for (int j = 0; j < 8; ++j) __builtin_nontemporal_store(v[u][j] * rs[u] * g4[j], xr + 64 * j); } }
	v_pk_mul_f32 v[32:33], v[148:149], v[184:185] op_sel_hi:[1,0]
	v_pk_mul_f32 v[34:35], v[150:151], v[184:185] op_sel_hi:[1,0]
	v_pk_mul_f32 v[32:33], v[4:5], v[32:33]
	v_pk_mul_f32 v[34:35], v[6:7], v[34:35]
	global_store_dwordx4 v[170:171], v[80:83], off offset:1024 nt
	global_store_dwordx4 v[164:165], v[40:43], off offset:1024 nt
	v_pk_mul_f32 v[36:37], v[36:37], v[186:187] op_sel_hi:[1,0]
	v_pk_mul_f32 v[38:39], v[38:39], v[186:187] op_sel_hi:[1,0]
	global_store_dwordx4 v[178:179], v[32:35], off offset:1024 nt
	v_pk_mul_f32 v[38:39], v[10:11], v[38:39]
	v_pk_mul_f32 v[36:37], v[8:9], v[36:37]
	s_waitcnt vmcnt(29)
	v_pk_mul_f32 v[32:33], v[140:141], v[184:185] op_sel_hi:[1,0]
	v_pk_mul_f32 v[34:35], v[142:143], v[184:185] op_sel_hi:[1,0]
	v_pk_mul_f32 v[32:33], v[8:9], v[32:33]
	v_pk_mul_f32 v[34:35], v[10:11], v[34:35]
	global_store_dwordx4 v[170:171], v[68:71], off offset:2048 nt
	global_store_dwordx4 v[164:165], v[36:39], off offset:2048 nt
	global_store_dwordx4 v[178:179], v[32:35], off offset:2048 nt
	v_mul_f32_e32 v188, v187, v185
	v_fma_f32 v189, -v180, v188, v187
	s_waitcnt vmcnt(31)
	v_pk_mul_f32 v[32:33], v[124:125], v[184:185] op_sel_hi:[1,0]
	v_pk_mul_f32 v[34:35], v[126:127], v[184:185] op_sel_hi:[1,0]
	v_pk_mul_f32 v[32:33], v[12:13], v[32:33]
	v_pk_mul_f32 v[34:35], v[14:15], v[34:35]
	global_store_dwordx4 v[178:179], v[32:35], off offset:3072 nt
	v_fmac_f32_e32 v188, v189, v185
	v_fma_f32 v180, -v180, v188, v187
	s_waitcnt vmcnt(31)
	v_pk_mul_f32 v[32:33], v[152:153], v[184:185] op_sel_hi:[1,0]
	v_pk_mul_f32 v[34:35], v[154:155], v[184:185] op_sel_hi:[1,0]
	v_pk_mul_f32 v[32:33], v[16:17], v[32:33]
	v_pk_mul_f32 v[34:35], v[18:19], v[34:35]
	global_store_dwordx4 v[176:177], v[32:35], off nt
	v_div_fmas_f32 v180, v180, v185, v188
	v_div_fixup_f32 v180, v180, v163, 1.0
	s_waitcnt vmcnt(31)
	v_pk_mul_f32 v[32:33], v[144:145], v[184:185] op_sel_hi:[1,0]
	v_pk_mul_f32 v[34:35], v[146:147], v[184:185] op_sel_hi:[1,0]
	v_pk_mul_f32 v[32:33], v[20:21], v[32:33]
	v_pk_mul_f32 v[34:35], v[22:23], v[34:35]
	global_store_dwordx4 v[176:177], v[32:35], off offset:1024 nt
	s_waitcnt vmcnt(31)
	s_nop 0
	v_pk_mul_f32 v[32:33], v[132:133], v[184:185] op_sel_hi:[1,0]
	v_pk_mul_f32 v[34:35], v[134:135], v[184:185] op_sel_hi:[1,0]
	v_pk_mul_f32 v[32:33], v[24:25], v[32:33]
	v_pk_mul_f32 v[34:35], v[26:27], v[34:35]
	global_store_dwordx4 v[176:177], v[32:35], off offset:2048 nt
	s_waitcnt vmcnt(31)
	s_nop 0
	v_pk_mul_f32 v[32:33], v[116:117], v[184:185] op_sel_hi:[1,0]
	v_pk_mul_f32 v[34:35], v[118:119], v[184:185] op_sel_hi:[1,0]
	v_pk_mul_f32 v[32:33], v[28:29], v[32:33]
	v_pk_mul_f32 v[34:35], v[30:31], v[34:35]
	global_store_dwordx4 v[176:177], v[32:35], off offset:3072 nt
	s_waitcnt vmcnt(31)
	s_nop 0
	v_pk_mul_f32 v[32:33], v[128:129], v[180:181] op_sel_hi:[1,0]
	v_pk_mul_f32 v[34:35], v[130:131], v[180:181] op_sel_hi:[1,0]
	v_pk_mul_f32 v[32:33], v[0:1], v[32:33]
	v_pk_mul_f32 v[34:35], v[2:3], v[34:35]
	global_store_dwordx4 v[174:175], v[32:35], off nt
	s_waitcnt vmcnt(31)
	s_nop 0
	v_pk_mul_f32 v[32:33], v[112:113], v[180:181] op_sel_hi:[1,0]
	v_pk_mul_f32 v[34:35], v[114:115], v[180:181] op_sel_hi:[1,0]
	v_pk_mul_f32 v[32:33], v[4:5], v[32:33]
	v_pk_mul_f32 v[34:35], v[6:7], v[34:35]
	global_store_dwordx4 v[174:175], v[32:35], off offset:1024 nt
	s_waitcnt vmcnt(31)
	s_nop 0
	v_pk_mul_f32 v[32:33], v[104:105], v[180:181] op_sel_hi:[1,0]
	v_pk_mul_f32 v[34:35], v[106:107], v[180:181] op_sel_hi:[1,0]
	v_pk_mul_f32 v[32:33], v[8:9], v[32:33]
	v_pk_mul_f32 v[34:35], v[10:11], v[34:35]
	global_store_dwordx4 v[174:175], v[32:35], off offset:2048 nt
	s_waitcnt vmcnt(31)
	s_nop 0
	v_pk_mul_f32 v[32:33], v[96:97], v[180:181] op_sel_hi:[1,0]
	v_pk_mul_f32 v[34:35], v[98:99], v[180:181] op_sel_hi:[1,0]
	v_pk_mul_f32 v[32:33], v[12:13], v[32:33]
	v_pk_mul_f32 v[34:35], v[14:15], v[34:35]
	global_store_dwordx4 v[174:175], v[32:35], off offset:3072 nt
	v_add_u32_e32 v96, s11, v162
	v_cmp_lt_i32_e32 vcc, s12, v96
	s_waitcnt vmcnt(31)
	v_pk_mul_f32 v[32:33], v[136:137], v[180:181] op_sel_hi:[1,0]
	v_pk_mul_f32 v[34:35], v[138:139], v[180:181] op_sel_hi:[1,0]
	v_pk_mul_f32 v[32:33], v[16:17], v[32:33]
	v_pk_mul_f32 v[34:35], v[18:19], v[34:35]
	global_store_dwordx4 v[172:173], v[32:35], off nt
	s_or_b64 s[4:5], vcc, s[4:5]
	s_waitcnt vmcnt(31)
	v_pk_mul_f32 v[32:33], v[120:121], v[180:181] op_sel_hi:[1,0]
	v_pk_mul_f32 v[34:35], v[122:123], v[180:181] op_sel_hi:[1,0]
	v_pk_mul_f32 v[32:33], v[20:21], v[32:33]
	v_pk_mul_f32 v[34:35], v[22:23], v[34:35]
	global_store_dwordx4 v[172:173], v[32:35], off offset:1024 nt
	s_waitcnt vmcnt(31)
	s_nop 0
	v_pk_mul_f32 v[32:33], v[108:109], v[180:181] op_sel_hi:[1,0]
	v_pk_mul_f32 v[34:35], v[110:111], v[180:181] op_sel_hi:[1,0]
	v_pk_mul_f32 v[32:33], v[24:25], v[32:33]
	v_pk_mul_f32 v[34:35], v[26:27], v[34:35]
	global_store_dwordx4 v[172:173], v[32:35], off offset:2048 nt
	s_waitcnt vmcnt(31)
	s_nop 0
	v_pk_mul_f32 v[32:33], v[100:101], v[180:181] op_sel_hi:[1,0]
	v_pk_mul_f32 v[34:35], v[102:103], v[180:181] op_sel_hi:[1,0]
	v_pk_mul_f32 v[32:33], v[28:29], v[32:33]
	v_pk_mul_f32 v[34:35], v[30:31], v[34:35]
	global_store_dwordx4 v[172:173], v[32:35], off offset:3072 nt
	s_andn2_b64 exec, exec, s[4:5]
	s_cbranch_execnz .LBB0_2004
